# static-priority strategy step A: all 144 per-segment s_setprio flips in the K-loops deleted
# speedup vs baseline: 1.0146x; 1.0055x over previous
; #define PG8_STAGE(bufoff, gbase, voff) do { _Pragma("unroll") for (int _i = 0; _i < 2; ++_i) \
;         __builtin_amdgcn_global_load_lds((const unsigned*)((const char*)(gbase) + (voff)[_i]), (LAS unsigned*)(lds + (bufoff) + ldsw + _i * 8192), 16, 0, 0); } while (0)
; #define PG8_LDA(dst, b, h) do { _Pragma("unroll") for (int m = 0; m < 4; ++m) _Pragma("unroll") for (int k = 0; k < 2; ++k) dst[m][k] = *(const LAS bf16x8*)(lds + PG8_SA(b, h) + aoff + m * 2048 + k * 1024); } while (0)
; #define PG8_LDB(dst, b, h) do { _Pragma("unroll") for (int n = 0; n < 2; ++n) _Pragma("unroll") for (int k = 0; k < 2; ++k) dst[n][k] = *(const LAS bf16x8*)(lds + PG8_SB(b, h) + boff + n * 2048 + k * 1024); } while (0)
; #define PG8_MMA(ai, bj, At, Bt) do { __builtin_amdgcn_s_setprio(1); _Pragma("unroll") for (int m = 0; m < 4; ++m) _Pragma("unroll") for (int n = 0; n < 2; ++n) _Pragma("unroll") for (int k = 0; k < 2; ++k) \
;         acc[ai][bj][m][n] = __builtin_amdgcn_mfma_f32_16x16x32_bf16(Bt[n][k], At[m][k], acc[ai][bj][m][n], 0, 0, 0); __builtin_amdgcn_s_setprio(0); } while (0)
; #define PG8_BAR __builtin_amdgcn_s_barrier()
; template <class Epi>
; __device__ __forceinline__ void gemm_phase(LAS unsigned char* lds, const Gemm g, const StaticOrder& S, const Epi& E, const int tid) {
;     ...
;         for (int t = 0; t < ntt; t += 2) {
;             const bool last = (t == ntt - 2);
;             const bool s1 = Epi::TWO && (t >= nt), s2 = Epi::TWO && (t + 2 >= nt);
;             const char* a1 = (s1 ? cA2 + (size_t)(t - nt + 1) * kstep : cA + (size_t)(t + 1) * kstep);
;             const char* a2 = last ? nA : (s2 ? cA2 + (size_t)(t + 2 - nt) * kstep : cA + (size_t)(t + 2) * kstep);
;             const char* b2 = last ? nB : (s2 ? cB2 + (size_t)(t + 2 - nt) * kstep : cB + (size_t)(t + 2) * kstep);
;             const char* a3 = a2 + kstep; const char* b3 = b2 + kstep;
;             if constexpr (Epi::TWO) { if (t == nt) E.mid(acc, cur, wr, wc, fr, fq); }
;             if constexpr (SP2) {
;             PG8_LDB(B0, 0, 0); PG8_LDB(B1, 0, 1); PG8_SCHED; PG8_LDA(At, 0, 0); PG8_STAGE(PG8_SA(1, 1), a1 + hstep, voffA);
;             PG8_WAIT_V(8); PG8_WAIT_L(0); PG8_BAR; PG8_MMA(0, 0, At, B0); PG8_MMA(0, 1, At, B1); PG8_BAR; PG8_SCHED;
;             PG8_LDA(At, 0, 1); PG8_STAGE(PG8_SB(0, 0), b2, voffB); PG8_STAGE(PG8_SB(0, 1), b2 + bhs, voffB); PG8_STAGE(PG8_SA(0, 0), a2, voffA);
.LBB0_126:
	s_add_u32 s30, s28, 0xffe00080
	s_addc_u32 s31, s29, -1
	s_add_i32 s52, 0, 0x10000
	s_cmpk_eq_i32 s51, 0x7c
	s_cselect_b32 s35, s17, s31
	s_cselect_b32 s34, s27, s30
	s_cselect_b32 s31, s15, s50
	s_cselect_b32 s30, s33, s49
	s_add_i32 s54, 0, 0x14000
	v_add_u32_e32 v30, s52, v193
	v_add_u32_e32 v54, s54, v193
	ds_read_b128 v[18:21], v30
	ds_read_b128 v[22:25], v30 offset:1024
	ds_read_b128 v[26:29], v30 offset:2048
	ds_read_b128 v[30:33], v30 offset:3072
	ds_read_b128 v[42:45], v54
	ds_read_b128 v[46:49], v54 offset:1024
	ds_read_b128 v[50:53], v54 offset:2048
	ds_read_b128 v[54:57], v54 offset:3072
	v_lshl_add_u64 v[172:173], s[28:29], 0, v[180:181]
	s_add_i32 m0, s37, 0xc000
	ds_read_b128 v[182:185], v199
	global_load_lds_dwordx4 v[172:173], off
	ds_read_b128 v[186:189], v199 offset:1024
	ds_read_b128 v[212:215], v199 offset:2048
	v_lshl_add_u64 v[172:173], s[28:29], 0, v[178:179]
	s_add_i32 m0, s37, 0xe000
	s_nop 0
	global_load_lds_dwordx4 v[172:173], off
	ds_read_b128 v[216:219], v199 offset:3072
	ds_read_b128 v[220:223], v199 offset:4096
	ds_read_b128 v[224:227], v199 offset:5120
	ds_read_b128 v[228:231], v199 offset:6144
	ds_read_b128 v[232:235], v199 offset:7168
	s_waitcnt vmcnt(8)
	s_waitcnt lgkmcnt(0)
	s_barrier
	s_waitcnt lgkmcnt(0)
	v_mfma_f32_16x16x32_bf16 v[158:161], v[18:21], v[182:185], v[158:161]
	v_mfma_f32_16x16x32_bf16 v[154:157], v[26:29], v[182:185], v[154:157]
	v_mfma_f32_16x16x32_bf16 v[142:145], v[18:21], v[212:215], v[142:145]
	v_mfma_f32_16x16x32_bf16 v[138:141], v[26:29], v[212:215], v[138:141]
	v_mfma_f32_16x16x32_bf16 v[126:129], v[18:21], v[220:223], v[126:129]
	v_mfma_f32_16x16x32_bf16 v[122:125], v[26:29], v[220:223], v[122:125]
	v_mfma_f32_16x16x32_bf16 v[110:113], v[18:21], v[228:231], v[110:113]
	v_mfma_f32_16x16x32_bf16 v[106:109], v[26:29], v[228:231], v[106:109]
	v_mfma_f32_16x16x32_bf16 v[158:161], v[22:25], v[186:189], v[158:161]
	v_mfma_f32_16x16x32_bf16 v[154:157], v[30:33], v[186:189], v[154:157]
	v_mfma_f32_16x16x32_bf16 v[142:145], v[22:25], v[216:219], v[142:145]
	v_mfma_f32_16x16x32_bf16 v[138:141], v[30:33], v[216:219], v[138:141]
	v_mfma_f32_16x16x32_bf16 v[126:129], v[22:25], v[224:227], v[126:129]
	v_mfma_f32_16x16x32_bf16 v[122:125], v[30:33], v[224:227], v[122:125]
	v_mfma_f32_16x16x32_bf16 v[110:113], v[22:25], v[232:235], v[110:113]
	v_mfma_f32_16x16x32_bf16 v[106:109], v[30:33], v[232:235], v[106:109]
	v_mfma_f32_16x16x32_bf16 v[150:153], v[42:45], v[182:185], v[150:153]
	v_mfma_f32_16x16x32_bf16 v[146:149], v[50:53], v[182:185], v[146:149]
	v_mfma_f32_16x16x32_bf16 v[134:137], v[42:45], v[212:215], v[134:137]
	v_mfma_f32_16x16x32_bf16 v[130:133], v[50:53], v[212:215], v[130:133]
	v_mfma_f32_16x16x32_bf16 v[118:121], v[42:45], v[220:223], v[118:121]
	v_mfma_f32_16x16x32_bf16 v[114:117], v[50:53], v[220:223], v[114:117]
	v_mfma_f32_16x16x32_bf16 v[102:105], v[42:45], v[228:231], v[102:105]
	v_mfma_f32_16x16x32_bf16 v[98:101], v[50:53], v[228:231], v[98:101]
	v_mfma_f32_16x16x32_bf16 v[150:153], v[46:49], v[186:189], v[150:153]
	v_mfma_f32_16x16x32_bf16 v[146:149], v[54:57], v[186:189], v[146:149]
	v_mfma_f32_16x16x32_bf16 v[134:137], v[46:49], v[216:219], v[134:137]
	v_mfma_f32_16x16x32_bf16 v[130:133], v[54:57], v[216:219], v[130:133]
	v_mfma_f32_16x16x32_bf16 v[118:121], v[46:49], v[224:227], v[118:121]
	v_mfma_f32_16x16x32_bf16 v[114:117], v[54:57], v[224:227], v[114:117]
	v_mfma_f32_16x16x32_bf16 v[102:105], v[46:49], v[232:235], v[102:105]
	v_mfma_f32_16x16x32_bf16 v[98:101], v[54:57], v[232:235], v[98:101]
	s_barrier
	s_add_i32 s52, s52, s36
	v_lshl_add_u64 v[172:173], s[30:31], 0, v[0:1]
	s_mov_b32 m0, s52
	ds_read_b128 v[182:185], v199 offset:16384
	global_load_lds_dwordx4 v[172:173], off
	ds_read_b128 v[186:189], v199 offset:17408
	ds_read_b128 v[212:215], v199 offset:18432
	s_add_i32 m0, s52, 0x2000
	s_add_u32 s52, s30, 0x20000
	v_lshl_add_u64 v[174:175], s[30:31], 0, v[166:167]
	s_addc_u32 s53, s31, 0
	s_add_i32 s54, s54, s36
	global_load_lds_dwordx4 v[174:175], off
	ds_read_b128 v[216:219], v199 offset:19456
	ds_read_b128 v[220:223], v199 offset:20480
	v_lshl_add_u64 v[176:177], s[52:53], 0, v[0:1]
	s_mov_b32 m0, s54
	v_lshl_add_u64 v[200:201], s[34:35], 0, v[164:165]
	global_load_lds_dwordx4 v[176:177], off
	ds_read_b128 v[224:227], v199 offset:21504
	ds_read_b128 v[228:231], v199 offset:22528
	v_lshl_add_u64 v[176:177], s[52:53], 0, v[166:167]
	s_add_i32 m0, s54, 0x2000
	s_nop 0
	global_load_lds_dwordx4 v[176:177], off
	ds_read_b128 v[232:235], v199 offset:23552
	v_lshl_add_u64 v[176:177], s[34:35], 0, v[162:163]
	s_mov_b32 m0, s37
	s_nop 0
	global_load_lds_dwordx4 v[176:177], off
	s_mov_b32 m0, s38
	s_nop 0
	global_load_lds_dwordx4 v[200:201], off
	s_waitcnt vmcnt(8)
	s_waitcnt lgkmcnt(0)
	s_barrier
; #define PG8_STAGE(bufoff, gbase, voff) do { _Pragma("unroll") for (int _i = 0; _i < 2; ++_i) \
;         __builtin_amdgcn_global_load_lds((const unsigned*)((const char*)(gbase) + (voff)[_i]), (LAS unsigned*)(lds + (bufoff) + ldsw + _i * 8192), 16, 0, 0); } while (0)
; #define PG8_LDA(dst, b, h) do { _Pragma("unroll") for (int m = 0; m < 4; ++m) _Pragma("unroll") for (int k = 0; k < 2; ++k) dst[m][k] = *(const LAS bf16x8*)(lds + PG8_SA(b, h) + aoff + m * 2048 + k * 1024); } while (0)
; #define PG8_LDB(dst, b, h) do { _Pragma("unroll") for (int n = 0; n < 2; ++n) _Pragma("unroll") for (int k = 0; k < 2; ++k) dst[n][k] = *(const LAS bf16x8*)(lds + PG8_SB(b, h) + boff + n * 2048 + k * 1024); } while (0)
; #define PG8_MMA(ai, bj, At, Bt) do { __builtin_amdgcn_s_setprio(1); _Pragma("unroll") for (int m = 0; m < 4; ++m) _Pragma("unroll") for (int n = 0; n < 2; ++n) _Pragma("unroll") for (int k = 0; k < 2; ++k) \
;         acc[ai][bj][m][n] = __builtin_amdgcn_mfma_f32_16x16x32_bf16(Bt[n][k], At[m][k], acc[ai][bj][m][n], 0, 0, 0); __builtin_amdgcn_s_setprio(0); } while (0)
; #define PG8_WAIT_V(n) asm volatile("s_waitcnt vmcnt(" #n ")" ::: "memory")
; #define PG8_WAIT_L(n) asm volatile("s_waitcnt lgkmcnt(" #n ")" ::: "memory")
; #define PG8_BAR __builtin_amdgcn_s_barrier()
; #define PG8_SCHED __builtin_amdgcn_sched_barrier(0)
; template <class Epi>
; __device__ __forceinline__ void gemm_phase(LAS unsigned char* lds, const Gemm g, const StaticOrder& S, const Epi& E, const int tid) {
;     ...
;             PG8_WAIT_V(8); PG8_WAIT_L(0); PG8_BAR; PG8_MMA(1, 0, At, B0); PG8_MMA(1, 1, At, B1); PG8_BAR; PG8_SCHED;
;             PG8_LDB(B0, 1, 0); PG8_LDB(B1, 1, 1); PG8_SCHED; PG8_LDA(At, 1, 0); PG8_STAGE(PG8_SA(0, 1), a2 + hstep, voffA);
;             PG8_WAIT_V(8); PG8_WAIT_L(0); PG8_BAR; PG8_MMA(0, 0, At, B0); PG8_MMA(0, 1, At, B1); PG8_BAR; PG8_SCHED;
	s_waitcnt lgkmcnt(0)
	v_mfma_f32_16x16x32_bf16 v[94:97], v[18:21], v[182:185], v[94:97]
	v_mfma_f32_16x16x32_bf16 v[90:93], v[26:29], v[182:185], v[90:93]
	v_mfma_f32_16x16x32_bf16 v[78:81], v[18:21], v[212:215], v[78:81]
	v_mfma_f32_16x16x32_bf16 v[74:77], v[26:29], v[212:215], v[74:77]
	v_mfma_f32_16x16x32_bf16 v[62:65], v[18:21], v[220:223], v[62:65]
	v_mfma_f32_16x16x32_bf16 v[58:61], v[26:29], v[220:223], v[58:61]
	v_mfma_f32_16x16x32_bf16 v[14:17], v[18:21], v[228:231], v[14:17]
	v_mfma_f32_16x16x32_bf16 v[10:13], v[26:29], v[228:231], v[10:13]
	v_mfma_f32_16x16x32_bf16 v[94:97], v[22:25], v[186:189], v[94:97]
	v_mfma_f32_16x16x32_bf16 v[90:93], v[30:33], v[186:189], v[90:93]
	v_mfma_f32_16x16x32_bf16 v[78:81], v[22:25], v[216:219], v[78:81]
	v_mfma_f32_16x16x32_bf16 v[74:77], v[30:33], v[216:219], v[74:77]
	v_mfma_f32_16x16x32_bf16 v[62:65], v[22:25], v[224:227], v[62:65]
	v_mfma_f32_16x16x32_bf16 v[58:61], v[30:33], v[224:227], v[58:61]
	v_mfma_f32_16x16x32_bf16 v[14:17], v[22:25], v[232:235], v[14:17]
	v_mfma_f32_16x16x32_bf16 v[10:13], v[30:33], v[232:235], v[10:13]
	v_mfma_f32_16x16x32_bf16 v[38:41], v[42:45], v[220:223], v[38:41]
	v_mfma_f32_16x16x32_bf16 v[34:37], v[50:53], v[220:223], v[34:37]
	v_mfma_f32_16x16x32_bf16 v[6:9], v[42:45], v[228:231], v[6:9]
	v_mfma_f32_16x16x32_bf16 v[2:5], v[50:53], v[228:231], v[2:5]
	v_mfma_f32_16x16x32_bf16 v[18:21], v[42:45], v[182:185], v[86:89]
	v_mfma_f32_16x16x32_bf16 v[22:25], v[50:53], v[182:185], v[82:85]
	v_mfma_f32_16x16x32_bf16 v[26:29], v[42:45], v[212:215], v[70:73]
	v_mfma_f32_16x16x32_bf16 v[30:33], v[50:53], v[212:215], v[66:69]
	v_mfma_f32_16x16x32_bf16 v[38:41], v[46:49], v[224:227], v[38:41]
	v_mfma_f32_16x16x32_bf16 v[34:37], v[54:57], v[224:227], v[34:37]
	v_mfma_f32_16x16x32_bf16 v[6:9], v[46:49], v[232:235], v[6:9]
	v_mfma_f32_16x16x32_bf16 v[2:5], v[54:57], v[232:235], v[2:5]
	v_mfma_f32_16x16x32_bf16 v[18:21], v[46:49], v[186:189], v[18:21]
	v_mfma_f32_16x16x32_bf16 v[22:25], v[54:57], v[186:189], v[22:25]
	v_mfma_f32_16x16x32_bf16 v[26:29], v[46:49], v[216:219], v[26:29]
	v_mfma_f32_16x16x32_bf16 v[30:33], v[54:57], v[216:219], v[30:33]
	s_barrier
	s_add_i32 s52, 0, 0x18000
	s_add_i32 s53, 0, 0x1c000
	v_add_u32_e32 v54, s52, v193
	v_add_u32_e32 v66, s53, v193
	ds_read_b128 v[42:45], v54
	ds_read_b128 v[46:49], v54 offset:1024
	ds_read_b128 v[50:53], v54 offset:2048
	ds_read_b128 v[54:57], v54 offset:3072
	ds_read_b128 v[182:185], v66
	ds_read_b128 v[186:189], v66 offset:1024
	ds_read_b128 v[212:215], v66 offset:2048
	ds_read_b128 v[216:219], v66 offset:3072
	s_add_u32 s34, s34, 0x200000
	s_addc_u32 s35, s35, 0
	s_mov_b32 m0, s39
	v_lshl_add_u64 v[236:237], s[34:35], 0, v[162:163]
	ds_read_b128 v[66:69], v199 offset:32768
	global_load_lds_dwordx4 v[236:237], off
	ds_read_b128 v[70:73], v199 offset:33792
	ds_read_b128 v[82:85], v199 offset:34816
	v_lshl_add_u64 v[236:237], s[34:35], 0, v[164:165]
	s_mov_b32 m0, s44
	s_nop 0
	global_load_lds_dwordx4 v[236:237], off
	ds_read_b128 v[86:89], v199 offset:35840
	ds_read_b128 v[220:223], v199 offset:36864
	ds_read_b128 v[224:227], v199 offset:37888
	ds_read_b128 v[228:231], v199 offset:38912
	ds_read_b128 v[232:235], v199 offset:39936
	s_waitcnt vmcnt(8)
	s_waitcnt lgkmcnt(0)
	s_barrier
	s_waitcnt lgkmcnt(0)
	v_mfma_f32_16x16x32_bf16 v[158:161], v[42:45], v[66:69], v[158:161]
	v_mfma_f32_16x16x32_bf16 v[154:157], v[50:53], v[66:69], v[154:157]
	v_mfma_f32_16x16x32_bf16 v[142:145], v[42:45], v[82:85], v[142:145]
	v_mfma_f32_16x16x32_bf16 v[138:141], v[50:53], v[82:85], v[138:141]
	v_mfma_f32_16x16x32_bf16 v[126:129], v[42:45], v[220:223], v[126:129]
	v_mfma_f32_16x16x32_bf16 v[122:125], v[50:53], v[220:223], v[122:125]
	v_mfma_f32_16x16x32_bf16 v[110:113], v[42:45], v[228:231], v[110:113]
	v_mfma_f32_16x16x32_bf16 v[106:109], v[50:53], v[228:231], v[106:109]
	v_mfma_f32_16x16x32_bf16 v[158:161], v[46:49], v[70:73], v[158:161]
	v_mfma_f32_16x16x32_bf16 v[154:157], v[54:57], v[70:73], v[154:157]
	v_mfma_f32_16x16x32_bf16 v[142:145], v[46:49], v[86:89], v[142:145]
	v_mfma_f32_16x16x32_bf16 v[138:141], v[54:57], v[86:89], v[138:141]
	v_mfma_f32_16x16x32_bf16 v[126:129], v[46:49], v[224:227], v[126:129]
	v_mfma_f32_16x16x32_bf16 v[122:125], v[54:57], v[224:227], v[122:125]
	v_mfma_f32_16x16x32_bf16 v[110:113], v[46:49], v[232:235], v[110:113]
	v_mfma_f32_16x16x32_bf16 v[106:109], v[54:57], v[232:235], v[106:109]
	v_mfma_f32_16x16x32_bf16 v[150:153], v[182:185], v[66:69], v[150:153]
	v_mfma_f32_16x16x32_bf16 v[66:69], v[212:215], v[66:69], v[146:149]
	v_mfma_f32_16x16x32_bf16 v[146:149], v[216:219], v[70:73], v[66:69]
	v_mfma_f32_16x16x32_bf16 v[66:69], v[182:185], v[82:85], v[134:137]
	v_mfma_f32_16x16x32_bf16 v[134:137], v[186:189], v[86:89], v[66:69]
	v_mfma_f32_16x16x32_bf16 v[66:69], v[212:215], v[82:85], v[130:133]
	v_mfma_f32_16x16x32_bf16 v[130:133], v[216:219], v[86:89], v[66:69]
	v_mfma_f32_16x16x32_bf16 v[66:69], v[182:185], v[220:223], v[118:121]
	v_mfma_f32_16x16x32_bf16 v[118:121], v[186:189], v[224:227], v[66:69]
	v_mfma_f32_16x16x32_bf16 v[66:69], v[212:215], v[220:223], v[114:117]
	v_mfma_f32_16x16x32_bf16 v[114:117], v[216:219], v[224:227], v[66:69]
	v_mfma_f32_16x16x32_bf16 v[66:69], v[182:185], v[228:231], v[102:105]
	v_mfma_f32_16x16x32_bf16 v[102:105], v[186:189], v[232:235], v[66:69]
	v_mfma_f32_16x16x32_bf16 v[66:69], v[212:215], v[228:231], v[98:101]
	v_mfma_f32_16x16x32_bf16 v[150:153], v[186:189], v[70:73], v[150:153]
	v_mfma_f32_16x16x32_bf16 v[98:101], v[216:219], v[232:235], v[66:69]
	s_barrier
; #define PG8_STAGE(bufoff, gbase, voff) do { _Pragma("unroll") for (int _i = 0; _i < 2; ++_i) \
;         __builtin_amdgcn_global_load_lds((const unsigned*)((const char*)(gbase) + (voff)[_i]), (LAS unsigned*)(lds + (bufoff) + ldsw + _i * 8192), 16, 0, 0); } while (0)
; #define PG8_LDA(dst, b, h) do { _Pragma("unroll") for (int m = 0; m < 4; ++m) _Pragma("unroll") for (int k = 0; k < 2; ++k) dst[m][k] = *(const LAS bf16x8*)(lds + PG8_SA(b, h) + aoff + m * 2048 + k * 1024); } while (0)
; #define PG8_MMA(ai, bj, At, Bt) do { __builtin_amdgcn_s_setprio(1); _Pragma("unroll") for (int m = 0; m < 4; ++m) _Pragma("unroll") for (int n = 0; n < 2; ++n) _Pragma("unroll") for (int k = 0; k < 2; ++k) \
;         acc[ai][bj][m][n] = __builtin_amdgcn_mfma_f32_16x16x32_bf16(Bt[n][k], At[m][k], acc[ai][bj][m][n], 0, 0, 0); __builtin_amdgcn_s_setprio(0); } while (0)
; #define PG8_WAIT_V(n) asm volatile("s_waitcnt vmcnt(" #n ")" ::: "memory")
; #define PG8_WAIT_L(n) asm volatile("s_waitcnt lgkmcnt(" #n ")" ::: "memory")
; #define PG8_BAR __builtin_amdgcn_s_barrier()
; #define PG8_SCHED __builtin_amdgcn_sched_barrier(0)
; template <class Epi>
; __device__ __forceinline__ void gemm_phase(LAS unsigned char* lds, const Gemm g, const StaticOrder& S, const Epi& E, const int tid) {
;     ...
;             PG8_LDA(At, 1, 1); PG8_STAGE(PG8_SB(1, 0), b3, voffB); PG8_STAGE(PG8_SB(1, 1), b3 + bhs, voffB); PG8_STAGE(PG8_SA(1, 0), a3, voffA);
;             PG8_WAIT_V(8); PG8_WAIT_L(0); PG8_BAR; PG8_MMA(1, 0, At, B0); PG8_MMA(1, 1, At, B1); PG8_BAR; PG8_SCHED;
;     ...
;         if (ALIGN_EPI) { if (wr == 0) PG8_BAR; }
	s_add_i32 s34, s52, s36
	v_lshl_add_u64 v[82:83], v[172:173], 0, s[70:71]
	s_mov_b32 m0, s34
	s_nop 0
	ds_read_b128 v[66:69], v199 offset:49152
	global_load_lds_dwordx4 v[82:83], off
	ds_read_b128 v[70:73], v199 offset:50176
	ds_read_b128 v[220:223], v199 offset:51200
	s_add_i32 m0, s34, 0x2000
	s_add_u32 s30, s30, 0x20080
	v_lshl_add_u64 v[82:83], v[174:175], 0, s[70:71]
	s_addc_u32 s31, s31, 0
	s_add_i32 s34, s53, s36
	global_load_lds_dwordx4 v[82:83], off
	ds_read_b128 v[224:227], v199 offset:52224
	ds_read_b128 v[228:231], v199 offset:53248
	v_lshl_add_u64 v[82:83], s[30:31], 0, v[0:1]
	s_mov_b32 m0, s34
	s_nop 0
	global_load_lds_dwordx4 v[82:83], off
	ds_read_b128 v[232:235], v199 offset:54272
	ds_read_b128 v[236:239], v199 offset:55296
	v_lshl_add_u64 v[82:83], s[30:31], 0, v[166:167]
	s_add_i32 m0, s34, 0x2000
	s_nop 0
	global_load_lds_dwordx4 v[82:83], off
	ds_read_b128 v[240:243], v199 offset:56320
	v_lshl_add_u64 v[82:83], v[176:177], 0, s[70:71]
	s_mov_b32 m0, s45
	s_nop 0
	global_load_lds_dwordx4 v[82:83], off
	v_lshl_add_u64 v[82:83], v[200:201], 0, s[70:71]
	s_mov_b32 m0, s46
	s_nop 0
	global_load_lds_dwordx4 v[82:83], off
	s_waitcnt vmcnt(8)
	s_waitcnt lgkmcnt(0)
	s_barrier
	s_waitcnt lgkmcnt(0)
	v_mfma_f32_16x16x32_bf16 v[82:85], v[42:45], v[66:69], v[94:97]
	v_mfma_f32_16x16x32_bf16 v[94:97], v[46:49], v[70:73], v[82:85]
	v_mfma_f32_16x16x32_bf16 v[82:85], v[50:53], v[66:69], v[90:93]
	v_mfma_f32_16x16x32_bf16 v[78:81], v[42:45], v[220:223], v[78:81]
	v_mfma_f32_16x16x32_bf16 v[74:77], v[50:53], v[220:223], v[74:77]
	v_mfma_f32_16x16x32_bf16 v[62:65], v[42:45], v[228:231], v[62:65]
	v_mfma_f32_16x16x32_bf16 v[58:61], v[50:53], v[228:231], v[58:61]
	v_mfma_f32_16x16x32_bf16 v[14:17], v[42:45], v[236:239], v[14:17]
	v_mfma_f32_16x16x32_bf16 v[10:13], v[50:53], v[236:239], v[10:13]
	v_mfma_f32_16x16x32_bf16 v[90:93], v[54:57], v[70:73], v[82:85]
	v_mfma_f32_16x16x32_bf16 v[78:81], v[46:49], v[224:227], v[78:81]
	v_mfma_f32_16x16x32_bf16 v[74:77], v[54:57], v[224:227], v[74:77]
	v_mfma_f32_16x16x32_bf16 v[62:65], v[46:49], v[232:235], v[62:65]
	v_mfma_f32_16x16x32_bf16 v[58:61], v[54:57], v[232:235], v[58:61]
	v_mfma_f32_16x16x32_bf16 v[14:17], v[46:49], v[240:243], v[14:17]
	v_mfma_f32_16x16x32_bf16 v[10:13], v[54:57], v[240:243], v[10:13]
	v_mfma_f32_16x16x32_bf16 v[18:21], v[182:185], v[66:69], v[18:21]
	v_mfma_f32_16x16x32_bf16 v[86:89], v[186:189], v[70:73], v[18:21]
	v_mfma_f32_16x16x32_bf16 v[18:21], v[212:215], v[66:69], v[22:25]
	v_mfma_f32_16x16x32_bf16 v[82:85], v[216:219], v[70:73], v[18:21]
	v_mfma_f32_16x16x32_bf16 v[18:21], v[182:185], v[220:223], v[26:29]
	v_mfma_f32_16x16x32_bf16 v[70:73], v[186:189], v[224:227], v[18:21]
	v_mfma_f32_16x16x32_bf16 v[18:21], v[212:215], v[220:223], v[30:33]
	v_mfma_f32_16x16x32_bf16 v[66:69], v[216:219], v[224:227], v[18:21]
	v_mfma_f32_16x16x32_bf16 v[18:21], v[182:185], v[228:231], v[38:41]
	v_mfma_f32_16x16x32_bf16 v[38:41], v[186:189], v[232:235], v[18:21]
	v_mfma_f32_16x16x32_bf16 v[18:21], v[212:215], v[228:231], v[34:37]
	v_mfma_f32_16x16x32_bf16 v[6:9], v[182:185], v[236:239], v[6:9]
	v_mfma_f32_16x16x32_bf16 v[2:5], v[212:215], v[236:239], v[2:5]
	v_mfma_f32_16x16x32_bf16 v[34:37], v[216:219], v[232:235], v[18:21]
	v_mfma_f32_16x16x32_bf16 v[6:9], v[186:189], v[240:243], v[6:9]
	v_mfma_f32_16x16x32_bf16 v[2:5], v[216:219], v[240:243], v[2:5]
	s_barrier
	s_add_i32 s51, s51, 2
	s_add_u32 s49, s49, 0x100
	s_addc_u32 s50, s50, 0
	s_add_u32 s28, s28, 0x100
	s_addc_u32 s29, s29, 0
	s_cmpk_gt_u32 s51, 0x7d
	s_cbranch_scc0 .LBB0_126
	s_and_b64 vcc, exec, s[12:13]
	s_cbranch_vccz .LBB0_129
	s_barrier

; #define PG8_STAGE(bufoff, gbase, voff) do { _Pragma("unroll") for (int _i = 0; _i < 2; ++_i) \
;         __builtin_amdgcn_global_load_lds((const unsigned*)((const char*)(gbase) + (voff)[_i]), (LAS unsigned*)(lds + (bufoff) + ldsw + _i * 8192), 16, 0, 0); } while (0)
; #define PG8_LDA(dst, b, h) do { _Pragma("unroll") for (int m = 0; m < 4; ++m) _Pragma("unroll") for (int k = 0; k < 2; ++k) dst[m][k] = *(const LAS bf16x8*)(lds + PG8_SA(b, h) + aoff + m * 2048 + k * 1024); } while (0)
; #define PG8_LDB(dst, b, h) do { _Pragma("unroll") for (int n = 0; n < 2; ++n) _Pragma("unroll") for (int k = 0; k < 2; ++k) dst[n][k] = *(const LAS bf16x8*)(lds + PG8_SB(b, h) + boff + n * 2048 + k * 1024); } while (0)
; #define PG8_MMA(ai, bj, At, Bt) do { __builtin_amdgcn_s_setprio(1); _Pragma("unroll") for (int m = 0; m < 4; ++m) _Pragma("unroll") for (int n = 0; n < 2; ++n) _Pragma("unroll") for (int k = 0; k < 2; ++k) \
;         acc[ai][bj][m][n] = __builtin_amdgcn_mfma_f32_16x16x32_bf16(Bt[n][k], At[m][k], acc[ai][bj][m][n], 0, 0, 0); __builtin_amdgcn_s_setprio(0); } while (0)
; #define PG8_BAR __builtin_amdgcn_s_barrier()
; template <class Epi>
; __device__ __forceinline__ void gemm_phase(LAS unsigned char* lds, const Gemm g, const StaticOrder& S, const Epi& E, const int tid) {
;     ...
;         for (int t = 0; t < ntt; t += 2) {
;             const bool last = (t == ntt - 2);
;             const bool s1 = Epi::TWO && (t >= nt), s2 = Epi::TWO && (t + 2 >= nt);
;             const char* a1 = (s1 ? cA2 + (size_t)(t - nt + 1) * kstep : cA + (size_t)(t + 1) * kstep);
;             const char* a2 = last ? nA : (s2 ? cA2 + (size_t)(t + 2 - nt) * kstep : cA + (size_t)(t + 2) * kstep);
;             const char* b2 = last ? nB : (s2 ? cB2 + (size_t)(t + 2 - nt) * kstep : cB + (size_t)(t + 2) * kstep);
;             const char* a3 = a2 + kstep; const char* b3 = b2 + kstep;
;             if constexpr (Epi::TWO) { if (t == nt) E.mid(acc, cur, wr, wc, fr, fq); }
;             if constexpr (SP2) {
;             PG8_LDB(B0, 0, 0); PG8_LDB(B1, 0, 1); PG8_SCHED; PG8_LDA(At, 0, 0); PG8_STAGE(PG8_SA(1, 1), a1 + hstep, voffA);
;             PG8_WAIT_V(8); PG8_WAIT_L(0); PG8_BAR; PG8_MMA(0, 0, At, B0); PG8_MMA(0, 1, At, B1); PG8_BAR; PG8_SCHED;
;             PG8_LDA(At, 0, 1); PG8_STAGE(PG8_SB(0, 0), b2, voffB); PG8_STAGE(PG8_SB(0, 1), b2 + bhs, voffB); PG8_STAGE(PG8_SA(0, 0), a2, voffA);
.LBB0_173:
	s_add_u32 s28, s26, 0xfff80080
	s_addc_u32 s29, s27, -1
	s_add_i32 s47, 0, 0x10000
	s_cmp_eq_u32 s46, 28
	s_cselect_b32 s31, s17, s29
	s_cselect_b32 s30, s42, s28
	v_add_u32_e32 v142, s47, v149
	s_cselect_b32 s29, s15, s45
	s_cselect_b32 s28, s43, s44
	s_add_i32 s50, 0, 0x14000
	ds_read_b128 v[156:159], v142
	ds_read_b128 v[160:163], v142 offset:1024
	ds_read_b128 v[164:167], v142 offset:2048
	ds_read_b128 v[178:181], v142 offset:3072
	v_add_u32_e32 v142, s50, v149
	ds_read_b128 v[182:185], v142
	ds_read_b128 v[186:189], v142 offset:1024
	ds_read_b128 v[190:193], v142 offset:2048
	ds_read_b128 v[194:197], v142 offset:3072
	v_lshl_add_u64 v[142:143], s[26:27], 0, v[140:141]
	s_add_i32 m0, s2, 0xc000
	ds_read_b128 v[198:201], v154
	global_load_lds_dwordx4 v[142:143], off
	ds_read_b128 v[212:215], v154 offset:1024
	ds_read_b128 v[216:219], v154 offset:2048
	v_lshl_add_u64 v[142:143], s[26:27], 0, v[138:139]
	s_add_i32 m0, s2, 0xe000
	s_nop 0
	global_load_lds_dwordx4 v[142:143], off
	ds_read_b128 v[220:223], v154 offset:3072
	ds_read_b128 v[224:227], v154 offset:4096
	ds_read_b128 v[228:231], v154 offset:5120
	ds_read_b128 v[232:235], v154 offset:6144
	ds_read_b128 v[236:239], v154 offset:7168
	s_waitcnt vmcnt(8)
	s_waitcnt lgkmcnt(0)
	s_barrier
	s_waitcnt lgkmcnt(0)
	v_mfma_f32_16x16x32_bf16 v[126:129], v[156:159], v[198:201], v[126:129]
	v_mfma_f32_16x16x32_bf16 v[122:125], v[164:167], v[198:201], v[122:125]
	v_mfma_f32_16x16x32_bf16 v[110:113], v[156:159], v[216:219], v[110:113]
	v_mfma_f32_16x16x32_bf16 v[106:109], v[164:167], v[216:219], v[106:109]
	v_mfma_f32_16x16x32_bf16 v[94:97], v[156:159], v[224:227], v[94:97]
	v_mfma_f32_16x16x32_bf16 v[90:93], v[164:167], v[224:227], v[90:93]
	v_mfma_f32_16x16x32_bf16 v[78:81], v[156:159], v[232:235], v[78:81]
	v_mfma_f32_16x16x32_bf16 v[74:77], v[164:167], v[232:235], v[74:77]
	v_mfma_f32_16x16x32_bf16 v[126:129], v[160:163], v[212:215], v[126:129]
	v_mfma_f32_16x16x32_bf16 v[122:125], v[178:181], v[212:215], v[122:125]
	v_mfma_f32_16x16x32_bf16 v[110:113], v[160:163], v[220:223], v[110:113]
	v_mfma_f32_16x16x32_bf16 v[106:109], v[178:181], v[220:223], v[106:109]
	v_mfma_f32_16x16x32_bf16 v[94:97], v[160:163], v[228:231], v[94:97]
	v_mfma_f32_16x16x32_bf16 v[90:93], v[178:181], v[228:231], v[90:93]
	v_mfma_f32_16x16x32_bf16 v[78:81], v[160:163], v[236:239], v[78:81]
	v_mfma_f32_16x16x32_bf16 v[74:77], v[178:181], v[236:239], v[74:77]
	v_mfma_f32_16x16x32_bf16 v[118:121], v[182:185], v[198:201], v[118:121]
	v_mfma_f32_16x16x32_bf16 v[114:117], v[190:193], v[198:201], v[114:117]
	v_mfma_f32_16x16x32_bf16 v[102:105], v[182:185], v[216:219], v[102:105]
	v_mfma_f32_16x16x32_bf16 v[98:101], v[190:193], v[216:219], v[98:101]
	v_mfma_f32_16x16x32_bf16 v[86:89], v[182:185], v[224:227], v[86:89]
	v_mfma_f32_16x16x32_bf16 v[82:85], v[190:193], v[224:227], v[82:85]
	v_mfma_f32_16x16x32_bf16 v[70:73], v[182:185], v[232:235], v[70:73]
	v_mfma_f32_16x16x32_bf16 v[66:69], v[190:193], v[232:235], v[66:69]
	v_mfma_f32_16x16x32_bf16 v[118:121], v[186:189], v[212:215], v[118:121]
	v_mfma_f32_16x16x32_bf16 v[114:117], v[194:197], v[212:215], v[114:117]
	v_mfma_f32_16x16x32_bf16 v[102:105], v[186:189], v[220:223], v[102:105]
	v_mfma_f32_16x16x32_bf16 v[98:101], v[194:197], v[220:223], v[98:101]
	v_mfma_f32_16x16x32_bf16 v[86:89], v[186:189], v[228:231], v[86:89]
	v_mfma_f32_16x16x32_bf16 v[82:85], v[194:197], v[228:231], v[82:85]
	v_mfma_f32_16x16x32_bf16 v[70:73], v[186:189], v[236:239], v[70:73]
	v_mfma_f32_16x16x32_bf16 v[66:69], v[194:197], v[236:239], v[66:69]
	s_barrier
	s_add_i32 s47, s47, s34
	v_lshl_add_u64 v[142:143], s[28:29], 0, v[0:1]
	s_mov_b32 m0, s47
	ds_read_b128 v[198:201], v154 offset:16384
	global_load_lds_dwordx4 v[142:143], off
	ds_read_b128 v[212:215], v154 offset:17408
	ds_read_b128 v[216:219], v154 offset:18432
	s_add_i32 m0, s47, 0x2000
	s_add_u32 s48, s28, 0x8000
	v_lshl_add_u64 v[168:169], s[28:29], 0, v[134:135]
	s_addc_u32 s49, s29, 0
	s_add_i32 s47, s50, s34
	global_load_lds_dwordx4 v[168:169], off
	ds_read_b128 v[220:223], v154 offset:19456
	ds_read_b128 v[224:227], v154 offset:20480
	v_lshl_add_u64 v[172:173], s[48:49], 0, v[0:1]
	s_mov_b32 m0, s47
	v_lshl_add_u64 v[174:175], s[30:31], 0, v[132:133]
	global_load_lds_dwordx4 v[172:173], off
	ds_read_b128 v[228:231], v154 offset:21504
	ds_read_b128 v[232:235], v154 offset:22528
	v_lshl_add_u64 v[172:173], s[48:49], 0, v[134:135]
	s_add_i32 m0, s47, 0x2000
	s_nop 0
	global_load_lds_dwordx4 v[172:173], off
	ds_read_b128 v[236:239], v154 offset:23552
	v_lshl_add_u64 v[172:173], s[30:31], 0, v[130:131]
	s_mov_b32 m0, s2
	s_nop 0
	global_load_lds_dwordx4 v[172:173], off
	s_mov_b32 m0, s25
	s_nop 0
	global_load_lds_dwordx4 v[174:175], off
	s_waitcnt vmcnt(8)
	s_waitcnt lgkmcnt(0)
	s_barrier
; #define PG8_STAGE(bufoff, gbase, voff) do { _Pragma("unroll") for (int _i = 0; _i < 2; ++_i) \
;         __builtin_amdgcn_global_load_lds((const unsigned*)((const char*)(gbase) + (voff)[_i]), (LAS unsigned*)(lds + (bufoff) + ldsw + _i * 8192), 16, 0, 0); } while (0)
; #define PG8_LDA(dst, b, h) do { _Pragma("unroll") for (int m = 0; m < 4; ++m) _Pragma("unroll") for (int k = 0; k < 2; ++k) dst[m][k] = *(const LAS bf16x8*)(lds + PG8_SA(b, h) + aoff + m * 2048 + k * 1024); } while (0)
; #define PG8_LDB(dst, b, h) do { _Pragma("unroll") for (int n = 0; n < 2; ++n) _Pragma("unroll") for (int k = 0; k < 2; ++k) dst[n][k] = *(const LAS bf16x8*)(lds + PG8_SB(b, h) + boff + n * 2048 + k * 1024); } while (0)
; #define PG8_MMA(ai, bj, At, Bt) do { __builtin_amdgcn_s_setprio(1); _Pragma("unroll") for (int m = 0; m < 4; ++m) _Pragma("unroll") for (int n = 0; n < 2; ++n) _Pragma("unroll") for (int k = 0; k < 2; ++k) \
;         acc[ai][bj][m][n] = __builtin_amdgcn_mfma_f32_16x16x32_bf16(Bt[n][k], At[m][k], acc[ai][bj][m][n], 0, 0, 0); __builtin_amdgcn_s_setprio(0); } while (0)
; #define PG8_WAIT_V(n) asm volatile("s_waitcnt vmcnt(" #n ")" ::: "memory")
; #define PG8_WAIT_L(n) asm volatile("s_waitcnt lgkmcnt(" #n ")" ::: "memory")
; #define PG8_BAR __builtin_amdgcn_s_barrier()
; #define PG8_SCHED __builtin_amdgcn_sched_barrier(0)
; template <class Epi>
; __device__ __forceinline__ void gemm_phase(LAS unsigned char* lds, const Gemm g, const StaticOrder& S, const Epi& E, const int tid) {
;     ...
;             PG8_WAIT_V(8); PG8_WAIT_L(0); PG8_BAR; PG8_MMA(1, 0, At, B0); PG8_MMA(1, 1, At, B1); PG8_BAR; PG8_SCHED;
;             PG8_LDB(B0, 1, 0); PG8_LDB(B1, 1, 1); PG8_SCHED; PG8_LDA(At, 1, 0); PG8_STAGE(PG8_SA(0, 1), a2 + hstep, voffA);
;             PG8_WAIT_V(8); PG8_WAIT_L(0); PG8_BAR; PG8_MMA(0, 0, At, B0); PG8_MMA(0, 1, At, B1); PG8_BAR; PG8_SCHED;
	s_waitcnt lgkmcnt(0)
	v_mfma_f32_16x16x32_bf16 v[62:65], v[156:159], v[198:201], v[62:65]
	v_mfma_f32_16x16x32_bf16 v[58:61], v[164:167], v[198:201], v[58:61]
	v_mfma_f32_16x16x32_bf16 v[46:49], v[156:159], v[216:219], v[46:49]
	v_mfma_f32_16x16x32_bf16 v[42:45], v[164:167], v[216:219], v[42:45]
	v_mfma_f32_16x16x32_bf16 v[30:33], v[156:159], v[224:227], v[30:33]
	v_mfma_f32_16x16x32_bf16 v[26:29], v[164:167], v[224:227], v[26:29]
	v_mfma_f32_16x16x32_bf16 v[14:17], v[156:159], v[232:235], v[14:17]
	v_mfma_f32_16x16x32_bf16 v[10:13], v[164:167], v[232:235], v[10:13]
	v_mfma_f32_16x16x32_bf16 v[62:65], v[160:163], v[212:215], v[62:65]
	v_mfma_f32_16x16x32_bf16 v[58:61], v[178:181], v[212:215], v[58:61]
	v_mfma_f32_16x16x32_bf16 v[46:49], v[160:163], v[220:223], v[46:49]
	v_mfma_f32_16x16x32_bf16 v[42:45], v[178:181], v[220:223], v[42:45]
	v_mfma_f32_16x16x32_bf16 v[30:33], v[160:163], v[228:231], v[30:33]
	v_mfma_f32_16x16x32_bf16 v[26:29], v[178:181], v[228:231], v[26:29]
	v_mfma_f32_16x16x32_bf16 v[14:17], v[160:163], v[236:239], v[14:17]
	v_mfma_f32_16x16x32_bf16 v[10:13], v[178:181], v[236:239], v[10:13]
	v_mfma_f32_16x16x32_bf16 v[54:57], v[182:185], v[198:201], v[54:57]
	v_mfma_f32_16x16x32_bf16 v[50:53], v[190:193], v[198:201], v[50:53]
	v_mfma_f32_16x16x32_bf16 v[38:41], v[182:185], v[216:219], v[38:41]
	v_mfma_f32_16x16x32_bf16 v[34:37], v[190:193], v[216:219], v[34:37]
	v_mfma_f32_16x16x32_bf16 v[22:25], v[182:185], v[224:227], v[22:25]
	v_mfma_f32_16x16x32_bf16 v[18:21], v[190:193], v[224:227], v[18:21]
	v_mfma_f32_16x16x32_bf16 v[6:9], v[182:185], v[232:235], v[6:9]
	v_mfma_f32_16x16x32_bf16 v[2:5], v[190:193], v[232:235], v[2:5]
	v_mfma_f32_16x16x32_bf16 v[54:57], v[186:189], v[212:215], v[54:57]
	v_mfma_f32_16x16x32_bf16 v[50:53], v[194:197], v[212:215], v[50:53]
	v_mfma_f32_16x16x32_bf16 v[38:41], v[186:189], v[220:223], v[38:41]
	v_mfma_f32_16x16x32_bf16 v[34:37], v[194:197], v[220:223], v[34:37]
	v_mfma_f32_16x16x32_bf16 v[22:25], v[186:189], v[228:231], v[22:25]
	v_mfma_f32_16x16x32_bf16 v[18:21], v[194:197], v[228:231], v[18:21]
	v_mfma_f32_16x16x32_bf16 v[6:9], v[186:189], v[236:239], v[6:9]
	v_mfma_f32_16x16x32_bf16 v[2:5], v[194:197], v[236:239], v[2:5]
	s_barrier
	s_add_i32 s47, 0, 0x18000
	v_add_u32_e32 v155, s47, v149
	s_add_i32 s48, 0, 0x1c000
	ds_read_b128 v[156:159], v155
	ds_read_b128 v[160:163], v155 offset:1024
	ds_read_b128 v[164:167], v155 offset:2048
	ds_read_b128 v[178:181], v155 offset:3072
	v_add_u32_e32 v155, s48, v149
	ds_read_b128 v[182:185], v155
	ds_read_b128 v[186:189], v155 offset:1024
	ds_read_b128 v[190:193], v155 offset:2048
	ds_read_b128 v[194:197], v155 offset:3072
	s_add_u32 s30, s30, 0x80000
	s_addc_u32 s31, s31, 0
	s_mov_b32 m0, s35
	v_lshl_add_u64 v[176:177], s[30:31], 0, v[130:131]
	ds_read_b128 v[198:201], v154 offset:32768
	global_load_lds_dwordx4 v[176:177], off
	ds_read_b128 v[212:215], v154 offset:33792
	ds_read_b128 v[216:219], v154 offset:34816
	v_lshl_add_u64 v[176:177], s[30:31], 0, v[132:133]
	s_mov_b32 m0, s36
	s_nop 0
	global_load_lds_dwordx4 v[176:177], off
	ds_read_b128 v[220:223], v154 offset:35840
	ds_read_b128 v[224:227], v154 offset:36864
	ds_read_b128 v[228:231], v154 offset:37888
	ds_read_b128 v[232:235], v154 offset:38912
	ds_read_b128 v[236:239], v154 offset:39936
	s_waitcnt vmcnt(8)
	s_waitcnt lgkmcnt(0)
	s_barrier
	s_waitcnt lgkmcnt(0)
	v_mfma_f32_16x16x32_bf16 v[126:129], v[156:159], v[198:201], v[126:129]
	v_mfma_f32_16x16x32_bf16 v[122:125], v[164:167], v[198:201], v[122:125]
	v_mfma_f32_16x16x32_bf16 v[110:113], v[156:159], v[216:219], v[110:113]
	v_mfma_f32_16x16x32_bf16 v[106:109], v[164:167], v[216:219], v[106:109]
	v_mfma_f32_16x16x32_bf16 v[94:97], v[156:159], v[224:227], v[94:97]
	v_mfma_f32_16x16x32_bf16 v[90:93], v[164:167], v[224:227], v[90:93]
	v_mfma_f32_16x16x32_bf16 v[78:81], v[156:159], v[232:235], v[78:81]
	v_mfma_f32_16x16x32_bf16 v[74:77], v[164:167], v[232:235], v[74:77]
	v_mfma_f32_16x16x32_bf16 v[126:129], v[160:163], v[212:215], v[126:129]
	v_mfma_f32_16x16x32_bf16 v[122:125], v[178:181], v[212:215], v[122:125]
	v_mfma_f32_16x16x32_bf16 v[110:113], v[160:163], v[220:223], v[110:113]
	v_mfma_f32_16x16x32_bf16 v[106:109], v[178:181], v[220:223], v[106:109]
	v_mfma_f32_16x16x32_bf16 v[94:97], v[160:163], v[228:231], v[94:97]
	v_mfma_f32_16x16x32_bf16 v[90:93], v[178:181], v[228:231], v[90:93]
	v_mfma_f32_16x16x32_bf16 v[78:81], v[160:163], v[236:239], v[78:81]
	v_mfma_f32_16x16x32_bf16 v[74:77], v[178:181], v[236:239], v[74:77]
	v_mfma_f32_16x16x32_bf16 v[118:121], v[182:185], v[198:201], v[118:121]
	v_mfma_f32_16x16x32_bf16 v[114:117], v[190:193], v[198:201], v[114:117]
	v_mfma_f32_16x16x32_bf16 v[102:105], v[182:185], v[216:219], v[102:105]
	v_mfma_f32_16x16x32_bf16 v[98:101], v[190:193], v[216:219], v[98:101]
	v_mfma_f32_16x16x32_bf16 v[86:89], v[182:185], v[224:227], v[86:89]
	v_mfma_f32_16x16x32_bf16 v[82:85], v[190:193], v[224:227], v[82:85]
	v_mfma_f32_16x16x32_bf16 v[70:73], v[182:185], v[232:235], v[70:73]
	v_mfma_f32_16x16x32_bf16 v[66:69], v[190:193], v[232:235], v[66:69]
	v_mfma_f32_16x16x32_bf16 v[118:121], v[186:189], v[212:215], v[118:121]
	v_mfma_f32_16x16x32_bf16 v[114:117], v[194:197], v[212:215], v[114:117]
	v_mfma_f32_16x16x32_bf16 v[102:105], v[186:189], v[220:223], v[102:105]
	v_mfma_f32_16x16x32_bf16 v[98:101], v[194:197], v[220:223], v[98:101]
	v_mfma_f32_16x16x32_bf16 v[86:89], v[186:189], v[228:231], v[86:89]
	v_mfma_f32_16x16x32_bf16 v[82:85], v[194:197], v[228:231], v[82:85]
	v_mfma_f32_16x16x32_bf16 v[70:73], v[186:189], v[236:239], v[70:73]
	v_mfma_f32_16x16x32_bf16 v[66:69], v[194:197], v[236:239], v[66:69]
	s_barrier
; #define PG8_STAGE(bufoff, gbase, voff) do { _Pragma("unroll") for (int _i = 0; _i < 2; ++_i) \
;         __builtin_amdgcn_global_load_lds((const unsigned*)((const char*)(gbase) + (voff)[_i]), (LAS unsigned*)(lds + (bufoff) + ldsw + _i * 8192), 16, 0, 0); } while (0)
; #define PG8_LDA(dst, b, h) do { _Pragma("unroll") for (int m = 0; m < 4; ++m) _Pragma("unroll") for (int k = 0; k < 2; ++k) dst[m][k] = *(const LAS bf16x8*)(lds + PG8_SA(b, h) + aoff + m * 2048 + k * 1024); } while (0)
; #define PG8_MMA(ai, bj, At, Bt) do { __builtin_amdgcn_s_setprio(1); _Pragma("unroll") for (int m = 0; m < 4; ++m) _Pragma("unroll") for (int n = 0; n < 2; ++n) _Pragma("unroll") for (int k = 0; k < 2; ++k) \
;         acc[ai][bj][m][n] = __builtin_amdgcn_mfma_f32_16x16x32_bf16(Bt[n][k], At[m][k], acc[ai][bj][m][n], 0, 0, 0); __builtin_amdgcn_s_setprio(0); } while (0)
; #define PG8_WAIT_V(n) asm volatile("s_waitcnt vmcnt(" #n ")" ::: "memory")
; #define PG8_WAIT_L(n) asm volatile("s_waitcnt lgkmcnt(" #n ")" ::: "memory")
; #define PG8_BAR __builtin_amdgcn_s_barrier()
; #define PG8_SCHED __builtin_amdgcn_sched_barrier(0)
; template <class Epi>
; __device__ __forceinline__ void gemm_phase(LAS unsigned char* lds, const Gemm g, const StaticOrder& S, const Epi& E, const int tid) {
;     ...
;             PG8_LDA(At, 1, 1); PG8_STAGE(PG8_SB(1, 0), b3, voffB); PG8_STAGE(PG8_SB(1, 1), b3 + bhs, voffB); PG8_STAGE(PG8_SA(1, 0), a3, voffA);
;             PG8_WAIT_V(8); PG8_WAIT_L(0); PG8_BAR; PG8_MMA(1, 0, At, B0); PG8_MMA(1, 1, At, B1); PG8_BAR; PG8_SCHED;
;     ...
;         if (ALIGN_EPI) { if (wr == 0) PG8_BAR; }
	s_add_i32 s30, s47, s34
	v_lshl_add_u64 v[142:143], v[142:143], 0, s[70:71]
	s_mov_b32 m0, s30
	ds_read_b128 v[198:201], v154 offset:49152
	global_load_lds_dwordx4 v[142:143], off
	ds_read_b128 v[212:215], v154 offset:50176
	ds_read_b128 v[216:219], v154 offset:51200
	s_add_i32 m0, s30, 0x2000
	s_add_u32 s28, s28, 0x8080
	v_lshl_add_u64 v[142:143], v[168:169], 0, s[70:71]
	s_addc_u32 s29, s29, 0
	s_add_i32 s30, s48, s34
	global_load_lds_dwordx4 v[142:143], off
	ds_read_b128 v[220:223], v154 offset:52224
	ds_read_b128 v[224:227], v154 offset:53248
	v_lshl_add_u64 v[142:143], s[28:29], 0, v[0:1]
	s_mov_b32 m0, s30
	s_nop 0
	global_load_lds_dwordx4 v[142:143], off
	ds_read_b128 v[228:231], v154 offset:54272
	ds_read_b128 v[232:235], v154 offset:55296
	v_lshl_add_u64 v[142:143], s[28:29], 0, v[134:135]
	s_add_i32 m0, s30, 0x2000
	s_nop 0
	global_load_lds_dwordx4 v[142:143], off
	ds_read_b128 v[236:239], v154 offset:56320
	v_lshl_add_u64 v[142:143], v[172:173], 0, s[70:71]
	s_mov_b32 m0, s37
	s_nop 0
	global_load_lds_dwordx4 v[142:143], off
	v_lshl_add_u64 v[142:143], v[174:175], 0, s[70:71]
	s_mov_b32 m0, s38
	s_nop 0
	global_load_lds_dwordx4 v[142:143], off
	s_waitcnt vmcnt(8)
	s_waitcnt lgkmcnt(0)
	s_barrier
	s_waitcnt lgkmcnt(0)
	v_mfma_f32_16x16x32_bf16 v[62:65], v[156:159], v[198:201], v[62:65]
	v_mfma_f32_16x16x32_bf16 v[58:61], v[164:167], v[198:201], v[58:61]
	v_mfma_f32_16x16x32_bf16 v[46:49], v[156:159], v[216:219], v[46:49]
	v_mfma_f32_16x16x32_bf16 v[42:45], v[164:167], v[216:219], v[42:45]
	v_mfma_f32_16x16x32_bf16 v[30:33], v[156:159], v[224:227], v[30:33]
	v_mfma_f32_16x16x32_bf16 v[26:29], v[164:167], v[224:227], v[26:29]
	v_mfma_f32_16x16x32_bf16 v[14:17], v[156:159], v[232:235], v[14:17]
	v_mfma_f32_16x16x32_bf16 v[10:13], v[164:167], v[232:235], v[10:13]
	v_mfma_f32_16x16x32_bf16 v[62:65], v[160:163], v[212:215], v[62:65]
	v_mfma_f32_16x16x32_bf16 v[58:61], v[178:181], v[212:215], v[58:61]
	v_mfma_f32_16x16x32_bf16 v[46:49], v[160:163], v[220:223], v[46:49]
	v_mfma_f32_16x16x32_bf16 v[42:45], v[178:181], v[220:223], v[42:45]
	v_mfma_f32_16x16x32_bf16 v[30:33], v[160:163], v[228:231], v[30:33]
	v_mfma_f32_16x16x32_bf16 v[26:29], v[178:181], v[228:231], v[26:29]
	v_mfma_f32_16x16x32_bf16 v[14:17], v[160:163], v[236:239], v[14:17]
	v_mfma_f32_16x16x32_bf16 v[10:13], v[178:181], v[236:239], v[10:13]
	v_mfma_f32_16x16x32_bf16 v[54:57], v[182:185], v[198:201], v[54:57]
	v_mfma_f32_16x16x32_bf16 v[50:53], v[190:193], v[198:201], v[50:53]
	v_mfma_f32_16x16x32_bf16 v[38:41], v[182:185], v[216:219], v[38:41]
	v_mfma_f32_16x16x32_bf16 v[34:37], v[190:193], v[216:219], v[34:37]
	v_mfma_f32_16x16x32_bf16 v[22:25], v[182:185], v[224:227], v[22:25]
	v_mfma_f32_16x16x32_bf16 v[18:21], v[190:193], v[224:227], v[18:21]
	v_mfma_f32_16x16x32_bf16 v[6:9], v[182:185], v[232:235], v[6:9]
	v_mfma_f32_16x16x32_bf16 v[2:5], v[190:193], v[232:235], v[2:5]
	v_mfma_f32_16x16x32_bf16 v[54:57], v[186:189], v[212:215], v[54:57]
	v_mfma_f32_16x16x32_bf16 v[50:53], v[194:197], v[212:215], v[50:53]
	v_mfma_f32_16x16x32_bf16 v[38:41], v[186:189], v[220:223], v[38:41]
	v_mfma_f32_16x16x32_bf16 v[34:37], v[194:197], v[220:223], v[34:37]
	v_mfma_f32_16x16x32_bf16 v[22:25], v[186:189], v[228:231], v[22:25]
	v_mfma_f32_16x16x32_bf16 v[18:21], v[194:197], v[228:231], v[18:21]
	v_mfma_f32_16x16x32_bf16 v[6:9], v[186:189], v[236:239], v[6:9]
	v_mfma_f32_16x16x32_bf16 v[2:5], v[194:197], v[236:239], v[2:5]
	s_barrier
	s_add_i32 s46, s46, 2
	s_add_u32 s44, s44, 0x100
	s_addc_u32 s45, s45, 0
	s_add_u32 s26, s26, 0x100
	s_addc_u32 s27, s27, 0
	s_cmp_gt_u32 s46, 29
	s_cbranch_scc0 .LBB0_173
	v_readlane_b32 s42, v251, 53
	s_and_b64 vcc, exec, s[12:13]
	v_readlane_b32 s43, v251, 54
	s_cbranch_vccz .LBB0_176
	s_barrier

; #define PG8_STAGE(bufoff, gbase, voff) do { _Pragma("unroll") for (int _i = 0; _i < 2; ++_i) \
;         __builtin_amdgcn_global_load_lds((const unsigned*)((const char*)(gbase) + (voff)[_i]), (LAS unsigned*)(lds + (bufoff) + ldsw + _i * 8192), 16, 0, 0); } while (0)
; #define PG8_LDA(dst, b, h) do { _Pragma("unroll") for (int m = 0; m < 4; ++m) _Pragma("unroll") for (int k = 0; k < 2; ++k) dst[m][k] = *(const LAS bf16x8*)(lds + PG8_SA(b, h) + aoff + m * 2048 + k * 1024); } while (0)
; #define PG8_LDB(dst, b, h) do { _Pragma("unroll") for (int n = 0; n < 2; ++n) _Pragma("unroll") for (int k = 0; k < 2; ++k) dst[n][k] = *(const LAS bf16x8*)(lds + PG8_SB(b, h) + boff + n * 2048 + k * 1024); } while (0)
; #define PG8_MMA(ai, bj, At, Bt) do { __builtin_amdgcn_s_setprio(1); _Pragma("unroll") for (int m = 0; m < 4; ++m) _Pragma("unroll") for (int n = 0; n < 2; ++n) _Pragma("unroll") for (int k = 0; k < 2; ++k) \
;         acc[ai][bj][m][n] = __builtin_amdgcn_mfma_f32_16x16x32_bf16(Bt[n][k], At[m][k], acc[ai][bj][m][n], 0, 0, 0); __builtin_amdgcn_s_setprio(0); } while (0)
; #define PG8_BAR __builtin_amdgcn_s_barrier()
; template <class Epi>
; __device__ __forceinline__ void gemm_phase(LAS unsigned char* lds, const Gemm g, const StaticOrder& S, const Epi& E, const int tid) {
;     ...
;         for (int t = 0; t < ntt; t += 2) {
;             const bool last = (t == ntt - 2);
;             const bool s1 = Epi::TWO && (t >= nt), s2 = Epi::TWO && (t + 2 >= nt);
;             const char* a1 = (s1 ? cA2 + (size_t)(t - nt + 1) * kstep : cA + (size_t)(t + 1) * kstep);
;             const char* a2 = last ? nA : (s2 ? cA2 + (size_t)(t + 2 - nt) * kstep : cA + (size_t)(t + 2) * kstep);
;             const char* b2 = last ? nB : (s2 ? cB2 + (size_t)(t + 2 - nt) * kstep : cB + (size_t)(t + 2) * kstep);
;             const char* a3 = a2 + kstep; const char* b3 = b2 + kstep;
;             if constexpr (Epi::TWO) { if (t == nt) E.mid(acc, cur, wr, wc, fr, fq); }
;             if constexpr (SP2) {
;             PG8_LDB(B0, 0, 0); PG8_LDB(B1, 0, 1); PG8_SCHED; PG8_LDA(At, 0, 0); PG8_STAGE(PG8_SA(1, 1), a1 + hstep, voffA);
;             PG8_WAIT_V(8); PG8_WAIT_L(0); PG8_BAR; PG8_MMA(0, 0, At, B0); PG8_MMA(0, 1, At, B1); PG8_BAR; PG8_SCHED;
;             PG8_LDA(At, 0, 1); PG8_STAGE(PG8_SB(0, 0), b2, voffB); PG8_STAGE(PG8_SB(0, 1), b2 + bhs, voffB); PG8_STAGE(PG8_SA(0, 0), a2, voffA);
.LBB0_206:
	s_add_u32 s30, s28, 0xfffe0080
	s_addc_u32 s31, s29, -1
	s_add_i32 s52, 0, 0x10000
	s_cmp_eq_u32 s51, 4
	s_cselect_b32 s35, s17, s31
	s_cselect_b32 s34, s27, s30
	s_cselect_b32 s31, s15, s50
	s_cselect_b32 s30, s33, s49
	s_add_i32 s54, 0, 0x14000
	v_add_u32_e32 v30, s52, v193
	v_add_u32_e32 v54, s54, v193
	ds_read_b128 v[18:21], v30
	ds_read_b128 v[22:25], v30 offset:1024
	ds_read_b128 v[26:29], v30 offset:2048
	ds_read_b128 v[30:33], v30 offset:3072
	ds_read_b128 v[42:45], v54
	ds_read_b128 v[46:49], v54 offset:1024
	ds_read_b128 v[50:53], v54 offset:2048
	ds_read_b128 v[54:57], v54 offset:3072
	v_lshl_add_u64 v[172:173], s[28:29], 0, v[180:181]
	s_add_i32 m0, s37, 0xc000
	ds_read_b128 v[182:185], v199
	global_load_lds_dwordx4 v[172:173], off
	ds_read_b128 v[186:189], v199 offset:1024
	ds_read_b128 v[212:215], v199 offset:2048
	v_lshl_add_u64 v[172:173], s[28:29], 0, v[178:179]
	s_add_i32 m0, s37, 0xe000
	s_nop 0
	global_load_lds_dwordx4 v[172:173], off
	ds_read_b128 v[216:219], v199 offset:3072
	ds_read_b128 v[220:223], v199 offset:4096
	ds_read_b128 v[224:227], v199 offset:5120
	ds_read_b128 v[228:231], v199 offset:6144
	ds_read_b128 v[232:235], v199 offset:7168
	s_waitcnt vmcnt(8)
	s_waitcnt lgkmcnt(0)
	s_barrier
	s_waitcnt lgkmcnt(0)
	v_mfma_f32_16x16x32_bf16 v[158:161], v[18:21], v[182:185], v[158:161]
	v_mfma_f32_16x16x32_bf16 v[154:157], v[26:29], v[182:185], v[154:157]
	v_mfma_f32_16x16x32_bf16 v[142:145], v[18:21], v[212:215], v[142:145]
	v_mfma_f32_16x16x32_bf16 v[138:141], v[26:29], v[212:215], v[138:141]
	v_mfma_f32_16x16x32_bf16 v[126:129], v[18:21], v[220:223], v[126:129]
	v_mfma_f32_16x16x32_bf16 v[122:125], v[26:29], v[220:223], v[122:125]
	v_mfma_f32_16x16x32_bf16 v[110:113], v[18:21], v[228:231], v[110:113]
	v_mfma_f32_16x16x32_bf16 v[106:109], v[26:29], v[228:231], v[106:109]
	v_mfma_f32_16x16x32_bf16 v[158:161], v[22:25], v[186:189], v[158:161]
	v_mfma_f32_16x16x32_bf16 v[154:157], v[30:33], v[186:189], v[154:157]
	v_mfma_f32_16x16x32_bf16 v[142:145], v[22:25], v[216:219], v[142:145]
	v_mfma_f32_16x16x32_bf16 v[138:141], v[30:33], v[216:219], v[138:141]
	v_mfma_f32_16x16x32_bf16 v[126:129], v[22:25], v[224:227], v[126:129]
	v_mfma_f32_16x16x32_bf16 v[122:125], v[30:33], v[224:227], v[122:125]
	v_mfma_f32_16x16x32_bf16 v[110:113], v[22:25], v[232:235], v[110:113]
	v_mfma_f32_16x16x32_bf16 v[106:109], v[30:33], v[232:235], v[106:109]
	v_mfma_f32_16x16x32_bf16 v[150:153], v[42:45], v[182:185], v[150:153]
	v_mfma_f32_16x16x32_bf16 v[146:149], v[50:53], v[182:185], v[146:149]
	v_mfma_f32_16x16x32_bf16 v[134:137], v[42:45], v[212:215], v[134:137]
	v_mfma_f32_16x16x32_bf16 v[130:133], v[50:53], v[212:215], v[130:133]
	v_mfma_f32_16x16x32_bf16 v[118:121], v[42:45], v[220:223], v[118:121]
	v_mfma_f32_16x16x32_bf16 v[114:117], v[50:53], v[220:223], v[114:117]
	v_mfma_f32_16x16x32_bf16 v[102:105], v[42:45], v[228:231], v[102:105]
	v_mfma_f32_16x16x32_bf16 v[98:101], v[50:53], v[228:231], v[98:101]
	v_mfma_f32_16x16x32_bf16 v[150:153], v[46:49], v[186:189], v[150:153]
	v_mfma_f32_16x16x32_bf16 v[146:149], v[54:57], v[186:189], v[146:149]
	v_mfma_f32_16x16x32_bf16 v[134:137], v[46:49], v[216:219], v[134:137]
	v_mfma_f32_16x16x32_bf16 v[130:133], v[54:57], v[216:219], v[130:133]
	v_mfma_f32_16x16x32_bf16 v[118:121], v[46:49], v[224:227], v[118:121]
	v_mfma_f32_16x16x32_bf16 v[114:117], v[54:57], v[224:227], v[114:117]
	v_mfma_f32_16x16x32_bf16 v[102:105], v[46:49], v[232:235], v[102:105]
	v_mfma_f32_16x16x32_bf16 v[98:101], v[54:57], v[232:235], v[98:101]
	s_barrier
	s_add_i32 s52, s52, s36
	v_lshl_add_u64 v[172:173], s[30:31], 0, v[0:1]
	s_mov_b32 m0, s52
	ds_read_b128 v[182:185], v199 offset:16384
	global_load_lds_dwordx4 v[172:173], off
	ds_read_b128 v[186:189], v199 offset:17408
	ds_read_b128 v[212:215], v199 offset:18432
	s_add_i32 m0, s52, 0x2000
	s_add_u32 s52, s30, 0x2000
	v_lshl_add_u64 v[174:175], s[30:31], 0, v[166:167]
	s_addc_u32 s53, s31, 0
	s_add_i32 s54, s54, s36
	global_load_lds_dwordx4 v[174:175], off
	ds_read_b128 v[216:219], v199 offset:19456
	ds_read_b128 v[220:223], v199 offset:20480
	v_lshl_add_u64 v[176:177], s[52:53], 0, v[0:1]
	s_mov_b32 m0, s54
	v_lshl_add_u64 v[200:201], s[34:35], 0, v[164:165]
	global_load_lds_dwordx4 v[176:177], off
	ds_read_b128 v[224:227], v199 offset:21504
	ds_read_b128 v[228:231], v199 offset:22528
	v_lshl_add_u64 v[176:177], s[52:53], 0, v[166:167]
	s_add_i32 m0, s54, 0x2000
	s_nop 0
	global_load_lds_dwordx4 v[176:177], off
	ds_read_b128 v[232:235], v199 offset:23552
	v_lshl_add_u64 v[176:177], s[34:35], 0, v[162:163]
	s_mov_b32 m0, s37
	s_nop 0
	global_load_lds_dwordx4 v[176:177], off
	s_mov_b32 m0, s38
	s_nop 0
	global_load_lds_dwordx4 v[200:201], off
	s_waitcnt vmcnt(8)
	s_waitcnt lgkmcnt(0)
	s_barrier
; #define PG8_STAGE(bufoff, gbase, voff) do { _Pragma("unroll") for (int _i = 0; _i < 2; ++_i) \
;         __builtin_amdgcn_global_load_lds((const unsigned*)((const char*)(gbase) + (voff)[_i]), (LAS unsigned*)(lds + (bufoff) + ldsw + _i * 8192), 16, 0, 0); } while (0)
; #define PG8_LDA(dst, b, h) do { _Pragma("unroll") for (int m = 0; m < 4; ++m) _Pragma("unroll") for (int k = 0; k < 2; ++k) dst[m][k] = *(const LAS bf16x8*)(lds + PG8_SA(b, h) + aoff + m * 2048 + k * 1024); } while (0)
; #define PG8_LDB(dst, b, h) do { _Pragma("unroll") for (int n = 0; n < 2; ++n) _Pragma("unroll") for (int k = 0; k < 2; ++k) dst[n][k] = *(const LAS bf16x8*)(lds + PG8_SB(b, h) + boff + n * 2048 + k * 1024); } while (0)
; #define PG8_MMA(ai, bj, At, Bt) do { __builtin_amdgcn_s_setprio(1); _Pragma("unroll") for (int m = 0; m < 4; ++m) _Pragma("unroll") for (int n = 0; n < 2; ++n) _Pragma("unroll") for (int k = 0; k < 2; ++k) \
;         acc[ai][bj][m][n] = __builtin_amdgcn_mfma_f32_16x16x32_bf16(Bt[n][k], At[m][k], acc[ai][bj][m][n], 0, 0, 0); __builtin_amdgcn_s_setprio(0); } while (0)
; #define PG8_WAIT_V(n) asm volatile("s_waitcnt vmcnt(" #n ")" ::: "memory")
; #define PG8_WAIT_L(n) asm volatile("s_waitcnt lgkmcnt(" #n ")" ::: "memory")
; #define PG8_BAR __builtin_amdgcn_s_barrier()
; #define PG8_SCHED __builtin_amdgcn_sched_barrier(0)
; template <class Epi>
; __device__ __forceinline__ void gemm_phase(LAS unsigned char* lds, const Gemm g, const StaticOrder& S, const Epi& E, const int tid) {
;     ...
;             PG8_WAIT_V(8); PG8_WAIT_L(0); PG8_BAR; PG8_MMA(1, 0, At, B0); PG8_MMA(1, 1, At, B1); PG8_BAR; PG8_SCHED;
;             PG8_LDB(B0, 1, 0); PG8_LDB(B1, 1, 1); PG8_SCHED; PG8_LDA(At, 1, 0); PG8_STAGE(PG8_SA(0, 1), a2 + hstep, voffA);
;             PG8_WAIT_V(8); PG8_WAIT_L(0); PG8_BAR; PG8_MMA(0, 0, At, B0); PG8_MMA(0, 1, At, B1); PG8_BAR; PG8_SCHED;
	s_waitcnt lgkmcnt(0)
	v_mfma_f32_16x16x32_bf16 v[94:97], v[18:21], v[182:185], v[94:97]
	v_mfma_f32_16x16x32_bf16 v[90:93], v[26:29], v[182:185], v[90:93]
	v_mfma_f32_16x16x32_bf16 v[78:81], v[18:21], v[212:215], v[78:81]
	v_mfma_f32_16x16x32_bf16 v[74:77], v[26:29], v[212:215], v[74:77]
	v_mfma_f32_16x16x32_bf16 v[62:65], v[18:21], v[220:223], v[62:65]
	v_mfma_f32_16x16x32_bf16 v[58:61], v[26:29], v[220:223], v[58:61]
	v_mfma_f32_16x16x32_bf16 v[14:17], v[18:21], v[228:231], v[14:17]
	v_mfma_f32_16x16x32_bf16 v[10:13], v[26:29], v[228:231], v[10:13]
	v_mfma_f32_16x16x32_bf16 v[94:97], v[22:25], v[186:189], v[94:97]
	v_mfma_f32_16x16x32_bf16 v[90:93], v[30:33], v[186:189], v[90:93]
	v_mfma_f32_16x16x32_bf16 v[78:81], v[22:25], v[216:219], v[78:81]
	v_mfma_f32_16x16x32_bf16 v[74:77], v[30:33], v[216:219], v[74:77]
	v_mfma_f32_16x16x32_bf16 v[62:65], v[22:25], v[224:227], v[62:65]
	v_mfma_f32_16x16x32_bf16 v[58:61], v[30:33], v[224:227], v[58:61]
	v_mfma_f32_16x16x32_bf16 v[14:17], v[22:25], v[232:235], v[14:17]
	v_mfma_f32_16x16x32_bf16 v[10:13], v[30:33], v[232:235], v[10:13]
	v_mfma_f32_16x16x32_bf16 v[38:41], v[42:45], v[220:223], v[38:41]
	v_mfma_f32_16x16x32_bf16 v[34:37], v[50:53], v[220:223], v[34:37]
	v_mfma_f32_16x16x32_bf16 v[6:9], v[42:45], v[228:231], v[6:9]
	v_mfma_f32_16x16x32_bf16 v[2:5], v[50:53], v[228:231], v[2:5]
	v_mfma_f32_16x16x32_bf16 v[18:21], v[42:45], v[182:185], v[86:89]
	v_mfma_f32_16x16x32_bf16 v[22:25], v[50:53], v[182:185], v[82:85]
	v_mfma_f32_16x16x32_bf16 v[26:29], v[42:45], v[212:215], v[70:73]
	v_mfma_f32_16x16x32_bf16 v[30:33], v[50:53], v[212:215], v[66:69]
	v_mfma_f32_16x16x32_bf16 v[38:41], v[46:49], v[224:227], v[38:41]
	v_mfma_f32_16x16x32_bf16 v[34:37], v[54:57], v[224:227], v[34:37]
	v_mfma_f32_16x16x32_bf16 v[6:9], v[46:49], v[232:235], v[6:9]
	v_mfma_f32_16x16x32_bf16 v[2:5], v[54:57], v[232:235], v[2:5]
	v_mfma_f32_16x16x32_bf16 v[18:21], v[46:49], v[186:189], v[18:21]
	v_mfma_f32_16x16x32_bf16 v[22:25], v[54:57], v[186:189], v[22:25]
	v_mfma_f32_16x16x32_bf16 v[26:29], v[46:49], v[216:219], v[26:29]
	v_mfma_f32_16x16x32_bf16 v[30:33], v[54:57], v[216:219], v[30:33]
	s_barrier
	s_add_i32 s52, 0, 0x18000
	s_add_i32 s53, 0, 0x1c000
	v_add_u32_e32 v54, s52, v193
	v_add_u32_e32 v66, s53, v193
	ds_read_b128 v[42:45], v54
	ds_read_b128 v[46:49], v54 offset:1024
	ds_read_b128 v[50:53], v54 offset:2048
	ds_read_b128 v[54:57], v54 offset:3072
	ds_read_b128 v[182:185], v66
	ds_read_b128 v[186:189], v66 offset:1024
	ds_read_b128 v[212:215], v66 offset:2048
	ds_read_b128 v[216:219], v66 offset:3072
	s_add_u32 s34, s34, 0x20000
	s_addc_u32 s35, s35, 0
	s_mov_b32 m0, s39
	v_lshl_add_u64 v[236:237], s[34:35], 0, v[162:163]
	ds_read_b128 v[66:69], v199 offset:32768
	global_load_lds_dwordx4 v[236:237], off
	ds_read_b128 v[70:73], v199 offset:33792
	ds_read_b128 v[82:85], v199 offset:34816
	v_lshl_add_u64 v[236:237], s[34:35], 0, v[164:165]
	s_mov_b32 m0, s44
	s_nop 0
	global_load_lds_dwordx4 v[236:237], off
	ds_read_b128 v[86:89], v199 offset:35840
	ds_read_b128 v[220:223], v199 offset:36864
	ds_read_b128 v[224:227], v199 offset:37888
	ds_read_b128 v[228:231], v199 offset:38912
	ds_read_b128 v[232:235], v199 offset:39936
	s_waitcnt vmcnt(8)
	s_waitcnt lgkmcnt(0)
	s_barrier
	s_waitcnt lgkmcnt(0)
	v_mfma_f32_16x16x32_bf16 v[158:161], v[42:45], v[66:69], v[158:161]
	v_mfma_f32_16x16x32_bf16 v[154:157], v[50:53], v[66:69], v[154:157]
	v_mfma_f32_16x16x32_bf16 v[142:145], v[42:45], v[82:85], v[142:145]
	v_mfma_f32_16x16x32_bf16 v[138:141], v[50:53], v[82:85], v[138:141]
	v_mfma_f32_16x16x32_bf16 v[126:129], v[42:45], v[220:223], v[126:129]
	v_mfma_f32_16x16x32_bf16 v[122:125], v[50:53], v[220:223], v[122:125]
	v_mfma_f32_16x16x32_bf16 v[110:113], v[42:45], v[228:231], v[110:113]
	v_mfma_f32_16x16x32_bf16 v[106:109], v[50:53], v[228:231], v[106:109]
	v_mfma_f32_16x16x32_bf16 v[158:161], v[46:49], v[70:73], v[158:161]
	v_mfma_f32_16x16x32_bf16 v[154:157], v[54:57], v[70:73], v[154:157]
	v_mfma_f32_16x16x32_bf16 v[142:145], v[46:49], v[86:89], v[142:145]
	v_mfma_f32_16x16x32_bf16 v[138:141], v[54:57], v[86:89], v[138:141]
	v_mfma_f32_16x16x32_bf16 v[126:129], v[46:49], v[224:227], v[126:129]
	v_mfma_f32_16x16x32_bf16 v[122:125], v[54:57], v[224:227], v[122:125]
	v_mfma_f32_16x16x32_bf16 v[110:113], v[46:49], v[232:235], v[110:113]
	v_mfma_f32_16x16x32_bf16 v[106:109], v[54:57], v[232:235], v[106:109]
	v_mfma_f32_16x16x32_bf16 v[150:153], v[182:185], v[66:69], v[150:153]
	v_mfma_f32_16x16x32_bf16 v[66:69], v[212:215], v[66:69], v[146:149]
	v_mfma_f32_16x16x32_bf16 v[146:149], v[216:219], v[70:73], v[66:69]
	v_mfma_f32_16x16x32_bf16 v[66:69], v[182:185], v[82:85], v[134:137]
	v_mfma_f32_16x16x32_bf16 v[134:137], v[186:189], v[86:89], v[66:69]
	v_mfma_f32_16x16x32_bf16 v[66:69], v[212:215], v[82:85], v[130:133]
	v_mfma_f32_16x16x32_bf16 v[130:133], v[216:219], v[86:89], v[66:69]
	v_mfma_f32_16x16x32_bf16 v[66:69], v[182:185], v[220:223], v[118:121]
	v_mfma_f32_16x16x32_bf16 v[118:121], v[186:189], v[224:227], v[66:69]
	v_mfma_f32_16x16x32_bf16 v[66:69], v[212:215], v[220:223], v[114:117]
	v_mfma_f32_16x16x32_bf16 v[114:117], v[216:219], v[224:227], v[66:69]
	v_mfma_f32_16x16x32_bf16 v[66:69], v[182:185], v[228:231], v[102:105]
	v_mfma_f32_16x16x32_bf16 v[102:105], v[186:189], v[232:235], v[66:69]
	v_mfma_f32_16x16x32_bf16 v[66:69], v[212:215], v[228:231], v[98:101]
	v_mfma_f32_16x16x32_bf16 v[150:153], v[186:189], v[70:73], v[150:153]
	v_mfma_f32_16x16x32_bf16 v[98:101], v[216:219], v[232:235], v[66:69]
	s_barrier
; #define PG8_STAGE(bufoff, gbase, voff) do { _Pragma("unroll") for (int _i = 0; _i < 2; ++_i) \
;         __builtin_amdgcn_global_load_lds((const unsigned*)((const char*)(gbase) + (voff)[_i]), (LAS unsigned*)(lds + (bufoff) + ldsw + _i * 8192), 16, 0, 0); } while (0)
; #define PG8_LDA(dst, b, h) do { _Pragma("unroll") for (int m = 0; m < 4; ++m) _Pragma("unroll") for (int k = 0; k < 2; ++k) dst[m][k] = *(const LAS bf16x8*)(lds + PG8_SA(b, h) + aoff + m * 2048 + k * 1024); } while (0)
; #define PG8_MMA(ai, bj, At, Bt) do { __builtin_amdgcn_s_setprio(1); _Pragma("unroll") for (int m = 0; m < 4; ++m) _Pragma("unroll") for (int n = 0; n < 2; ++n) _Pragma("unroll") for (int k = 0; k < 2; ++k) \
;         acc[ai][bj][m][n] = __builtin_amdgcn_mfma_f32_16x16x32_bf16(Bt[n][k], At[m][k], acc[ai][bj][m][n], 0, 0, 0); __builtin_amdgcn_s_setprio(0); } while (0)
; #define PG8_WAIT_V(n) asm volatile("s_waitcnt vmcnt(" #n ")" ::: "memory")
; #define PG8_WAIT_L(n) asm volatile("s_waitcnt lgkmcnt(" #n ")" ::: "memory")
; #define PG8_BAR __builtin_amdgcn_s_barrier()
; #define PG8_SCHED __builtin_amdgcn_sched_barrier(0)
; template <class Epi>
; __device__ __forceinline__ void gemm_phase(LAS unsigned char* lds, const Gemm g, const StaticOrder& S, const Epi& E, const int tid) {
;     ...
;             PG8_LDA(At, 1, 1); PG8_STAGE(PG8_SB(1, 0), b3, voffB); PG8_STAGE(PG8_SB(1, 1), b3 + bhs, voffB); PG8_STAGE(PG8_SA(1, 0), a3, voffA);
;             PG8_WAIT_V(8); PG8_WAIT_L(0); PG8_BAR; PG8_MMA(1, 0, At, B0); PG8_MMA(1, 1, At, B1); PG8_BAR; PG8_SCHED;
;     ...
;         if (ALIGN_EPI) { if (wr == 0) PG8_BAR; }
	s_add_i32 s34, s52, s36
	v_lshl_add_u64 v[82:83], v[172:173], 0, s[70:71]
	s_mov_b32 m0, s34
	s_nop 0
	ds_read_b128 v[66:69], v199 offset:49152
	global_load_lds_dwordx4 v[82:83], off
	ds_read_b128 v[70:73], v199 offset:50176
	ds_read_b128 v[220:223], v199 offset:51200
	s_add_i32 m0, s34, 0x2000
	s_add_u32 s30, s30, 0x2080
	v_lshl_add_u64 v[82:83], v[174:175], 0, s[70:71]
	s_addc_u32 s31, s31, 0
	s_add_i32 s34, s53, s36
	global_load_lds_dwordx4 v[82:83], off
	ds_read_b128 v[224:227], v199 offset:52224
	ds_read_b128 v[228:231], v199 offset:53248
	v_lshl_add_u64 v[82:83], s[30:31], 0, v[0:1]
	s_mov_b32 m0, s34
	s_nop 0
	global_load_lds_dwordx4 v[82:83], off
	ds_read_b128 v[232:235], v199 offset:54272
	ds_read_b128 v[236:239], v199 offset:55296
	v_lshl_add_u64 v[82:83], s[30:31], 0, v[166:167]
	s_add_i32 m0, s34, 0x2000
	s_nop 0
	global_load_lds_dwordx4 v[82:83], off
	ds_read_b128 v[240:243], v199 offset:56320
	v_lshl_add_u64 v[82:83], v[176:177], 0, s[70:71]
	s_mov_b32 m0, s45
	s_nop 0
	global_load_lds_dwordx4 v[82:83], off
	v_lshl_add_u64 v[82:83], v[200:201], 0, s[70:71]
	s_mov_b32 m0, s46
	s_nop 0
	global_load_lds_dwordx4 v[82:83], off
	s_waitcnt vmcnt(8)
	s_waitcnt lgkmcnt(0)
	s_barrier
	s_waitcnt lgkmcnt(0)
	v_mfma_f32_16x16x32_bf16 v[82:85], v[42:45], v[66:69], v[94:97]
	v_mfma_f32_16x16x32_bf16 v[94:97], v[46:49], v[70:73], v[82:85]
	v_mfma_f32_16x16x32_bf16 v[82:85], v[50:53], v[66:69], v[90:93]
	v_mfma_f32_16x16x32_bf16 v[78:81], v[42:45], v[220:223], v[78:81]
	v_mfma_f32_16x16x32_bf16 v[74:77], v[50:53], v[220:223], v[74:77]
	v_mfma_f32_16x16x32_bf16 v[62:65], v[42:45], v[228:231], v[62:65]
	v_mfma_f32_16x16x32_bf16 v[58:61], v[50:53], v[228:231], v[58:61]
	v_mfma_f32_16x16x32_bf16 v[14:17], v[42:45], v[236:239], v[14:17]
	v_mfma_f32_16x16x32_bf16 v[10:13], v[50:53], v[236:239], v[10:13]
	v_mfma_f32_16x16x32_bf16 v[90:93], v[54:57], v[70:73], v[82:85]
	v_mfma_f32_16x16x32_bf16 v[78:81], v[46:49], v[224:227], v[78:81]
	v_mfma_f32_16x16x32_bf16 v[74:77], v[54:57], v[224:227], v[74:77]
	v_mfma_f32_16x16x32_bf16 v[62:65], v[46:49], v[232:235], v[62:65]
	v_mfma_f32_16x16x32_bf16 v[58:61], v[54:57], v[232:235], v[58:61]
	v_mfma_f32_16x16x32_bf16 v[14:17], v[46:49], v[240:243], v[14:17]
	v_mfma_f32_16x16x32_bf16 v[10:13], v[54:57], v[240:243], v[10:13]
	v_mfma_f32_16x16x32_bf16 v[18:21], v[182:185], v[66:69], v[18:21]
	v_mfma_f32_16x16x32_bf16 v[86:89], v[186:189], v[70:73], v[18:21]
	v_mfma_f32_16x16x32_bf16 v[18:21], v[212:215], v[66:69], v[22:25]
	v_mfma_f32_16x16x32_bf16 v[82:85], v[216:219], v[70:73], v[18:21]
	v_mfma_f32_16x16x32_bf16 v[18:21], v[182:185], v[220:223], v[26:29]
	v_mfma_f32_16x16x32_bf16 v[70:73], v[186:189], v[224:227], v[18:21]
	v_mfma_f32_16x16x32_bf16 v[18:21], v[212:215], v[220:223], v[30:33]
	v_mfma_f32_16x16x32_bf16 v[66:69], v[216:219], v[224:227], v[18:21]
	v_mfma_f32_16x16x32_bf16 v[18:21], v[182:185], v[228:231], v[38:41]
	v_mfma_f32_16x16x32_bf16 v[38:41], v[186:189], v[232:235], v[18:21]
	v_mfma_f32_16x16x32_bf16 v[18:21], v[212:215], v[228:231], v[34:37]
	v_mfma_f32_16x16x32_bf16 v[6:9], v[182:185], v[236:239], v[6:9]
	v_mfma_f32_16x16x32_bf16 v[2:5], v[212:215], v[236:239], v[2:5]
	v_mfma_f32_16x16x32_bf16 v[34:37], v[216:219], v[232:235], v[18:21]
	v_mfma_f32_16x16x32_bf16 v[6:9], v[186:189], v[240:243], v[6:9]
	v_mfma_f32_16x16x32_bf16 v[2:5], v[216:219], v[240:243], v[2:5]
	s_barrier
	s_add_i32 s51, s51, 2
	s_add_u32 s49, s49, 0x100
	s_addc_u32 s50, s50, 0
	s_add_u32 s28, s28, 0x100
	s_addc_u32 s29, s29, 0
	s_cmp_gt_u32 s51, 5
	s_cbranch_scc0 .LBB0_206
	s_and_b64 vcc, exec, s[12:13]
	s_cbranch_vccz .LBB0_209
	s_barrier

; #define PG8_STAGE(bufoff, gbase, voff) do { _Pragma("unroll") for (int _i = 0; _i < 2; ++_i) \
;         __builtin_amdgcn_global_load_lds((const unsigned*)((const char*)(gbase) + (voff)[_i]), (LAS unsigned*)(lds + (bufoff) + ldsw + _i * 8192), 16, 0, 0); } while (0)
; #define PG8_LDA(dst, b, h) do { _Pragma("unroll") for (int m = 0; m < 4; ++m) _Pragma("unroll") for (int k = 0; k < 2; ++k) dst[m][k] = *(const LAS bf16x8*)(lds + PG8_SA(b, h) + aoff + m * 2048 + k * 1024); } while (0)
; #define PG8_LDB(dst, b, h) do { _Pragma("unroll") for (int n = 0; n < 2; ++n) _Pragma("unroll") for (int k = 0; k < 2; ++k) dst[n][k] = *(const LAS bf16x8*)(lds + PG8_SB(b, h) + boff + n * 2048 + k * 1024); } while (0)
; #define PG8_MMA(ai, bj, At, Bt) do { __builtin_amdgcn_s_setprio(1); _Pragma("unroll") for (int m = 0; m < 4; ++m) _Pragma("unroll") for (int n = 0; n < 2; ++n) _Pragma("unroll") for (int k = 0; k < 2; ++k) \
;         acc[ai][bj][m][n] = __builtin_amdgcn_mfma_f32_16x16x32_bf16(Bt[n][k], At[m][k], acc[ai][bj][m][n], 0, 0, 0); __builtin_amdgcn_s_setprio(0); } while (0)
; #define PG8_BAR __builtin_amdgcn_s_barrier()
; template <class Epi>
; __device__ __forceinline__ void gemm_phase(LAS unsigned char* lds, const Gemm g, const StaticOrder& S, const Epi& E, const int tid) {
;     ...
;         for (int t = 0; t < ntt; t += 2) {
;             const bool last = (t == ntt - 2);
;             const bool s1 = Epi::TWO && (t >= nt), s2 = Epi::TWO && (t + 2 >= nt);
;             const char* a1 = (s1 ? cA2 + (size_t)(t - nt + 1) * kstep : cA + (size_t)(t + 1) * kstep);
;             const char* a2 = last ? nA : (s2 ? cA2 + (size_t)(t + 2 - nt) * kstep : cA + (size_t)(t + 2) * kstep);
;             const char* b2 = last ? nB : (s2 ? cB2 + (size_t)(t + 2 - nt) * kstep : cB + (size_t)(t + 2) * kstep);
;             const char* a3 = a2 + kstep; const char* b3 = b2 + kstep;
;             if constexpr (Epi::TWO) { if (t == nt) E.mid(acc, cur, wr, wc, fr, fq); }
;             if constexpr (SP2) {
;             PG8_LDB(B0, 0, 0); PG8_LDB(B1, 0, 1); PG8_SCHED; PG8_LDA(At, 0, 0); PG8_STAGE(PG8_SA(1, 1), a1 + hstep, voffA);
;             PG8_WAIT_V(8); PG8_WAIT_L(0); PG8_BAR; PG8_MMA(0, 0, At, B0); PG8_MMA(0, 1, At, B1); PG8_BAR; PG8_SCHED;
;             PG8_LDA(At, 0, 1); PG8_STAGE(PG8_SB(0, 0), b2, voffB); PG8_STAGE(PG8_SB(0, 1), b2 + bhs, voffB); PG8_STAGE(PG8_SA(0, 0), a2, voffA);
.LBB0_261:
	s_add_u32 s30, s28, 0xfff80080
	s_addc_u32 s31, s29, -1
	s_add_i32 s49, 0, 0x10000
	s_cmp_eq_u32 s48, 28
	s_cselect_b32 s35, s19, s31
	s_cselect_b32 s34, s44, s30
	v_add_u32_e32 v142, s49, v149
	s_cselect_b32 s31, s17, s47
	s_cselect_b32 s30, s45, s46
	s_add_i32 s52, 0, 0x14000
	ds_read_b128 v[156:159], v142
	ds_read_b128 v[160:163], v142 offset:1024
	ds_read_b128 v[164:167], v142 offset:2048
	ds_read_b128 v[178:181], v142 offset:3072
	v_add_u32_e32 v142, s52, v149
	ds_read_b128 v[182:185], v142
	ds_read_b128 v[186:189], v142 offset:1024
	ds_read_b128 v[190:193], v142 offset:2048
	ds_read_b128 v[194:197], v142 offset:3072
	v_lshl_add_u64 v[142:143], s[28:29], 0, v[140:141]
	s_add_i32 m0, s2, 0xc000
	ds_read_b128 v[198:201], v154
	global_load_lds_dwordx4 v[142:143], off
	ds_read_b128 v[212:215], v154 offset:1024
	ds_read_b128 v[216:219], v154 offset:2048
	v_lshl_add_u64 v[142:143], s[28:29], 0, v[138:139]
	s_add_i32 m0, s2, 0xe000
	s_nop 0
	global_load_lds_dwordx4 v[142:143], off
	ds_read_b128 v[220:223], v154 offset:3072
	ds_read_b128 v[224:227], v154 offset:4096
	ds_read_b128 v[228:231], v154 offset:5120
	ds_read_b128 v[232:235], v154 offset:6144
	ds_read_b128 v[236:239], v154 offset:7168
	s_waitcnt vmcnt(8)
	s_waitcnt lgkmcnt(0)
	s_barrier
	s_waitcnt lgkmcnt(0)
	v_mfma_f32_16x16x32_bf16 v[126:129], v[156:159], v[198:201], v[126:129]
	v_mfma_f32_16x16x32_bf16 v[122:125], v[164:167], v[198:201], v[122:125]
	v_mfma_f32_16x16x32_bf16 v[110:113], v[156:159], v[216:219], v[110:113]
	v_mfma_f32_16x16x32_bf16 v[106:109], v[164:167], v[216:219], v[106:109]
	v_mfma_f32_16x16x32_bf16 v[94:97], v[156:159], v[224:227], v[94:97]
	v_mfma_f32_16x16x32_bf16 v[90:93], v[164:167], v[224:227], v[90:93]
	v_mfma_f32_16x16x32_bf16 v[78:81], v[156:159], v[232:235], v[78:81]
	v_mfma_f32_16x16x32_bf16 v[74:77], v[164:167], v[232:235], v[74:77]
	v_mfma_f32_16x16x32_bf16 v[126:129], v[160:163], v[212:215], v[126:129]
	v_mfma_f32_16x16x32_bf16 v[122:125], v[178:181], v[212:215], v[122:125]
	v_mfma_f32_16x16x32_bf16 v[110:113], v[160:163], v[220:223], v[110:113]
	v_mfma_f32_16x16x32_bf16 v[106:109], v[178:181], v[220:223], v[106:109]
	v_mfma_f32_16x16x32_bf16 v[94:97], v[160:163], v[228:231], v[94:97]
	v_mfma_f32_16x16x32_bf16 v[90:93], v[178:181], v[228:231], v[90:93]
	v_mfma_f32_16x16x32_bf16 v[78:81], v[160:163], v[236:239], v[78:81]
	v_mfma_f32_16x16x32_bf16 v[74:77], v[178:181], v[236:239], v[74:77]
	v_mfma_f32_16x16x32_bf16 v[118:121], v[182:185], v[198:201], v[118:121]
	v_mfma_f32_16x16x32_bf16 v[114:117], v[190:193], v[198:201], v[114:117]
	v_mfma_f32_16x16x32_bf16 v[102:105], v[182:185], v[216:219], v[102:105]
	v_mfma_f32_16x16x32_bf16 v[98:101], v[190:193], v[216:219], v[98:101]
	v_mfma_f32_16x16x32_bf16 v[86:89], v[182:185], v[224:227], v[86:89]
	v_mfma_f32_16x16x32_bf16 v[82:85], v[190:193], v[224:227], v[82:85]
	v_mfma_f32_16x16x32_bf16 v[70:73], v[182:185], v[232:235], v[70:73]
	v_mfma_f32_16x16x32_bf16 v[66:69], v[190:193], v[232:235], v[66:69]
	v_mfma_f32_16x16x32_bf16 v[118:121], v[186:189], v[212:215], v[118:121]
	v_mfma_f32_16x16x32_bf16 v[114:117], v[194:197], v[212:215], v[114:117]
	v_mfma_f32_16x16x32_bf16 v[102:105], v[186:189], v[220:223], v[102:105]
	v_mfma_f32_16x16x32_bf16 v[98:101], v[194:197], v[220:223], v[98:101]
	v_mfma_f32_16x16x32_bf16 v[86:89], v[186:189], v[228:231], v[86:89]
	v_mfma_f32_16x16x32_bf16 v[82:85], v[194:197], v[228:231], v[82:85]
	v_mfma_f32_16x16x32_bf16 v[70:73], v[186:189], v[236:239], v[70:73]
	v_mfma_f32_16x16x32_bf16 v[66:69], v[194:197], v[236:239], v[66:69]
	s_barrier
	s_add_i32 s49, s49, s36
	v_lshl_add_u64 v[142:143], s[30:31], 0, v[0:1]
	s_mov_b32 m0, s49
	ds_read_b128 v[198:201], v154 offset:16384
	global_load_lds_dwordx4 v[142:143], off
	ds_read_b128 v[212:215], v154 offset:17408
	ds_read_b128 v[216:219], v154 offset:18432
	s_add_i32 m0, s49, 0x2000
	s_add_u32 s50, s30, 0x8000
	v_lshl_add_u64 v[168:169], s[30:31], 0, v[134:135]
	s_addc_u32 s51, s31, 0
	s_add_i32 s49, s52, s36
	global_load_lds_dwordx4 v[168:169], off
	ds_read_b128 v[220:223], v154 offset:19456
	ds_read_b128 v[224:227], v154 offset:20480
	v_lshl_add_u64 v[172:173], s[50:51], 0, v[0:1]
	s_mov_b32 m0, s49
	v_lshl_add_u64 v[174:175], s[34:35], 0, v[132:133]
	global_load_lds_dwordx4 v[172:173], off
	ds_read_b128 v[228:231], v154 offset:21504
	ds_read_b128 v[232:235], v154 offset:22528
	v_lshl_add_u64 v[172:173], s[50:51], 0, v[134:135]
	s_add_i32 m0, s49, 0x2000
	s_nop 0
	global_load_lds_dwordx4 v[172:173], off
	ds_read_b128 v[236:239], v154 offset:23552
	v_lshl_add_u64 v[172:173], s[34:35], 0, v[130:131]
	s_mov_b32 m0, s2
	s_nop 0
	global_load_lds_dwordx4 v[172:173], off
	s_mov_b32 m0, s27
	s_nop 0
	global_load_lds_dwordx4 v[174:175], off
	s_waitcnt vmcnt(8)
	s_waitcnt lgkmcnt(0)
	s_barrier
; #define PG8_STAGE(bufoff, gbase, voff) do { _Pragma("unroll") for (int _i = 0; _i < 2; ++_i) \
;         __builtin_amdgcn_global_load_lds((const unsigned*)((const char*)(gbase) + (voff)[_i]), (LAS unsigned*)(lds + (bufoff) + ldsw + _i * 8192), 16, 0, 0); } while (0)
; #define PG8_LDA(dst, b, h) do { _Pragma("unroll") for (int m = 0; m < 4; ++m) _Pragma("unroll") for (int k = 0; k < 2; ++k) dst[m][k] = *(const LAS bf16x8*)(lds + PG8_SA(b, h) + aoff + m * 2048 + k * 1024); } while (0)
; #define PG8_LDB(dst, b, h) do { _Pragma("unroll") for (int n = 0; n < 2; ++n) _Pragma("unroll") for (int k = 0; k < 2; ++k) dst[n][k] = *(const LAS bf16x8*)(lds + PG8_SB(b, h) + boff + n * 2048 + k * 1024); } while (0)
; #define PG8_MMA(ai, bj, At, Bt) do { __builtin_amdgcn_s_setprio(1); _Pragma("unroll") for (int m = 0; m < 4; ++m) _Pragma("unroll") for (int n = 0; n < 2; ++n) _Pragma("unroll") for (int k = 0; k < 2; ++k) \
;         acc[ai][bj][m][n] = __builtin_amdgcn_mfma_f32_16x16x32_bf16(Bt[n][k], At[m][k], acc[ai][bj][m][n], 0, 0, 0); __builtin_amdgcn_s_setprio(0); } while (0)
; #define PG8_WAIT_V(n) asm volatile("s_waitcnt vmcnt(" #n ")" ::: "memory")
; #define PG8_WAIT_L(n) asm volatile("s_waitcnt lgkmcnt(" #n ")" ::: "memory")
; #define PG8_BAR __builtin_amdgcn_s_barrier()
; #define PG8_SCHED __builtin_amdgcn_sched_barrier(0)
; template <class Epi>
; __device__ __forceinline__ void gemm_phase(LAS unsigned char* lds, const Gemm g, const StaticOrder& S, const Epi& E, const int tid) {
;     ...
;             PG8_WAIT_V(8); PG8_WAIT_L(0); PG8_BAR; PG8_MMA(1, 0, At, B0); PG8_MMA(1, 1, At, B1); PG8_BAR; PG8_SCHED;
;             PG8_LDB(B0, 1, 0); PG8_LDB(B1, 1, 1); PG8_SCHED; PG8_LDA(At, 1, 0); PG8_STAGE(PG8_SA(0, 1), a2 + hstep, voffA);
;             PG8_WAIT_V(8); PG8_WAIT_L(0); PG8_BAR; PG8_MMA(0, 0, At, B0); PG8_MMA(0, 1, At, B1); PG8_BAR; PG8_SCHED;
	s_waitcnt lgkmcnt(0)
	v_mfma_f32_16x16x32_bf16 v[62:65], v[156:159], v[198:201], v[62:65]
	v_mfma_f32_16x16x32_bf16 v[58:61], v[164:167], v[198:201], v[58:61]
	v_mfma_f32_16x16x32_bf16 v[46:49], v[156:159], v[216:219], v[46:49]
	v_mfma_f32_16x16x32_bf16 v[42:45], v[164:167], v[216:219], v[42:45]
	v_mfma_f32_16x16x32_bf16 v[30:33], v[156:159], v[224:227], v[30:33]
	v_mfma_f32_16x16x32_bf16 v[26:29], v[164:167], v[224:227], v[26:29]
	v_mfma_f32_16x16x32_bf16 v[14:17], v[156:159], v[232:235], v[14:17]
	v_mfma_f32_16x16x32_bf16 v[10:13], v[164:167], v[232:235], v[10:13]
	v_mfma_f32_16x16x32_bf16 v[62:65], v[160:163], v[212:215], v[62:65]
	v_mfma_f32_16x16x32_bf16 v[58:61], v[178:181], v[212:215], v[58:61]
	v_mfma_f32_16x16x32_bf16 v[46:49], v[160:163], v[220:223], v[46:49]
	v_mfma_f32_16x16x32_bf16 v[42:45], v[178:181], v[220:223], v[42:45]
	v_mfma_f32_16x16x32_bf16 v[30:33], v[160:163], v[228:231], v[30:33]
	v_mfma_f32_16x16x32_bf16 v[26:29], v[178:181], v[228:231], v[26:29]
	v_mfma_f32_16x16x32_bf16 v[14:17], v[160:163], v[236:239], v[14:17]
	v_mfma_f32_16x16x32_bf16 v[10:13], v[178:181], v[236:239], v[10:13]
	v_mfma_f32_16x16x32_bf16 v[54:57], v[182:185], v[198:201], v[54:57]
	v_mfma_f32_16x16x32_bf16 v[50:53], v[190:193], v[198:201], v[50:53]
	v_mfma_f32_16x16x32_bf16 v[38:41], v[182:185], v[216:219], v[38:41]
	v_mfma_f32_16x16x32_bf16 v[34:37], v[190:193], v[216:219], v[34:37]
	v_mfma_f32_16x16x32_bf16 v[22:25], v[182:185], v[224:227], v[22:25]
	v_mfma_f32_16x16x32_bf16 v[18:21], v[190:193], v[224:227], v[18:21]
	v_mfma_f32_16x16x32_bf16 v[6:9], v[182:185], v[232:235], v[6:9]
	v_mfma_f32_16x16x32_bf16 v[2:5], v[190:193], v[232:235], v[2:5]
	v_mfma_f32_16x16x32_bf16 v[54:57], v[186:189], v[212:215], v[54:57]
	v_mfma_f32_16x16x32_bf16 v[50:53], v[194:197], v[212:215], v[50:53]
	v_mfma_f32_16x16x32_bf16 v[38:41], v[186:189], v[220:223], v[38:41]
	v_mfma_f32_16x16x32_bf16 v[34:37], v[194:197], v[220:223], v[34:37]
	v_mfma_f32_16x16x32_bf16 v[22:25], v[186:189], v[228:231], v[22:25]
	v_mfma_f32_16x16x32_bf16 v[18:21], v[194:197], v[228:231], v[18:21]
	v_mfma_f32_16x16x32_bf16 v[6:9], v[186:189], v[236:239], v[6:9]
	v_mfma_f32_16x16x32_bf16 v[2:5], v[194:197], v[236:239], v[2:5]
	s_barrier
	s_add_i32 s49, 0, 0x18000
	v_add_u32_e32 v155, s49, v149
	s_add_i32 s50, 0, 0x1c000
	ds_read_b128 v[156:159], v155
	ds_read_b128 v[160:163], v155 offset:1024
	ds_read_b128 v[164:167], v155 offset:2048
	ds_read_b128 v[178:181], v155 offset:3072
	v_add_u32_e32 v155, s50, v149
	ds_read_b128 v[182:185], v155
	ds_read_b128 v[186:189], v155 offset:1024
	ds_read_b128 v[190:193], v155 offset:2048
	ds_read_b128 v[194:197], v155 offset:3072
	s_add_u32 s34, s34, 0x80000
	s_addc_u32 s35, s35, 0
	s_mov_b32 m0, s37
	v_lshl_add_u64 v[176:177], s[34:35], 0, v[130:131]
	ds_read_b128 v[198:201], v154 offset:32768
	global_load_lds_dwordx4 v[176:177], off
	ds_read_b128 v[212:215], v154 offset:33792
	ds_read_b128 v[216:219], v154 offset:34816
	v_lshl_add_u64 v[176:177], s[34:35], 0, v[132:133]
	s_mov_b32 m0, s38
	s_nop 0
	global_load_lds_dwordx4 v[176:177], off
	ds_read_b128 v[220:223], v154 offset:35840
	ds_read_b128 v[224:227], v154 offset:36864
	ds_read_b128 v[228:231], v154 offset:37888
	ds_read_b128 v[232:235], v154 offset:38912
	ds_read_b128 v[236:239], v154 offset:39936
	s_waitcnt vmcnt(8)
	s_waitcnt lgkmcnt(0)
	s_barrier
	s_waitcnt lgkmcnt(0)
	v_mfma_f32_16x16x32_bf16 v[126:129], v[156:159], v[198:201], v[126:129]
	v_mfma_f32_16x16x32_bf16 v[122:125], v[164:167], v[198:201], v[122:125]
	v_mfma_f32_16x16x32_bf16 v[110:113], v[156:159], v[216:219], v[110:113]
	v_mfma_f32_16x16x32_bf16 v[106:109], v[164:167], v[216:219], v[106:109]
	v_mfma_f32_16x16x32_bf16 v[94:97], v[156:159], v[224:227], v[94:97]
	v_mfma_f32_16x16x32_bf16 v[90:93], v[164:167], v[224:227], v[90:93]
	v_mfma_f32_16x16x32_bf16 v[78:81], v[156:159], v[232:235], v[78:81]
	v_mfma_f32_16x16x32_bf16 v[74:77], v[164:167], v[232:235], v[74:77]
	v_mfma_f32_16x16x32_bf16 v[126:129], v[160:163], v[212:215], v[126:129]
	v_mfma_f32_16x16x32_bf16 v[122:125], v[178:181], v[212:215], v[122:125]
	v_mfma_f32_16x16x32_bf16 v[110:113], v[160:163], v[220:223], v[110:113]
	v_mfma_f32_16x16x32_bf16 v[106:109], v[178:181], v[220:223], v[106:109]
	v_mfma_f32_16x16x32_bf16 v[94:97], v[160:163], v[228:231], v[94:97]
	v_mfma_f32_16x16x32_bf16 v[90:93], v[178:181], v[228:231], v[90:93]
	v_mfma_f32_16x16x32_bf16 v[78:81], v[160:163], v[236:239], v[78:81]
	v_mfma_f32_16x16x32_bf16 v[74:77], v[178:181], v[236:239], v[74:77]
	v_mfma_f32_16x16x32_bf16 v[118:121], v[182:185], v[198:201], v[118:121]
	v_mfma_f32_16x16x32_bf16 v[114:117], v[190:193], v[198:201], v[114:117]
	v_mfma_f32_16x16x32_bf16 v[102:105], v[182:185], v[216:219], v[102:105]
	v_mfma_f32_16x16x32_bf16 v[98:101], v[190:193], v[216:219], v[98:101]
	v_mfma_f32_16x16x32_bf16 v[86:89], v[182:185], v[224:227], v[86:89]
	v_mfma_f32_16x16x32_bf16 v[82:85], v[190:193], v[224:227], v[82:85]
	v_mfma_f32_16x16x32_bf16 v[70:73], v[182:185], v[232:235], v[70:73]
	v_mfma_f32_16x16x32_bf16 v[66:69], v[190:193], v[232:235], v[66:69]
	v_mfma_f32_16x16x32_bf16 v[118:121], v[186:189], v[212:215], v[118:121]
	v_mfma_f32_16x16x32_bf16 v[114:117], v[194:197], v[212:215], v[114:117]
	v_mfma_f32_16x16x32_bf16 v[102:105], v[186:189], v[220:223], v[102:105]
	v_mfma_f32_16x16x32_bf16 v[98:101], v[194:197], v[220:223], v[98:101]
	v_mfma_f32_16x16x32_bf16 v[86:89], v[186:189], v[228:231], v[86:89]
	v_mfma_f32_16x16x32_bf16 v[82:85], v[194:197], v[228:231], v[82:85]
	v_mfma_f32_16x16x32_bf16 v[70:73], v[186:189], v[236:239], v[70:73]
	v_mfma_f32_16x16x32_bf16 v[66:69], v[194:197], v[236:239], v[66:69]
	s_barrier
; #define PG8_STAGE(bufoff, gbase, voff) do { _Pragma("unroll") for (int _i = 0; _i < 2; ++_i) \
;         __builtin_amdgcn_global_load_lds((const unsigned*)((const char*)(gbase) + (voff)[_i]), (LAS unsigned*)(lds + (bufoff) + ldsw + _i * 8192), 16, 0, 0); } while (0)
; #define PG8_LDA(dst, b, h) do { _Pragma("unroll") for (int m = 0; m < 4; ++m) _Pragma("unroll") for (int k = 0; k < 2; ++k) dst[m][k] = *(const LAS bf16x8*)(lds + PG8_SA(b, h) + aoff + m * 2048 + k * 1024); } while (0)
; #define PG8_MMA(ai, bj, At, Bt) do { __builtin_amdgcn_s_setprio(1); _Pragma("unroll") for (int m = 0; m < 4; ++m) _Pragma("unroll") for (int n = 0; n < 2; ++n) _Pragma("unroll") for (int k = 0; k < 2; ++k) \
;         acc[ai][bj][m][n] = __builtin_amdgcn_mfma_f32_16x16x32_bf16(Bt[n][k], At[m][k], acc[ai][bj][m][n], 0, 0, 0); __builtin_amdgcn_s_setprio(0); } while (0)
; #define PG8_WAIT_V(n) asm volatile("s_waitcnt vmcnt(" #n ")" ::: "memory")
; #define PG8_WAIT_L(n) asm volatile("s_waitcnt lgkmcnt(" #n ")" ::: "memory")
; #define PG8_BAR __builtin_amdgcn_s_barrier()
; #define PG8_SCHED __builtin_amdgcn_sched_barrier(0)
; template <class Epi>
; __device__ __forceinline__ void gemm_phase(LAS unsigned char* lds, const Gemm g, const StaticOrder& S, const Epi& E, const int tid) {
;     ...
;             PG8_LDA(At, 1, 1); PG8_STAGE(PG8_SB(1, 0), b3, voffB); PG8_STAGE(PG8_SB(1, 1), b3 + bhs, voffB); PG8_STAGE(PG8_SA(1, 0), a3, voffA);
;             PG8_WAIT_V(8); PG8_WAIT_L(0); PG8_BAR; PG8_MMA(1, 0, At, B0); PG8_MMA(1, 1, At, B1); PG8_BAR; PG8_SCHED;
;     ...
;         if (ALIGN_EPI) { if (wr == 0) PG8_BAR; }
	s_add_i32 s34, s49, s36
	v_lshl_add_u64 v[142:143], v[142:143], 0, s[70:71]
	s_mov_b32 m0, s34
	ds_read_b128 v[198:201], v154 offset:49152
	global_load_lds_dwordx4 v[142:143], off
	ds_read_b128 v[212:215], v154 offset:50176
	ds_read_b128 v[216:219], v154 offset:51200
	s_add_i32 m0, s34, 0x2000
	s_add_u32 s30, s30, 0x8080
	v_lshl_add_u64 v[142:143], v[168:169], 0, s[70:71]
	s_addc_u32 s31, s31, 0
	s_add_i32 s34, s50, s36
	global_load_lds_dwordx4 v[142:143], off
	ds_read_b128 v[220:223], v154 offset:52224
	ds_read_b128 v[224:227], v154 offset:53248
	v_lshl_add_u64 v[142:143], s[30:31], 0, v[0:1]
	s_mov_b32 m0, s34
	s_nop 0
	global_load_lds_dwordx4 v[142:143], off
	ds_read_b128 v[228:231], v154 offset:54272
	ds_read_b128 v[232:235], v154 offset:55296
	v_lshl_add_u64 v[142:143], s[30:31], 0, v[134:135]
	s_add_i32 m0, s34, 0x2000
	s_nop 0
	global_load_lds_dwordx4 v[142:143], off
	ds_read_b128 v[236:239], v154 offset:56320
	v_lshl_add_u64 v[142:143], v[172:173], 0, s[70:71]
	s_mov_b32 m0, s39
	s_nop 0
	global_load_lds_dwordx4 v[142:143], off
	v_lshl_add_u64 v[142:143], v[174:175], 0, s[70:71]
	s_mov_b32 m0, s40
	s_nop 0
	global_load_lds_dwordx4 v[142:143], off
	s_waitcnt vmcnt(8)
	s_waitcnt lgkmcnt(0)
	s_barrier
	s_waitcnt lgkmcnt(0)
	v_mfma_f32_16x16x32_bf16 v[62:65], v[156:159], v[198:201], v[62:65]
	v_mfma_f32_16x16x32_bf16 v[58:61], v[164:167], v[198:201], v[58:61]
	v_mfma_f32_16x16x32_bf16 v[46:49], v[156:159], v[216:219], v[46:49]
	v_mfma_f32_16x16x32_bf16 v[42:45], v[164:167], v[216:219], v[42:45]
	v_mfma_f32_16x16x32_bf16 v[30:33], v[156:159], v[224:227], v[30:33]
	v_mfma_f32_16x16x32_bf16 v[26:29], v[164:167], v[224:227], v[26:29]
	v_mfma_f32_16x16x32_bf16 v[14:17], v[156:159], v[232:235], v[14:17]
	v_mfma_f32_16x16x32_bf16 v[10:13], v[164:167], v[232:235], v[10:13]
	v_mfma_f32_16x16x32_bf16 v[62:65], v[160:163], v[212:215], v[62:65]
	v_mfma_f32_16x16x32_bf16 v[58:61], v[178:181], v[212:215], v[58:61]
	v_mfma_f32_16x16x32_bf16 v[46:49], v[160:163], v[220:223], v[46:49]
	v_mfma_f32_16x16x32_bf16 v[42:45], v[178:181], v[220:223], v[42:45]
	v_mfma_f32_16x16x32_bf16 v[30:33], v[160:163], v[228:231], v[30:33]
	v_mfma_f32_16x16x32_bf16 v[26:29], v[178:181], v[228:231], v[26:29]
	v_mfma_f32_16x16x32_bf16 v[14:17], v[160:163], v[236:239], v[14:17]
	v_mfma_f32_16x16x32_bf16 v[10:13], v[178:181], v[236:239], v[10:13]
	v_mfma_f32_16x16x32_bf16 v[54:57], v[182:185], v[198:201], v[54:57]
	v_mfma_f32_16x16x32_bf16 v[50:53], v[190:193], v[198:201], v[50:53]
	v_mfma_f32_16x16x32_bf16 v[38:41], v[182:185], v[216:219], v[38:41]
	v_mfma_f32_16x16x32_bf16 v[34:37], v[190:193], v[216:219], v[34:37]
	v_mfma_f32_16x16x32_bf16 v[22:25], v[182:185], v[224:227], v[22:25]
	v_mfma_f32_16x16x32_bf16 v[18:21], v[190:193], v[224:227], v[18:21]
	v_mfma_f32_16x16x32_bf16 v[6:9], v[182:185], v[232:235], v[6:9]
	v_mfma_f32_16x16x32_bf16 v[2:5], v[190:193], v[232:235], v[2:5]
	v_mfma_f32_16x16x32_bf16 v[54:57], v[186:189], v[212:215], v[54:57]
	v_mfma_f32_16x16x32_bf16 v[50:53], v[194:197], v[212:215], v[50:53]
	v_mfma_f32_16x16x32_bf16 v[38:41], v[186:189], v[220:223], v[38:41]
	v_mfma_f32_16x16x32_bf16 v[34:37], v[194:197], v[220:223], v[34:37]
	v_mfma_f32_16x16x32_bf16 v[22:25], v[186:189], v[228:231], v[22:25]
	v_mfma_f32_16x16x32_bf16 v[18:21], v[194:197], v[228:231], v[18:21]
	v_mfma_f32_16x16x32_bf16 v[6:9], v[186:189], v[236:239], v[6:9]
	v_mfma_f32_16x16x32_bf16 v[2:5], v[194:197], v[236:239], v[2:5]
	s_barrier
	s_add_i32 s48, s48, 2
	s_add_u32 s46, s46, 0x100
	s_addc_u32 s47, s47, 0
	s_add_u32 s28, s28, 0x100
	s_addc_u32 s29, s29, 0
	s_cmp_gt_u32 s48, 29
	s_cbranch_scc0 .LBB0_261
	s_and_b64 vcc, exec, s[14:15]
	s_cbranch_vccz .LBB0_264
	s_barrier

; #define PG8_STAGE(bufoff, gbase, voff) do { _Pragma("unroll") for (int _i = 0; _i < 2; ++_i) \
;         __builtin_amdgcn_global_load_lds((const unsigned*)((const char*)(gbase) + (voff)[_i]), (LAS unsigned*)(lds + (bufoff) + ldsw + _i * 8192), 16, 0, 0); } while (0)
; #define PG8_LDA(dst, b, h) do { _Pragma("unroll") for (int m = 0; m < 4; ++m) _Pragma("unroll") for (int k = 0; k < 2; ++k) dst[m][k] = *(const LAS bf16x8*)(lds + PG8_SA(b, h) + aoff + m * 2048 + k * 1024); } while (0)
; #define PG8_LDB(dst, b, h) do { _Pragma("unroll") for (int n = 0; n < 2; ++n) _Pragma("unroll") for (int k = 0; k < 2; ++k) dst[n][k] = *(const LAS bf16x8*)(lds + PG8_SB(b, h) + boff + n * 2048 + k * 1024); } while (0)
; #define PG8_MMA(ai, bj, At, Bt) do { __builtin_amdgcn_s_setprio(1); _Pragma("unroll") for (int m = 0; m < 4; ++m) _Pragma("unroll") for (int n = 0; n < 2; ++n) _Pragma("unroll") for (int k = 0; k < 2; ++k) \
;         acc[ai][bj][m][n] = __builtin_amdgcn_mfma_f32_16x16x32_bf16(Bt[n][k], At[m][k], acc[ai][bj][m][n], 0, 0, 0); __builtin_amdgcn_s_setprio(0); } while (0)
; #define PG8_WAIT_V(n) asm volatile("s_waitcnt vmcnt(" #n ")" ::: "memory")
; #define PG8_WAIT_L(n) asm volatile("s_waitcnt lgkmcnt(" #n ")" ::: "memory")
; #define PG8_BAR __builtin_amdgcn_s_barrier()
; #define PG8_SCHED __builtin_amdgcn_sched_barrier(0)
; template <class Epi>
; __device__ __forceinline__ void gemm_phase(LAS unsigned char* lds, const Gemm g, const StaticOrder& S, const Epi& E, const int tid) {
;     ...
;             PG8_LDB(B0, 0, 0); PG8_LDB(B1, 0, 1); PG8_SCHED; PG8_LDA(At, 0, 0); PG8_STAGE(PG8_SA(1, 1), a1 + hstep, voffA);
;             PG8_WAIT_V(8); PG8_WAIT_L(0); PG8_BAR; PG8_MMA(0, 0, At, B0); PG8_MMA(0, 1, At, B1); PG8_BAR; PG8_SCHED;
;             PG8_LDA(At, 0, 1); PG8_STAGE(PG8_SB(0, 0), b2, voffB); PG8_STAGE(PG8_SB(0, 1), b2 + bhs, voffB); PG8_STAGE(PG8_SA(0, 0), a2, voffA);
;             PG8_WAIT_V(8); PG8_WAIT_L(0); PG8_BAR; PG8_MMA(1, 0, At, B0); PG8_MMA(1, 1, At, B1); PG8_BAR; PG8_SCHED;
.LBB0_314:
	s_add_u32 s40, s6, 0xfff80080
	s_addc_u32 s41, s7, -1
	s_add_i32 s56, 0, 0x10000
	s_cmp_eq_u32 s55, 28
	s_cselect_b32 s43, s27, s41
	s_cselect_b32 s42, s39, s40
	s_cselect_b32 s41, s25, s54
	s_cselect_b32 s40, s52, s53
	s_add_i32 s58, 0, 0x14000
	v_add_u32_e32 v46, s56, v212
	v_add_u32_e32 v70, s58, v212
	ds_read_b128 v[34:37], v46
	ds_read_b128 v[38:41], v46 offset:1024
	ds_read_b128 v[42:45], v46 offset:2048
	ds_read_b128 v[46:49], v46 offset:3072
	ds_read_b128 v[58:61], v70
	ds_read_b128 v[62:65], v70 offset:1024
	ds_read_b128 v[66:69], v70 offset:2048
	ds_read_b128 v[70:73], v70 offset:3072
	v_lshl_add_u64 v[172:173], s[6:7], 0, v[188:189]
	s_add_i32 m0, s44, 0xc000
	ds_read_b128 v[162:165], v220
	global_load_lds_dwordx4 v[172:173], off
	ds_read_b128 v[166:169], v220 offset:1024
	ds_read_b128 v[190:193], v220 offset:2048
	v_lshl_add_u64 v[172:173], s[6:7], 0, v[186:187]
	s_add_i32 m0, s44, 0xe000
	s_nop 0
	global_load_lds_dwordx4 v[172:173], off
	ds_read_b128 v[194:197], v220 offset:3072
	ds_read_b128 v[198:201], v220 offset:4096
	ds_read_b128 v[222:225], v220 offset:5120
	ds_read_b128 v[226:229], v220 offset:6144
	ds_read_b128 v[230:233], v220 offset:7168
	s_waitcnt vmcnt(8)
	s_waitcnt lgkmcnt(0)
	s_barrier
	s_waitcnt lgkmcnt(0)
	v_mfma_f32_16x16x32_bf16 v[158:161], v[34:37], v[162:165], v[158:161]
	v_mfma_f32_16x16x32_bf16 v[154:157], v[42:45], v[162:165], v[154:157]
	v_mfma_f32_16x16x32_bf16 v[142:145], v[34:37], v[190:193], v[142:145]
	v_mfma_f32_16x16x32_bf16 v[138:141], v[42:45], v[190:193], v[138:141]
	v_mfma_f32_16x16x32_bf16 v[126:129], v[34:37], v[198:201], v[126:129]
	v_mfma_f32_16x16x32_bf16 v[122:125], v[42:45], v[198:201], v[122:125]
	v_mfma_f32_16x16x32_bf16 v[110:113], v[34:37], v[226:229], v[110:113]
	v_mfma_f32_16x16x32_bf16 v[106:109], v[42:45], v[226:229], v[106:109]
	v_mfma_f32_16x16x32_bf16 v[158:161], v[38:41], v[166:169], v[158:161]
	v_mfma_f32_16x16x32_bf16 v[154:157], v[46:49], v[166:169], v[154:157]
	v_mfma_f32_16x16x32_bf16 v[142:145], v[38:41], v[194:197], v[142:145]
	v_mfma_f32_16x16x32_bf16 v[138:141], v[46:49], v[194:197], v[138:141]
	v_mfma_f32_16x16x32_bf16 v[126:129], v[38:41], v[222:225], v[126:129]
	v_mfma_f32_16x16x32_bf16 v[122:125], v[46:49], v[222:225], v[122:125]
	v_mfma_f32_16x16x32_bf16 v[110:113], v[38:41], v[230:233], v[110:113]
	v_mfma_f32_16x16x32_bf16 v[106:109], v[46:49], v[230:233], v[106:109]
	v_mfma_f32_16x16x32_bf16 v[150:153], v[58:61], v[162:165], v[150:153]
	v_mfma_f32_16x16x32_bf16 v[146:149], v[66:69], v[162:165], v[146:149]
	v_mfma_f32_16x16x32_bf16 v[134:137], v[58:61], v[190:193], v[134:137]
	v_mfma_f32_16x16x32_bf16 v[130:133], v[66:69], v[190:193], v[130:133]
	v_mfma_f32_16x16x32_bf16 v[118:121], v[58:61], v[198:201], v[118:121]
	v_mfma_f32_16x16x32_bf16 v[114:117], v[66:69], v[198:201], v[114:117]
	v_mfma_f32_16x16x32_bf16 v[102:105], v[58:61], v[226:229], v[102:105]
	v_mfma_f32_16x16x32_bf16 v[98:101], v[66:69], v[226:229], v[98:101]
	v_mfma_f32_16x16x32_bf16 v[150:153], v[62:65], v[166:169], v[150:153]
	v_mfma_f32_16x16x32_bf16 v[146:149], v[70:73], v[166:169], v[146:149]
	v_mfma_f32_16x16x32_bf16 v[134:137], v[62:65], v[194:197], v[134:137]
	v_mfma_f32_16x16x32_bf16 v[130:133], v[70:73], v[194:197], v[130:133]
	v_mfma_f32_16x16x32_bf16 v[118:121], v[62:65], v[222:225], v[118:121]
	v_mfma_f32_16x16x32_bf16 v[114:117], v[70:73], v[222:225], v[114:117]
	v_mfma_f32_16x16x32_bf16 v[102:105], v[62:65], v[230:233], v[102:105]
	v_mfma_f32_16x16x32_bf16 v[98:101], v[70:73], v[230:233], v[98:101]
	s_barrier
	s_add_i32 s56, s56, s33
	v_lshl_add_u64 v[172:173], s[40:41], 0, v[0:1]
	s_mov_b32 m0, s56
	ds_read_b128 v[162:165], v220 offset:16384
	global_load_lds_dwordx4 v[172:173], off
	ds_read_b128 v[166:169], v220 offset:17408
	ds_read_b128 v[190:193], v220 offset:18432
	s_add_i32 m0, s56, 0x2000
	s_add_u32 s56, s40, 0x8000
	v_lshl_add_u64 v[174:175], s[40:41], 0, v[182:183]
	s_addc_u32 s57, s41, 0
	s_add_i32 s58, s58, s33
	global_load_lds_dwordx4 v[174:175], off
	ds_read_b128 v[194:197], v220 offset:19456
	ds_read_b128 v[198:201], v220 offset:20480
	v_lshl_add_u64 v[176:177], s[56:57], 0, v[0:1]
	s_mov_b32 m0, s58
	v_lshl_add_u64 v[238:239], s[42:43], 0, v[180:181]
	global_load_lds_dwordx4 v[176:177], off
	ds_read_b128 v[222:225], v220 offset:21504
	ds_read_b128 v[226:229], v220 offset:22528
	v_lshl_add_u64 v[176:177], s[56:57], 0, v[182:183]
	s_add_i32 m0, s58, 0x2000
	s_nop 0
	global_load_lds_dwordx4 v[176:177], off
	ds_read_b128 v[230:233], v220 offset:23552
	v_lshl_add_u64 v[176:177], s[42:43], 0, v[178:179]
	s_mov_b32 m0, s44
	s_nop 0
	global_load_lds_dwordx4 v[176:177], off
	s_mov_b32 m0, s45
	s_nop 0
	global_load_lds_dwordx4 v[238:239], off
	s_waitcnt vmcnt(8)
	s_waitcnt lgkmcnt(0)
	s_barrier
; #define PG8_STAGE(bufoff, gbase, voff) do { _Pragma("unroll") for (int _i = 0; _i < 2; ++_i) \
;         __builtin_amdgcn_global_load_lds((const unsigned*)((const char*)(gbase) + (voff)[_i]), (LAS unsigned*)(lds + (bufoff) + ldsw + _i * 8192), 16, 0, 0); } while (0)
; #define PG8_LDA(dst, b, h) do { _Pragma("unroll") for (int m = 0; m < 4; ++m) _Pragma("unroll") for (int k = 0; k < 2; ++k) dst[m][k] = *(const LAS bf16x8*)(lds + PG8_SA(b, h) + aoff + m * 2048 + k * 1024); } while (0)
; #define PG8_LDB(dst, b, h) do { _Pragma("unroll") for (int n = 0; n < 2; ++n) _Pragma("unroll") for (int k = 0; k < 2; ++k) dst[n][k] = *(const LAS bf16x8*)(lds + PG8_SB(b, h) + boff + n * 2048 + k * 1024); } while (0)
; #define PG8_MMA(ai, bj, At, Bt) do { __builtin_amdgcn_s_setprio(1); _Pragma("unroll") for (int m = 0; m < 4; ++m) _Pragma("unroll") for (int n = 0; n < 2; ++n) _Pragma("unroll") for (int k = 0; k < 2; ++k) \
;         acc[ai][bj][m][n] = __builtin_amdgcn_mfma_f32_16x16x32_bf16(Bt[n][k], At[m][k], acc[ai][bj][m][n], 0, 0, 0); __builtin_amdgcn_s_setprio(0); } while (0)
; #define PG8_WAIT_V(n) asm volatile("s_waitcnt vmcnt(" #n ")" ::: "memory")
; #define PG8_WAIT_L(n) asm volatile("s_waitcnt lgkmcnt(" #n ")" ::: "memory")
; #define PG8_BAR __builtin_amdgcn_s_barrier()
; #define PG8_SCHED __builtin_amdgcn_sched_barrier(0)
; template <class Epi>
; __device__ __forceinline__ void gemm_phase(LAS unsigned char* lds, const Gemm g, const StaticOrder& S, const Epi& E, const int tid) {
;     ...
;             PG8_WAIT_V(8); PG8_WAIT_L(0); PG8_BAR; PG8_MMA(1, 0, At, B0); PG8_MMA(1, 1, At, B1); PG8_BAR; PG8_SCHED;
;             PG8_LDB(B0, 1, 0); PG8_LDB(B1, 1, 1); PG8_SCHED; PG8_LDA(At, 1, 0); PG8_STAGE(PG8_SA(0, 1), a2 + hstep, voffA);
;             PG8_WAIT_V(8); PG8_WAIT_L(0); PG8_BAR; PG8_MMA(0, 0, At, B0); PG8_MMA(0, 1, At, B1); PG8_BAR; PG8_SCHED;
	s_waitcnt lgkmcnt(0)
	v_mfma_f32_16x16x32_bf16 v[94:97], v[34:37], v[162:165], v[94:97]
	v_mfma_f32_16x16x32_bf16 v[90:93], v[42:45], v[162:165], v[90:93]
	v_mfma_f32_16x16x32_bf16 v[78:81], v[34:37], v[190:193], v[78:81]
	v_mfma_f32_16x16x32_bf16 v[74:77], v[42:45], v[190:193], v[74:77]
	v_mfma_f32_16x16x32_bf16 v[30:33], v[34:37], v[198:201], v[30:33]
	v_mfma_f32_16x16x32_bf16 v[26:29], v[42:45], v[198:201], v[26:29]
	v_mfma_f32_16x16x32_bf16 v[14:17], v[34:37], v[226:229], v[14:17]
	v_mfma_f32_16x16x32_bf16 v[10:13], v[42:45], v[226:229], v[10:13]
	v_mfma_f32_16x16x32_bf16 v[94:97], v[38:41], v[166:169], v[94:97]
	v_mfma_f32_16x16x32_bf16 v[90:93], v[46:49], v[166:169], v[90:93]
	v_mfma_f32_16x16x32_bf16 v[78:81], v[38:41], v[194:197], v[78:81]
	v_mfma_f32_16x16x32_bf16 v[74:77], v[46:49], v[194:197], v[74:77]
	v_mfma_f32_16x16x32_bf16 v[30:33], v[38:41], v[222:225], v[30:33]
	v_mfma_f32_16x16x32_bf16 v[26:29], v[46:49], v[222:225], v[26:29]
	v_mfma_f32_16x16x32_bf16 v[14:17], v[38:41], v[230:233], v[14:17]
	v_mfma_f32_16x16x32_bf16 v[10:13], v[46:49], v[230:233], v[10:13]
	v_mfma_f32_16x16x32_bf16 v[22:25], v[58:61], v[198:201], v[22:25]
	v_mfma_f32_16x16x32_bf16 v[18:21], v[66:69], v[198:201], v[18:21]
	v_mfma_f32_16x16x32_bf16 v[6:9], v[58:61], v[226:229], v[6:9]
	v_mfma_f32_16x16x32_bf16 v[2:5], v[66:69], v[226:229], v[2:5]
	v_mfma_f32_16x16x32_bf16 v[34:37], v[58:61], v[162:165], v[86:89]
	v_mfma_f32_16x16x32_bf16 v[38:41], v[66:69], v[162:165], v[82:85]
	v_mfma_f32_16x16x32_bf16 v[42:45], v[58:61], v[190:193], v[54:57]
	v_mfma_f32_16x16x32_bf16 v[46:49], v[66:69], v[190:193], v[50:53]
	v_mfma_f32_16x16x32_bf16 v[22:25], v[62:65], v[222:225], v[22:25]
	v_mfma_f32_16x16x32_bf16 v[18:21], v[70:73], v[222:225], v[18:21]
	v_mfma_f32_16x16x32_bf16 v[6:9], v[62:65], v[230:233], v[6:9]
	v_mfma_f32_16x16x32_bf16 v[2:5], v[70:73], v[230:233], v[2:5]
	v_mfma_f32_16x16x32_bf16 v[34:37], v[62:65], v[166:169], v[34:37]
	v_mfma_f32_16x16x32_bf16 v[38:41], v[70:73], v[166:169], v[38:41]
	v_mfma_f32_16x16x32_bf16 v[42:45], v[62:65], v[194:197], v[42:45]
	v_mfma_f32_16x16x32_bf16 v[46:49], v[70:73], v[194:197], v[46:49]
	s_barrier
	s_add_i32 s56, 0, 0x18000
	s_add_i32 s57, 0, 0x1c000
	v_add_u32_e32 v62, s56, v212
	v_add_u32_e32 v82, s57, v212
	ds_read_b128 v[50:53], v62
	ds_read_b128 v[54:57], v62 offset:1024
	ds_read_b128 v[58:61], v62 offset:2048
	ds_read_b128 v[62:65], v62 offset:3072
	ds_read_b128 v[66:69], v82
	ds_read_b128 v[70:73], v82 offset:1024
	ds_read_b128 v[162:165], v82 offset:2048
	ds_read_b128 v[166:169], v82 offset:3072
	s_add_u32 s42, s42, 0x80000
	s_addc_u32 s43, s43, 0
	s_mov_b32 m0, s46
	v_lshl_add_u64 v[234:235], s[42:43], 0, v[178:179]
	ds_read_b128 v[82:85], v220 offset:32768
	global_load_lds_dwordx4 v[234:235], off
	ds_read_b128 v[86:89], v220 offset:33792
	ds_read_b128 v[190:193], v220 offset:34816
	v_lshl_add_u64 v[234:235], s[42:43], 0, v[180:181]
	s_mov_b32 m0, s47
	s_nop 0
	global_load_lds_dwordx4 v[234:235], off
	ds_read_b128 v[194:197], v220 offset:35840
	ds_read_b128 v[198:201], v220 offset:36864
	ds_read_b128 v[222:225], v220 offset:37888
	ds_read_b128 v[226:229], v220 offset:38912
	ds_read_b128 v[230:233], v220 offset:39936
	s_waitcnt vmcnt(8)
	s_waitcnt lgkmcnt(0)
	s_barrier
	s_waitcnt lgkmcnt(0)
	v_mfma_f32_16x16x32_bf16 v[158:161], v[50:53], v[82:85], v[158:161]
	v_mfma_f32_16x16x32_bf16 v[154:157], v[58:61], v[82:85], v[154:157]
	v_mfma_f32_16x16x32_bf16 v[142:145], v[50:53], v[190:193], v[142:145]
	v_mfma_f32_16x16x32_bf16 v[138:141], v[58:61], v[190:193], v[138:141]
	v_mfma_f32_16x16x32_bf16 v[126:129], v[50:53], v[198:201], v[126:129]
	v_mfma_f32_16x16x32_bf16 v[122:125], v[58:61], v[198:201], v[122:125]
	v_mfma_f32_16x16x32_bf16 v[110:113], v[50:53], v[226:229], v[110:113]
	v_mfma_f32_16x16x32_bf16 v[106:109], v[58:61], v[226:229], v[106:109]
	v_mfma_f32_16x16x32_bf16 v[158:161], v[54:57], v[86:89], v[158:161]
	v_mfma_f32_16x16x32_bf16 v[154:157], v[62:65], v[86:89], v[154:157]
	v_mfma_f32_16x16x32_bf16 v[142:145], v[54:57], v[194:197], v[142:145]
	v_mfma_f32_16x16x32_bf16 v[138:141], v[62:65], v[194:197], v[138:141]
	v_mfma_f32_16x16x32_bf16 v[126:129], v[54:57], v[222:225], v[126:129]
	v_mfma_f32_16x16x32_bf16 v[122:125], v[62:65], v[222:225], v[122:125]
	v_mfma_f32_16x16x32_bf16 v[110:113], v[54:57], v[230:233], v[110:113]
	v_mfma_f32_16x16x32_bf16 v[106:109], v[62:65], v[230:233], v[106:109]
	v_mfma_f32_16x16x32_bf16 v[150:153], v[66:69], v[82:85], v[150:153]
	v_mfma_f32_16x16x32_bf16 v[82:85], v[162:165], v[82:85], v[146:149]
	v_mfma_f32_16x16x32_bf16 v[146:149], v[166:169], v[86:89], v[82:85]
	v_mfma_f32_16x16x32_bf16 v[82:85], v[66:69], v[190:193], v[134:137]
	v_mfma_f32_16x16x32_bf16 v[134:137], v[70:73], v[194:197], v[82:85]
	v_mfma_f32_16x16x32_bf16 v[82:85], v[162:165], v[190:193], v[130:133]
	v_mfma_f32_16x16x32_bf16 v[130:133], v[166:169], v[194:197], v[82:85]
	v_mfma_f32_16x16x32_bf16 v[82:85], v[66:69], v[198:201], v[118:121]
	v_mfma_f32_16x16x32_bf16 v[118:121], v[70:73], v[222:225], v[82:85]
	v_mfma_f32_16x16x32_bf16 v[82:85], v[162:165], v[198:201], v[114:117]
	v_mfma_f32_16x16x32_bf16 v[114:117], v[166:169], v[222:225], v[82:85]
	v_mfma_f32_16x16x32_bf16 v[82:85], v[66:69], v[226:229], v[102:105]
	v_mfma_f32_16x16x32_bf16 v[102:105], v[70:73], v[230:233], v[82:85]
	v_mfma_f32_16x16x32_bf16 v[82:85], v[162:165], v[226:229], v[98:101]
	v_mfma_f32_16x16x32_bf16 v[150:153], v[70:73], v[86:89], v[150:153]
	v_mfma_f32_16x16x32_bf16 v[98:101], v[166:169], v[230:233], v[82:85]
	s_barrier
; #define PG8_STAGE(bufoff, gbase, voff) do { _Pragma("unroll") for (int _i = 0; _i < 2; ++_i) \
;         __builtin_amdgcn_global_load_lds((const unsigned*)((const char*)(gbase) + (voff)[_i]), (LAS unsigned*)(lds + (bufoff) + ldsw + _i * 8192), 16, 0, 0); } while (0)
; #define PG8_LDA(dst, b, h) do { _Pragma("unroll") for (int m = 0; m < 4; ++m) _Pragma("unroll") for (int k = 0; k < 2; ++k) dst[m][k] = *(const LAS bf16x8*)(lds + PG8_SA(b, h) + aoff + m * 2048 + k * 1024); } while (0)
; #define PG8_MMA(ai, bj, At, Bt) do { __builtin_amdgcn_s_setprio(1); _Pragma("unroll") for (int m = 0; m < 4; ++m) _Pragma("unroll") for (int n = 0; n < 2; ++n) _Pragma("unroll") for (int k = 0; k < 2; ++k) \
;         acc[ai][bj][m][n] = __builtin_amdgcn_mfma_f32_16x16x32_bf16(Bt[n][k], At[m][k], acc[ai][bj][m][n], 0, 0, 0); __builtin_amdgcn_s_setprio(0); } while (0)
; #define PG8_WAIT_V(n) asm volatile("s_waitcnt vmcnt(" #n ")" ::: "memory")
; #define PG8_WAIT_L(n) asm volatile("s_waitcnt lgkmcnt(" #n ")" ::: "memory")
; #define PG8_BAR __builtin_amdgcn_s_barrier()
; #define PG8_SCHED __builtin_amdgcn_sched_barrier(0)
; template <class Epi>
; __device__ __forceinline__ void gemm_phase(LAS unsigned char* lds, const Gemm g, const StaticOrder& S, const Epi& E, const int tid) {
;     ...
;             PG8_LDA(At, 1, 1); PG8_STAGE(PG8_SB(1, 0), b3, voffB); PG8_STAGE(PG8_SB(1, 1), b3 + bhs, voffB); PG8_STAGE(PG8_SA(1, 0), a3, voffA);
;             PG8_WAIT_V(8); PG8_WAIT_L(0); PG8_BAR; PG8_MMA(1, 0, At, B0); PG8_MMA(1, 1, At, B1); PG8_BAR; PG8_SCHED;
;     ...
;         if (ALIGN_EPI) { if (wr == 0) PG8_BAR; }
	s_add_i32 s42, s56, s33
	v_lshl_add_u64 v[86:87], v[172:173], 0, s[70:71]
	s_mov_b32 m0, s42
	s_nop 0
	ds_read_b128 v[82:85], v220 offset:49152
	global_load_lds_dwordx4 v[86:87], off
	ds_read_b128 v[190:193], v220 offset:50176
	ds_read_b128 v[194:197], v220 offset:51200
	s_add_i32 m0, s42, 0x2000
	s_add_u32 s40, s40, 0x8080
	v_lshl_add_u64 v[86:87], v[174:175], 0, s[70:71]
	s_addc_u32 s41, s41, 0
	s_add_i32 s42, s57, s33
	global_load_lds_dwordx4 v[86:87], off
	ds_read_b128 v[198:201], v220 offset:52224
	ds_read_b128 v[222:225], v220 offset:53248
	v_lshl_add_u64 v[86:87], s[40:41], 0, v[0:1]
	s_mov_b32 m0, s42
	s_nop 0
	global_load_lds_dwordx4 v[86:87], off
	ds_read_b128 v[226:229], v220 offset:54272
	ds_read_b128 v[230:233], v220 offset:55296
	v_lshl_add_u64 v[86:87], s[40:41], 0, v[182:183]
	s_add_i32 m0, s42, 0x2000
	s_nop 0
	global_load_lds_dwordx4 v[86:87], off
	ds_read_b128 v[234:237], v220 offset:56320
	v_lshl_add_u64 v[86:87], v[176:177], 0, s[70:71]
	s_mov_b32 m0, s48
	s_nop 0
	global_load_lds_dwordx4 v[86:87], off
	v_lshl_add_u64 v[86:87], v[238:239], 0, s[70:71]
	s_mov_b32 m0, s49
	s_nop 0
	global_load_lds_dwordx4 v[86:87], off
	s_waitcnt vmcnt(8)
	s_waitcnt lgkmcnt(0)
	s_barrier
	s_waitcnt lgkmcnt(0)
	v_mfma_f32_16x16x32_bf16 v[86:89], v[50:53], v[82:85], v[94:97]
	v_mfma_f32_16x16x32_bf16 v[94:97], v[54:57], v[190:193], v[86:89]
	v_mfma_f32_16x16x32_bf16 v[86:89], v[58:61], v[82:85], v[90:93]
	v_mfma_f32_16x16x32_bf16 v[78:81], v[50:53], v[194:197], v[78:81]
	v_mfma_f32_16x16x32_bf16 v[74:77], v[58:61], v[194:197], v[74:77]
	v_mfma_f32_16x16x32_bf16 v[30:33], v[50:53], v[222:225], v[30:33]
	v_mfma_f32_16x16x32_bf16 v[26:29], v[58:61], v[222:225], v[26:29]
	v_mfma_f32_16x16x32_bf16 v[14:17], v[50:53], v[230:233], v[14:17]
	v_mfma_f32_16x16x32_bf16 v[10:13], v[58:61], v[230:233], v[10:13]
	v_mfma_f32_16x16x32_bf16 v[90:93], v[62:65], v[190:193], v[86:89]
	v_mfma_f32_16x16x32_bf16 v[78:81], v[54:57], v[198:201], v[78:81]
	v_mfma_f32_16x16x32_bf16 v[74:77], v[62:65], v[198:201], v[74:77]
	v_mfma_f32_16x16x32_bf16 v[30:33], v[54:57], v[226:229], v[30:33]
	v_mfma_f32_16x16x32_bf16 v[26:29], v[62:65], v[226:229], v[26:29]
	v_mfma_f32_16x16x32_bf16 v[14:17], v[54:57], v[234:237], v[14:17]
	v_mfma_f32_16x16x32_bf16 v[10:13], v[62:65], v[234:237], v[10:13]
	v_mfma_f32_16x16x32_bf16 v[34:37], v[66:69], v[82:85], v[34:37]
	v_mfma_f32_16x16x32_bf16 v[86:89], v[70:73], v[190:193], v[34:37]
	v_mfma_f32_16x16x32_bf16 v[34:37], v[162:165], v[82:85], v[38:41]
	v_mfma_f32_16x16x32_bf16 v[82:85], v[166:169], v[190:193], v[34:37]
	v_mfma_f32_16x16x32_bf16 v[34:37], v[66:69], v[194:197], v[42:45]
	v_mfma_f32_16x16x32_bf16 v[54:57], v[70:73], v[198:201], v[34:37]
	v_mfma_f32_16x16x32_bf16 v[34:37], v[162:165], v[194:197], v[46:49]
	v_mfma_f32_16x16x32_bf16 v[22:25], v[66:69], v[222:225], v[22:25]
	v_mfma_f32_16x16x32_bf16 v[18:21], v[162:165], v[222:225], v[18:21]
	v_mfma_f32_16x16x32_bf16 v[6:9], v[66:69], v[230:233], v[6:9]
	v_mfma_f32_16x16x32_bf16 v[2:5], v[162:165], v[230:233], v[2:5]
	v_mfma_f32_16x16x32_bf16 v[50:53], v[166:169], v[198:201], v[34:37]
	v_mfma_f32_16x16x32_bf16 v[22:25], v[70:73], v[226:229], v[22:25]
	v_mfma_f32_16x16x32_bf16 v[18:21], v[166:169], v[226:229], v[18:21]
	v_mfma_f32_16x16x32_bf16 v[6:9], v[70:73], v[234:237], v[6:9]
	v_mfma_f32_16x16x32_bf16 v[2:5], v[166:169], v[234:237], v[2:5]
	s_barrier
	s_add_i32 s55, s55, 2
	s_add_u32 s53, s53, 0x100
	s_addc_u32 s54, s54, 0
	s_add_u32 s6, s6, 0x100
	s_addc_u32 s7, s7, 0
	s_cmp_gt_u32 s55, 29
	s_cbranch_scc0 .LBB0_314
	s_and_b64 vcc, exec, s[22:23]
	s_cbranch_vccz .LBB0_317
	s_barrier

; #define PG8_STAGE(bufoff, gbase, voff) do { _Pragma("unroll") for (int _i = 0; _i < 2; ++_i) \
;         __builtin_amdgcn_global_load_lds((const unsigned*)((const char*)(gbase) + (voff)[_i]), (LAS unsigned*)(lds + (bufoff) + ldsw + _i * 8192), 16, 0, 0); } while (0)
; #define PG8_LDA(dst, b, h) do { _Pragma("unroll") for (int m = 0; m < 4; ++m) _Pragma("unroll") for (int k = 0; k < 2; ++k) dst[m][k] = *(const LAS bf16x8*)(lds + PG8_SA(b, h) + aoff + m * 2048 + k * 1024); } while (0)
; #define PG8_LDB(dst, b, h) do { _Pragma("unroll") for (int n = 0; n < 2; ++n) _Pragma("unroll") for (int k = 0; k < 2; ++k) dst[n][k] = *(const LAS bf16x8*)(lds + PG8_SB(b, h) + boff + n * 2048 + k * 1024); } while (0)
; #define PG8_MMA(ai, bj, At, Bt) do { __builtin_amdgcn_s_setprio(1); _Pragma("unroll") for (int m = 0; m < 4; ++m) _Pragma("unroll") for (int n = 0; n < 2; ++n) _Pragma("unroll") for (int k = 0; k < 2; ++k) \
;         acc[ai][bj][m][n] = __builtin_amdgcn_mfma_f32_16x16x32_bf16(Bt[n][k], At[m][k], acc[ai][bj][m][n], 0, 0, 0); __builtin_amdgcn_s_setprio(0); } while (0)
; #define PG8_WAIT_V(n) asm volatile("s_waitcnt vmcnt(" #n ")" ::: "memory")
; #define PG8_WAIT_L(n) asm volatile("s_waitcnt lgkmcnt(" #n ")" ::: "memory")
; #define PG8_BAR __builtin_amdgcn_s_barrier()
; #define PG8_SCHED __builtin_amdgcn_sched_barrier(0)
; template <class Epi>
; __device__ __forceinline__ void gemm_phase(LAS unsigned char* lds, const Gemm g, const StaticOrder& S, const Epi& E, const int tid) {
;     ...
;             PG8_LDB(B0, 0, 0); PG8_LDB(B1, 0, 1); PG8_SCHED; PG8_LDA(At, 0, 0); PG8_STAGE(PG8_SA(1, 1), a1 + hstep, voffA);
;             PG8_WAIT_V(8); PG8_WAIT_L(0); PG8_BAR; PG8_MMA(0, 0, At, B0); PG8_MMA(0, 1, At, B1); PG8_BAR; PG8_SCHED;
;             PG8_LDA(At, 0, 1); PG8_STAGE(PG8_SB(0, 0), b2, voffB); PG8_STAGE(PG8_SB(0, 1), b2 + bhs, voffB); PG8_STAGE(PG8_SA(0, 0), a2, voffA);
;             PG8_WAIT_V(8); PG8_WAIT_L(0); PG8_BAR; PG8_MMA(1, 0, At, B0); PG8_MMA(1, 1, At, B1); PG8_BAR; PG8_SCHED;
.LBB0_454:
	s_add_i32 s13, 0, 0x10000
	v_add_u32_e32 v0, s13, v153
	s_add_i32 s36, 0, 0x14000
	ds_read_b128 v[132:135], v0
	ds_read_b128 v[136:139], v0 offset:1024
	ds_read_b128 v[156:159], v0 offset:2048
	ds_read_b128 v[160:163], v0 offset:3072
	v_add_u32_e32 v0, s36, v153
	ds_read_b128 v[164:167], v0
	ds_read_b128 v[178:181], v0 offset:1024
	ds_read_b128 v[182:185], v0 offset:2048
	ds_read_b128 v[186:189], v0 offset:3072
	s_add_u32 s34, s34, 0x40000
	s_addc_u32 s35, s35, 0
	v_lshl_add_u64 v[2:3], s[34:35], 0, v[140:141]
	s_add_i32 m0, s43, 0xc000
	ds_read_b128 v[190:193], v155
	global_load_lds_dwordx4 v[2:3], off
	ds_read_b128 v[194:197], v155 offset:1024
	ds_read_b128 v[198:201], v155 offset:2048
	v_lshl_add_u64 v[2:3], s[34:35], 0, v[144:145]
	s_add_i32 m0, s43, 0xe000
	s_nop 0
	global_load_lds_dwordx4 v[2:3], off
	ds_read_b128 v[212:215], v155 offset:3072
	ds_read_b128 v[216:219], v155 offset:4096
	ds_read_b128 v[220:223], v155 offset:5120
	ds_read_b128 v[224:227], v155 offset:6144
	ds_read_b128 v[228:231], v155 offset:7168
	s_waitcnt vmcnt(8)
	s_waitcnt lgkmcnt(0)
	s_barrier
	s_waitcnt lgkmcnt(0)
	v_mfma_f32_16x16x32_bf16 v[128:131], v[132:135], v[190:193], v[128:131]
	v_mfma_f32_16x16x32_bf16 v[124:127], v[156:159], v[190:193], v[124:127]
	v_mfma_f32_16x16x32_bf16 v[112:115], v[132:135], v[198:201], v[112:115]
	v_mfma_f32_16x16x32_bf16 v[108:111], v[156:159], v[198:201], v[108:111]
	v_mfma_f32_16x16x32_bf16 v[96:99], v[132:135], v[216:219], v[96:99]
	v_mfma_f32_16x16x32_bf16 v[92:95], v[156:159], v[216:219], v[92:95]
	v_mfma_f32_16x16x32_bf16 v[80:83], v[132:135], v[224:227], v[80:83]
	v_mfma_f32_16x16x32_bf16 v[76:79], v[156:159], v[224:227], v[76:79]
	v_mfma_f32_16x16x32_bf16 v[128:131], v[136:139], v[194:197], v[128:131]
	v_mfma_f32_16x16x32_bf16 v[124:127], v[160:163], v[194:197], v[124:127]
	v_mfma_f32_16x16x32_bf16 v[112:115], v[136:139], v[212:215], v[112:115]
	v_mfma_f32_16x16x32_bf16 v[108:111], v[160:163], v[212:215], v[108:111]
	v_mfma_f32_16x16x32_bf16 v[96:99], v[136:139], v[220:223], v[96:99]
	v_mfma_f32_16x16x32_bf16 v[92:95], v[160:163], v[220:223], v[92:95]
	v_mfma_f32_16x16x32_bf16 v[80:83], v[136:139], v[228:231], v[80:83]
	v_mfma_f32_16x16x32_bf16 v[76:79], v[160:163], v[228:231], v[76:79]
	v_mfma_f32_16x16x32_bf16 v[120:123], v[164:167], v[190:193], v[120:123]
	v_mfma_f32_16x16x32_bf16 v[116:119], v[182:185], v[190:193], v[116:119]
	v_mfma_f32_16x16x32_bf16 v[104:107], v[164:167], v[198:201], v[104:107]
	v_mfma_f32_16x16x32_bf16 v[100:103], v[182:185], v[198:201], v[100:103]
	v_mfma_f32_16x16x32_bf16 v[88:91], v[164:167], v[216:219], v[88:91]
	v_mfma_f32_16x16x32_bf16 v[84:87], v[182:185], v[216:219], v[84:87]
	v_mfma_f32_16x16x32_bf16 v[72:75], v[164:167], v[224:227], v[72:75]
	v_mfma_f32_16x16x32_bf16 v[68:71], v[182:185], v[224:227], v[68:71]
	v_mfma_f32_16x16x32_bf16 v[120:123], v[178:181], v[194:197], v[120:123]
	v_mfma_f32_16x16x32_bf16 v[116:119], v[186:189], v[194:197], v[116:119]
	v_mfma_f32_16x16x32_bf16 v[104:107], v[178:181], v[212:215], v[104:107]
	v_mfma_f32_16x16x32_bf16 v[100:103], v[186:189], v[212:215], v[100:103]
	v_mfma_f32_16x16x32_bf16 v[88:91], v[178:181], v[220:223], v[88:91]
	v_mfma_f32_16x16x32_bf16 v[84:87], v[186:189], v[220:223], v[84:87]
	v_mfma_f32_16x16x32_bf16 v[72:75], v[178:181], v[228:231], v[72:75]
	v_mfma_f32_16x16x32_bf16 v[68:71], v[186:189], v[228:231], v[68:71]
	s_barrier
	s_add_i32 s13, s13, s42
	v_lshl_add_u64 v[168:169], s[28:29], 0, v[142:143]
	s_mov_b32 m0, s13
	ds_read_b128 v[190:193], v155 offset:16384
	global_load_lds_dwordx4 v[168:169], off
	ds_read_b128 v[194:197], v155 offset:17408
	ds_read_b128 v[198:201], v155 offset:18432
	s_add_i32 m0, s13, 0x2000
	s_add_u32 s34, s28, 0x4000
	v_lshl_add_u64 v[172:173], s[28:29], 0, v[146:147]
	s_addc_u32 s35, s29, 0
	s_add_i32 s13, s36, s42
	global_load_lds_dwordx4 v[172:173], off
	ds_read_b128 v[212:215], v155 offset:19456
	ds_read_b128 v[216:219], v155 offset:20480
	v_lshl_add_u64 v[2:3], s[34:35], 0, v[142:143]
	s_mov_b32 m0, s13
	v_lshl_add_u64 v[174:175], s[30:31], 0, v[140:141]
	global_load_lds_dwordx4 v[2:3], off
	ds_read_b128 v[220:223], v155 offset:21504
	ds_read_b128 v[224:227], v155 offset:22528
	v_lshl_add_u64 v[2:3], s[34:35], 0, v[146:147]
	s_add_i32 m0, s13, 0x2000
	v_lshl_add_u64 v[176:177], s[30:31], 0, v[144:145]
	global_load_lds_dwordx4 v[2:3], off
	ds_read_b128 v[228:231], v155 offset:23552
	s_mov_b32 m0, s43
	s_nop 0
	global_load_lds_dwordx4 v[174:175], off
	s_mov_b32 m0, s44
	s_nop 0
	global_load_lds_dwordx4 v[176:177], off
	s_waitcnt vmcnt(8)
	s_waitcnt lgkmcnt(0)
	s_barrier
; #define PG8_STAGE(bufoff, gbase, voff) do { _Pragma("unroll") for (int _i = 0; _i < 2; ++_i) \
;         __builtin_amdgcn_global_load_lds((const unsigned*)((const char*)(gbase) + (voff)[_i]), (LAS unsigned*)(lds + (bufoff) + ldsw + _i * 8192), 16, 0, 0); } while (0)
; #define PG8_LDA(dst, b, h) do { _Pragma("unroll") for (int m = 0; m < 4; ++m) _Pragma("unroll") for (int k = 0; k < 2; ++k) dst[m][k] = *(const LAS bf16x8*)(lds + PG8_SA(b, h) + aoff + m * 2048 + k * 1024); } while (0)
; #define PG8_LDB(dst, b, h) do { _Pragma("unroll") for (int n = 0; n < 2; ++n) _Pragma("unroll") for (int k = 0; k < 2; ++k) dst[n][k] = *(const LAS bf16x8*)(lds + PG8_SB(b, h) + boff + n * 2048 + k * 1024); } while (0)
; #define PG8_MMA(ai, bj, At, Bt) do { __builtin_amdgcn_s_setprio(1); _Pragma("unroll") for (int m = 0; m < 4; ++m) _Pragma("unroll") for (int n = 0; n < 2; ++n) _Pragma("unroll") for (int k = 0; k < 2; ++k) \
;         acc[ai][bj][m][n] = __builtin_amdgcn_mfma_f32_16x16x32_bf16(Bt[n][k], At[m][k], acc[ai][bj][m][n], 0, 0, 0); __builtin_amdgcn_s_setprio(0); } while (0)
; #define PG8_WAIT_V(n) asm volatile("s_waitcnt vmcnt(" #n ")" ::: "memory")
; #define PG8_WAIT_L(n) asm volatile("s_waitcnt lgkmcnt(" #n ")" ::: "memory")
; #define PG8_BAR __builtin_amdgcn_s_barrier()
; #define PG8_SCHED __builtin_amdgcn_sched_barrier(0)
; template <class Epi>
; __device__ __forceinline__ void gemm_phase(LAS unsigned char* lds, const Gemm g, const StaticOrder& S, const Epi& E, const int tid) {
;     ...
;             PG8_WAIT_V(8); PG8_WAIT_L(0); PG8_BAR; PG8_MMA(1, 0, At, B0); PG8_MMA(1, 1, At, B1); PG8_BAR; PG8_SCHED;
;             PG8_LDB(B0, 1, 0); PG8_LDB(B1, 1, 1); PG8_SCHED; PG8_LDA(At, 1, 0); PG8_STAGE(PG8_SA(0, 1), a2 + hstep, voffA);
;             PG8_WAIT_V(8); PG8_WAIT_L(0); PG8_BAR; PG8_MMA(0, 0, At, B0); PG8_MMA(0, 1, At, B1); PG8_BAR; PG8_SCHED;
	s_waitcnt lgkmcnt(0)
	v_mfma_f32_16x16x32_bf16 v[64:67], v[132:135], v[190:193], v[64:67]
	v_mfma_f32_16x16x32_bf16 v[60:63], v[156:159], v[190:193], v[60:63]
	v_mfma_f32_16x16x32_bf16 v[48:51], v[132:135], v[198:201], v[48:51]
	v_mfma_f32_16x16x32_bf16 v[44:47], v[156:159], v[198:201], v[44:47]
	v_mfma_f32_16x16x32_bf16 v[32:35], v[132:135], v[216:219], v[32:35]
	v_mfma_f32_16x16x32_bf16 v[28:31], v[156:159], v[216:219], v[28:31]
	v_mfma_f32_16x16x32_bf16 v[16:19], v[132:135], v[224:227], v[16:19]
	v_mfma_f32_16x16x32_bf16 v[12:15], v[156:159], v[224:227], v[12:15]
	v_mfma_f32_16x16x32_bf16 v[64:67], v[136:139], v[194:197], v[64:67]
	v_mfma_f32_16x16x32_bf16 v[60:63], v[160:163], v[194:197], v[60:63]
	v_mfma_f32_16x16x32_bf16 v[48:51], v[136:139], v[212:215], v[48:51]
	v_mfma_f32_16x16x32_bf16 v[44:47], v[160:163], v[212:215], v[44:47]
	v_mfma_f32_16x16x32_bf16 v[32:35], v[136:139], v[220:223], v[32:35]
	v_mfma_f32_16x16x32_bf16 v[28:31], v[160:163], v[220:223], v[28:31]
	v_mfma_f32_16x16x32_bf16 v[16:19], v[136:139], v[228:231], v[16:19]
	v_mfma_f32_16x16x32_bf16 v[12:15], v[160:163], v[228:231], v[12:15]
	v_mfma_f32_16x16x32_bf16 v[56:59], v[164:167], v[190:193], v[56:59]
	v_mfma_f32_16x16x32_bf16 v[52:55], v[182:185], v[190:193], v[52:55]
	v_mfma_f32_16x16x32_bf16 v[40:43], v[164:167], v[198:201], v[40:43]
	v_mfma_f32_16x16x32_bf16 v[36:39], v[182:185], v[198:201], v[36:39]
	v_mfma_f32_16x16x32_bf16 v[24:27], v[164:167], v[216:219], v[24:27]
	v_mfma_f32_16x16x32_bf16 v[20:23], v[182:185], v[216:219], v[20:23]
	v_mfma_f32_16x16x32_bf16 v[8:11], v[164:167], v[224:227], v[8:11]
	v_mfma_f32_16x16x32_bf16 v[2:5], v[182:185], v[224:227], v[4:7]
	v_mfma_f32_16x16x32_bf16 v[56:59], v[178:181], v[194:197], v[56:59]
	v_mfma_f32_16x16x32_bf16 v[52:55], v[186:189], v[194:197], v[52:55]
	v_mfma_f32_16x16x32_bf16 v[40:43], v[178:181], v[212:215], v[40:43]
	v_mfma_f32_16x16x32_bf16 v[36:39], v[186:189], v[212:215], v[36:39]
	v_mfma_f32_16x16x32_bf16 v[24:27], v[178:181], v[220:223], v[24:27]
	v_mfma_f32_16x16x32_bf16 v[20:23], v[186:189], v[220:223], v[20:23]
	v_mfma_f32_16x16x32_bf16 v[8:11], v[178:181], v[228:231], v[8:11]
	v_mfma_f32_16x16x32_bf16 v[2:5], v[186:189], v[228:231], v[2:5]
	s_barrier
	s_add_i32 s13, 0, 0x18000
	v_add_u32_e32 v0, s13, v153
	s_add_i32 s34, 0, 0x1c000
	ds_read_b128 v[132:135], v0
	ds_read_b128 v[136:139], v0 offset:1024
	ds_read_b128 v[156:159], v0 offset:2048
	ds_read_b128 v[160:163], v0 offset:3072
	v_add_u32_e32 v0, s34, v153
	ds_read_b128 v[164:167], v0
	ds_read_b128 v[178:181], v0 offset:1024
	ds_read_b128 v[182:185], v0 offset:2048
	ds_read_b128 v[186:189], v0 offset:3072
	s_add_u32 s30, s30, 0x40000
	s_addc_u32 s31, s31, 0
	s_mov_b32 m0, s45
	v_lshl_add_u64 v[6:7], s[30:31], 0, v[140:141]
	ds_read_b128 v[190:193], v155 offset:32768
	global_load_lds_dwordx4 v[6:7], off
	ds_read_b128 v[194:197], v155 offset:33792
	ds_read_b128 v[198:201], v155 offset:34816
	v_lshl_add_u64 v[6:7], s[30:31], 0, v[144:145]
	s_mov_b32 m0, s46
	s_nop 0
	global_load_lds_dwordx4 v[6:7], off
	ds_read_b128 v[212:215], v155 offset:35840
	ds_read_b128 v[216:219], v155 offset:36864
	ds_read_b128 v[220:223], v155 offset:37888
	ds_read_b128 v[224:227], v155 offset:38912
	ds_read_b128 v[228:231], v155 offset:39936
	s_waitcnt vmcnt(8)
	s_waitcnt lgkmcnt(0)
	s_barrier
	s_waitcnt lgkmcnt(0)
	v_mfma_f32_16x16x32_bf16 v[128:131], v[132:135], v[190:193], v[128:131]
	v_mfma_f32_16x16x32_bf16 v[124:127], v[156:159], v[190:193], v[124:127]
	v_mfma_f32_16x16x32_bf16 v[112:115], v[132:135], v[198:201], v[112:115]
	v_mfma_f32_16x16x32_bf16 v[108:111], v[156:159], v[198:201], v[108:111]
	v_mfma_f32_16x16x32_bf16 v[96:99], v[132:135], v[216:219], v[96:99]
	v_mfma_f32_16x16x32_bf16 v[92:95], v[156:159], v[216:219], v[92:95]
	v_mfma_f32_16x16x32_bf16 v[80:83], v[132:135], v[224:227], v[80:83]
	v_mfma_f32_16x16x32_bf16 v[76:79], v[156:159], v[224:227], v[76:79]
	v_mfma_f32_16x16x32_bf16 v[128:131], v[136:139], v[194:197], v[128:131]
	v_mfma_f32_16x16x32_bf16 v[124:127], v[160:163], v[194:197], v[124:127]
	v_mfma_f32_16x16x32_bf16 v[112:115], v[136:139], v[212:215], v[112:115]
	v_mfma_f32_16x16x32_bf16 v[108:111], v[160:163], v[212:215], v[108:111]
	v_mfma_f32_16x16x32_bf16 v[96:99], v[136:139], v[220:223], v[96:99]
	v_mfma_f32_16x16x32_bf16 v[92:95], v[160:163], v[220:223], v[92:95]
	v_mfma_f32_16x16x32_bf16 v[80:83], v[136:139], v[228:231], v[80:83]
	v_mfma_f32_16x16x32_bf16 v[76:79], v[160:163], v[228:231], v[76:79]
	v_mfma_f32_16x16x32_bf16 v[120:123], v[164:167], v[190:193], v[120:123]
	v_mfma_f32_16x16x32_bf16 v[116:119], v[182:185], v[190:193], v[116:119]
	v_mfma_f32_16x16x32_bf16 v[104:107], v[164:167], v[198:201], v[104:107]
	v_mfma_f32_16x16x32_bf16 v[100:103], v[182:185], v[198:201], v[100:103]
	v_mfma_f32_16x16x32_bf16 v[88:91], v[164:167], v[216:219], v[88:91]
	v_mfma_f32_16x16x32_bf16 v[84:87], v[182:185], v[216:219], v[84:87]
	v_mfma_f32_16x16x32_bf16 v[72:75], v[164:167], v[224:227], v[72:75]
	v_mfma_f32_16x16x32_bf16 v[68:71], v[182:185], v[224:227], v[68:71]
	v_mfma_f32_16x16x32_bf16 v[120:123], v[178:181], v[194:197], v[120:123]
	v_mfma_f32_16x16x32_bf16 v[116:119], v[186:189], v[194:197], v[116:119]
	v_mfma_f32_16x16x32_bf16 v[104:107], v[178:181], v[212:215], v[104:107]
	v_mfma_f32_16x16x32_bf16 v[100:103], v[186:189], v[212:215], v[100:103]
	v_mfma_f32_16x16x32_bf16 v[88:91], v[178:181], v[220:223], v[88:91]
	v_mfma_f32_16x16x32_bf16 v[84:87], v[186:189], v[220:223], v[84:87]
	v_mfma_f32_16x16x32_bf16 v[72:75], v[178:181], v[228:231], v[72:75]
	v_mfma_f32_16x16x32_bf16 v[68:71], v[186:189], v[228:231], v[68:71]
	s_barrier
; #define PG8_STAGE(bufoff, gbase, voff) do { _Pragma("unroll") for (int _i = 0; _i < 2; ++_i) \
;         __builtin_amdgcn_global_load_lds((const unsigned*)((const char*)(gbase) + (voff)[_i]), (LAS unsigned*)(lds + (bufoff) + ldsw + _i * 8192), 16, 0, 0); } while (0)
; #define PG8_LDA(dst, b, h) do { _Pragma("unroll") for (int m = 0; m < 4; ++m) _Pragma("unroll") for (int k = 0; k < 2; ++k) dst[m][k] = *(const LAS bf16x8*)(lds + PG8_SA(b, h) + aoff + m * 2048 + k * 1024); } while (0)
; #define PG8_MMA(ai, bj, At, Bt) do { __builtin_amdgcn_s_setprio(1); _Pragma("unroll") for (int m = 0; m < 4; ++m) _Pragma("unroll") for (int n = 0; n < 2; ++n) _Pragma("unroll") for (int k = 0; k < 2; ++k) \
;         acc[ai][bj][m][n] = __builtin_amdgcn_mfma_f32_16x16x32_bf16(Bt[n][k], At[m][k], acc[ai][bj][m][n], 0, 0, 0); __builtin_amdgcn_s_setprio(0); } while (0)
; #define PG8_WAIT_V(n) asm volatile("s_waitcnt vmcnt(" #n ")" ::: "memory")
; #define PG8_WAIT_L(n) asm volatile("s_waitcnt lgkmcnt(" #n ")" ::: "memory")
; #define PG8_BAR __builtin_amdgcn_s_barrier()
; #define PG8_SCHED __builtin_amdgcn_sched_barrier(0)
; template <class Epi>
; __device__ __forceinline__ void gemm_phase(LAS unsigned char* lds, const Gemm g, const StaticOrder& S, const Epi& E, const int tid) {
;     ...
;             PG8_LDA(At, 1, 1); PG8_STAGE(PG8_SB(1, 0), b3, voffB); PG8_STAGE(PG8_SB(1, 1), b3 + bhs, voffB); PG8_STAGE(PG8_SA(1, 0), a3, voffA);
;             PG8_WAIT_V(8); PG8_WAIT_L(0); PG8_BAR; PG8_MMA(1, 0, At, B0); PG8_MMA(1, 1, At, B1); PG8_BAR; PG8_SCHED;
	s_add_i32 s13, s13, s42
	v_lshl_add_u64 v[6:7], v[168:169], 0, s[70:71]
	s_mov_b32 m0, s13
	ds_read_b128 v[190:193], v155 offset:49152
	global_load_lds_dwordx4 v[6:7], off
	ds_read_b128 v[194:197], v155 offset:50176
	ds_read_b128 v[198:201], v155 offset:51200
	s_add_i32 m0, s13, 0x2000
	s_add_u32 s28, s28, 0x4080
	v_lshl_add_u64 v[6:7], v[172:173], 0, s[70:71]
	s_addc_u32 s29, s29, 0
	s_add_i32 s13, s34, s42
	global_load_lds_dwordx4 v[6:7], off
	ds_read_b128 v[212:215], v155 offset:52224
	ds_read_b128 v[216:219], v155 offset:53248
	v_lshl_add_u64 v[6:7], s[28:29], 0, v[142:143]
	s_mov_b32 m0, s13
	s_nop 0
	global_load_lds_dwordx4 v[6:7], off
	ds_read_b128 v[220:223], v155 offset:54272
	ds_read_b128 v[224:227], v155 offset:55296
	v_lshl_add_u64 v[6:7], s[28:29], 0, v[146:147]
	s_add_i32 m0, s13, 0x2000
	s_nop 0
	global_load_lds_dwordx4 v[6:7], off
	ds_read_b128 v[228:231], v155 offset:56320
	v_lshl_add_u64 v[6:7], v[174:175], 0, s[70:71]
	s_mov_b32 m0, s47
	s_nop 0
	global_load_lds_dwordx4 v[6:7], off
	v_lshl_add_u64 v[6:7], v[176:177], 0, s[70:71]
	s_mov_b32 m0, s48
	s_nop 0
	global_load_lds_dwordx4 v[6:7], off
	s_waitcnt vmcnt(8)
	s_waitcnt lgkmcnt(0)
	s_barrier
	s_waitcnt lgkmcnt(0)
	v_mfma_f32_16x16x32_bf16 v[64:67], v[132:135], v[190:193], v[64:67]
	v_mfma_f32_16x16x32_bf16 v[60:63], v[156:159], v[190:193], v[60:63]
	v_mfma_f32_16x16x32_bf16 v[48:51], v[132:135], v[198:201], v[48:51]
	v_mfma_f32_16x16x32_bf16 v[44:47], v[156:159], v[198:201], v[44:47]
	v_mfma_f32_16x16x32_bf16 v[32:35], v[132:135], v[216:219], v[32:35]
	v_mfma_f32_16x16x32_bf16 v[28:31], v[156:159], v[216:219], v[28:31]
	v_mfma_f32_16x16x32_bf16 v[16:19], v[132:135], v[224:227], v[16:19]
	v_mfma_f32_16x16x32_bf16 v[12:15], v[156:159], v[224:227], v[12:15]
	v_mfma_f32_16x16x32_bf16 v[64:67], v[136:139], v[194:197], v[64:67]
	v_mfma_f32_16x16x32_bf16 v[60:63], v[160:163], v[194:197], v[60:63]
	v_mfma_f32_16x16x32_bf16 v[48:51], v[136:139], v[212:215], v[48:51]
	v_mfma_f32_16x16x32_bf16 v[44:47], v[160:163], v[212:215], v[44:47]
	v_mfma_f32_16x16x32_bf16 v[32:35], v[136:139], v[220:223], v[32:35]
	v_mfma_f32_16x16x32_bf16 v[28:31], v[160:163], v[220:223], v[28:31]
	v_mfma_f32_16x16x32_bf16 v[16:19], v[136:139], v[228:231], v[16:19]
	v_mfma_f32_16x16x32_bf16 v[12:15], v[160:163], v[228:231], v[12:15]
	v_mfma_f32_16x16x32_bf16 v[56:59], v[164:167], v[190:193], v[56:59]
	v_mfma_f32_16x16x32_bf16 v[52:55], v[182:185], v[190:193], v[52:55]
	v_mfma_f32_16x16x32_bf16 v[40:43], v[164:167], v[198:201], v[40:43]
	v_mfma_f32_16x16x32_bf16 v[36:39], v[182:185], v[198:201], v[36:39]
	v_mfma_f32_16x16x32_bf16 v[24:27], v[164:167], v[216:219], v[24:27]
	v_mfma_f32_16x16x32_bf16 v[20:23], v[182:185], v[216:219], v[20:23]
	v_mfma_f32_16x16x32_bf16 v[6:9], v[164:167], v[224:227], v[8:11]
	v_mfma_f32_16x16x32_bf16 v[2:5], v[182:185], v[224:227], v[2:5]
	v_mfma_f32_16x16x32_bf16 v[56:59], v[178:181], v[194:197], v[56:59]
	v_mfma_f32_16x16x32_bf16 v[52:55], v[186:189], v[194:197], v[52:55]
	v_mfma_f32_16x16x32_bf16 v[40:43], v[178:181], v[212:215], v[40:43]
	v_mfma_f32_16x16x32_bf16 v[36:39], v[186:189], v[212:215], v[36:39]
	v_mfma_f32_16x16x32_bf16 v[24:27], v[178:181], v[220:223], v[24:27]
	v_mfma_f32_16x16x32_bf16 v[20:23], v[186:189], v[220:223], v[20:23]
	v_mfma_f32_16x16x32_bf16 v[8:11], v[178:181], v[228:231], v[6:9]
	v_mfma_f32_16x16x32_bf16 v[4:7], v[186:189], v[228:231], v[2:5]
	s_barrier
	s_add_i32 s2, s2, 2
	s_add_u32 s24, s24, 0x100
	s_addc_u32 s25, s25, 0
	s_add_u32 s26, s26, 0x100
	s_addc_u32 s27, s27, 0
	s_cmp_gt_u32 s11, 29
	s_cbranch_scc1 .LBB0_467

; #define PG8_STAGE(bufoff, gbase, voff) do { _Pragma("unroll") for (int _i = 0; _i < 2; ++_i) \
;         __builtin_amdgcn_global_load_lds((const unsigned*)((const char*)(gbase) + (voff)[_i]), (LAS unsigned*)(lds + (bufoff) + ldsw + _i * 8192), 16, 0, 0); } while (0)
; #define PG8_LDA(dst, b, h) do { _Pragma("unroll") for (int m = 0; m < 4; ++m) _Pragma("unroll") for (int k = 0; k < 2; ++k) dst[m][k] = *(const LAS bf16x8*)(lds + PG8_SA(b, h) + aoff + m * 2048 + k * 1024); } while (0)
; #define PG8_LDB(dst, b, h) do { _Pragma("unroll") for (int n = 0; n < 2; ++n) _Pragma("unroll") for (int k = 0; k < 2; ++k) dst[n][k] = *(const LAS bf16x8*)(lds + PG8_SB(b, h) + boff + n * 2048 + k * 1024); } while (0)
; #define PG8_MMA(ai, bj, At, Bt) do { __builtin_amdgcn_s_setprio(1); _Pragma("unroll") for (int m = 0; m < 4; ++m) _Pragma("unroll") for (int n = 0; n < 2; ++n) _Pragma("unroll") for (int k = 0; k < 2; ++k) \
;         acc[ai][bj][m][n] = __builtin_amdgcn_mfma_f32_16x16x32_bf16(Bt[n][k], At[m][k], acc[ai][bj][m][n], 0, 0, 0); __builtin_amdgcn_s_setprio(0); } while (0)
; #define PG8_WAIT_V(n) asm volatile("s_waitcnt vmcnt(" #n ")" ::: "memory")
; #define PG8_WAIT_L(n) asm volatile("s_waitcnt lgkmcnt(" #n ")" ::: "memory")
; #define PG8_BAR __builtin_amdgcn_s_barrier()
; #define PG8_SCHED __builtin_amdgcn_sched_barrier(0)
; template <class Epi>
; __device__ __forceinline__ void gemm_phase(LAS unsigned char* lds, const Gemm g, const StaticOrder& S, const Epi& E, const int tid) {
;     ...
;             PG8_LDB(B0, 0, 0); PG8_LDB(B1, 0, 1); PG8_SCHED; PG8_LDA(At, 0, 0); PG8_STAGE(PG8_SA(1, 1), a1 + hstep, voffA);
;             PG8_WAIT_V(8); PG8_WAIT_L(0); PG8_BAR; PG8_MMA(0, 0, At, B0); PG8_MMA(0, 1, At, B1); PG8_BAR; PG8_SCHED;
;             PG8_LDA(At, 0, 1); PG8_STAGE(PG8_SB(0, 0), b2, voffB); PG8_STAGE(PG8_SB(0, 1), b2 + bhs, voffB); PG8_STAGE(PG8_SA(0, 0), a2, voffA);
;             PG8_WAIT_V(8); PG8_WAIT_L(0); PG8_BAR; PG8_MMA(1, 0, At, B0); PG8_MMA(1, 1, At, B1); PG8_BAR; PG8_SCHED;
.LBB0_546:
	s_add_u32 s28, s26, 0xfff80080
	s_addc_u32 s29, s27, -1
	s_add_i32 s44, 0, 0x10000
	s_cmp_eq_u32 s39, 28
	s_cselect_b32 s35, s19, s29
	s_cselect_b32 s34, s31, s28
	v_add_u32_e32 v0, s44, v149
	s_cselect_b32 s29, s17, s38
	s_cselect_b32 s28, s33, s37
	s_add_i32 s46, 0, 0x14000
	ds_read_b128 v[150:153], v0
	ds_read_b128 v[154:157], v0 offset:1024
	ds_read_b128 v[158:161], v0 offset:2048
	ds_read_b128 v[186:189], v0 offset:3072
	v_add_u32_e32 v0, s46, v149
	ds_read_b128 v[190:193], v0
	ds_read_b128 v[194:197], v0 offset:1024
	ds_read_b128 v[198:201], v0 offset:2048
	ds_read_b128 v[212:215], v0 offset:3072
	v_lshl_add_u64 v[162:163], s[26:27], 0, v[146:147]
	s_add_i32 m0, s57, 0xc000
	ds_read_b128 v[216:219], v184
	global_load_lds_dwordx4 v[162:163], off
	ds_read_b128 v[220:223], v184 offset:1024
	ds_read_b128 v[224:227], v184 offset:2048
	v_lshl_add_u64 v[162:163], s[26:27], 0, v[144:145]
	s_add_i32 m0, s57, 0xe000
	s_nop 0
	global_load_lds_dwordx4 v[162:163], off
	ds_read_b128 v[228:231], v184 offset:3072
	ds_read_b128 v[232:235], v184 offset:4096
	ds_read_b128 v[236:239], v184 offset:5120
	ds_read_b128 v[240:243], v184 offset:6144
	ds_read_b128 v[244:247], v184 offset:7168
	s_waitcnt vmcnt(8)
	s_waitcnt lgkmcnt(0)
	s_barrier
	s_waitcnt lgkmcnt(0)
	v_mfma_f32_16x16x32_bf16 v[126:129], v[150:153], v[216:219], v[126:129]
	v_mfma_f32_16x16x32_bf16 v[122:125], v[158:161], v[216:219], v[122:125]
	v_mfma_f32_16x16x32_bf16 v[110:113], v[150:153], v[224:227], v[110:113]
	v_mfma_f32_16x16x32_bf16 v[106:109], v[158:161], v[224:227], v[106:109]
	v_mfma_f32_16x16x32_bf16 v[94:97], v[150:153], v[232:235], v[94:97]
	v_mfma_f32_16x16x32_bf16 v[90:93], v[158:161], v[232:235], v[90:93]
	v_mfma_f32_16x16x32_bf16 v[78:81], v[150:153], v[240:243], v[78:81]
	v_mfma_f32_16x16x32_bf16 v[74:77], v[158:161], v[240:243], v[74:77]
	v_mfma_f32_16x16x32_bf16 v[126:129], v[154:157], v[220:223], v[126:129]
	v_mfma_f32_16x16x32_bf16 v[122:125], v[186:189], v[220:223], v[122:125]
	v_mfma_f32_16x16x32_bf16 v[110:113], v[154:157], v[228:231], v[110:113]
	v_mfma_f32_16x16x32_bf16 v[106:109], v[186:189], v[228:231], v[106:109]
	v_mfma_f32_16x16x32_bf16 v[94:97], v[154:157], v[236:239], v[94:97]
	v_mfma_f32_16x16x32_bf16 v[90:93], v[186:189], v[236:239], v[90:93]
	v_mfma_f32_16x16x32_bf16 v[78:81], v[154:157], v[244:247], v[78:81]
	v_mfma_f32_16x16x32_bf16 v[74:77], v[186:189], v[244:247], v[74:77]
	v_mfma_f32_16x16x32_bf16 v[118:121], v[190:193], v[216:219], v[118:121]
	v_mfma_f32_16x16x32_bf16 v[114:117], v[198:201], v[216:219], v[114:117]
	v_mfma_f32_16x16x32_bf16 v[102:105], v[190:193], v[224:227], v[102:105]
	v_mfma_f32_16x16x32_bf16 v[98:101], v[198:201], v[224:227], v[98:101]
	v_mfma_f32_16x16x32_bf16 v[86:89], v[190:193], v[232:235], v[86:89]
	v_mfma_f32_16x16x32_bf16 v[82:85], v[198:201], v[232:235], v[82:85]
	v_mfma_f32_16x16x32_bf16 v[70:73], v[190:193], v[240:243], v[70:73]
	v_mfma_f32_16x16x32_bf16 v[66:69], v[198:201], v[240:243], v[66:69]
	v_mfma_f32_16x16x32_bf16 v[118:121], v[194:197], v[220:223], v[118:121]
	v_mfma_f32_16x16x32_bf16 v[114:117], v[212:215], v[220:223], v[114:117]
	v_mfma_f32_16x16x32_bf16 v[102:105], v[194:197], v[228:231], v[102:105]
	v_mfma_f32_16x16x32_bf16 v[98:101], v[212:215], v[228:231], v[98:101]
	v_mfma_f32_16x16x32_bf16 v[86:89], v[194:197], v[236:239], v[86:89]
	v_mfma_f32_16x16x32_bf16 v[82:85], v[212:215], v[236:239], v[82:85]
	v_mfma_f32_16x16x32_bf16 v[70:73], v[194:197], v[244:247], v[70:73]
	v_mfma_f32_16x16x32_bf16 v[66:69], v[212:215], v[244:247], v[66:69]
	s_barrier
	s_add_i32 s44, s44, s56
	v_lshl_add_u64 v[162:163], s[28:29], 0, v[132:133]
	s_mov_b32 m0, s44
	ds_read_b128 v[216:219], v184 offset:16384
	global_load_lds_dwordx4 v[162:163], off
	ds_read_b128 v[220:223], v184 offset:17408
	ds_read_b128 v[224:227], v184 offset:18432
	s_add_i32 m0, s44, 0x2000
	s_add_u32 s44, s28, 0x8000
	v_lshl_add_u64 v[248:249], s[28:29], 0, v[136:137]
	s_addc_u32 s45, s29, 0
	s_add_i32 s46, s46, s56
	global_load_lds_dwordx4 v[248:249], off
	ds_read_b128 v[228:231], v184 offset:19456
	ds_read_b128 v[232:235], v184 offset:20480
	v_lshl_add_u64 v[172:173], s[44:45], 0, v[132:133]
	s_mov_b32 m0, s46
	v_lshl_add_u64 v[174:175], s[34:35], 0, v[134:135]
	global_load_lds_dwordx4 v[172:173], off
	ds_read_b128 v[236:239], v184 offset:21504
	ds_read_b128 v[240:243], v184 offset:22528
	v_lshl_add_u64 v[172:173], s[44:45], 0, v[136:137]
	s_add_i32 m0, s46, 0x2000
	s_nop 0
	global_load_lds_dwordx4 v[172:173], off
	ds_read_b128 v[244:247], v184 offset:23552
	v_lshl_add_u64 v[172:173], s[34:35], 0, v[130:131]
	s_mov_b32 m0, s57
	s_nop 0
	global_load_lds_dwordx4 v[172:173], off
	s_mov_b32 m0, s58
	s_nop 0
	global_load_lds_dwordx4 v[174:175], off
	s_waitcnt vmcnt(8)
	s_waitcnt lgkmcnt(0)
	s_barrier
; #define PG8_STAGE(bufoff, gbase, voff) do { _Pragma("unroll") for (int _i = 0; _i < 2; ++_i) \
;         __builtin_amdgcn_global_load_lds((const unsigned*)((const char*)(gbase) + (voff)[_i]), (LAS unsigned*)(lds + (bufoff) + ldsw + _i * 8192), 16, 0, 0); } while (0)
; #define PG8_LDA(dst, b, h) do { _Pragma("unroll") for (int m = 0; m < 4; ++m) _Pragma("unroll") for (int k = 0; k < 2; ++k) dst[m][k] = *(const LAS bf16x8*)(lds + PG8_SA(b, h) + aoff + m * 2048 + k * 1024); } while (0)
; #define PG8_LDB(dst, b, h) do { _Pragma("unroll") for (int n = 0; n < 2; ++n) _Pragma("unroll") for (int k = 0; k < 2; ++k) dst[n][k] = *(const LAS bf16x8*)(lds + PG8_SB(b, h) + boff + n * 2048 + k * 1024); } while (0)
; #define PG8_MMA(ai, bj, At, Bt) do { __builtin_amdgcn_s_setprio(1); _Pragma("unroll") for (int m = 0; m < 4; ++m) _Pragma("unroll") for (int n = 0; n < 2; ++n) _Pragma("unroll") for (int k = 0; k < 2; ++k) \
;         acc[ai][bj][m][n] = __builtin_amdgcn_mfma_f32_16x16x32_bf16(Bt[n][k], At[m][k], acc[ai][bj][m][n], 0, 0, 0); __builtin_amdgcn_s_setprio(0); } while (0)
; #define PG8_WAIT_V(n) asm volatile("s_waitcnt vmcnt(" #n ")" ::: "memory")
; #define PG8_WAIT_L(n) asm volatile("s_waitcnt lgkmcnt(" #n ")" ::: "memory")
; #define PG8_BAR __builtin_amdgcn_s_barrier()
; #define PG8_SCHED __builtin_amdgcn_sched_barrier(0)
; template <class Epi>
; __device__ __forceinline__ void gemm_phase(LAS unsigned char* lds, const Gemm g, const StaticOrder& S, const Epi& E, const int tid) {
;     ...
;             PG8_WAIT_V(8); PG8_WAIT_L(0); PG8_BAR; PG8_MMA(1, 0, At, B0); PG8_MMA(1, 1, At, B1); PG8_BAR; PG8_SCHED;
;             PG8_LDB(B0, 1, 0); PG8_LDB(B1, 1, 1); PG8_SCHED; PG8_LDA(At, 1, 0); PG8_STAGE(PG8_SA(0, 1), a2 + hstep, voffA);
;             PG8_WAIT_V(8); PG8_WAIT_L(0); PG8_BAR; PG8_MMA(0, 0, At, B0); PG8_MMA(0, 1, At, B1); PG8_BAR; PG8_SCHED;
	s_waitcnt lgkmcnt(0)
	v_mfma_f32_16x16x32_bf16 v[62:65], v[150:153], v[216:219], v[62:65]
	v_mfma_f32_16x16x32_bf16 v[58:61], v[158:161], v[216:219], v[58:61]
	v_mfma_f32_16x16x32_bf16 v[46:49], v[150:153], v[224:227], v[46:49]
	v_mfma_f32_16x16x32_bf16 v[42:45], v[158:161], v[224:227], v[42:45]
	v_mfma_f32_16x16x32_bf16 v[30:33], v[150:153], v[232:235], v[30:33]
	v_mfma_f32_16x16x32_bf16 v[26:29], v[158:161], v[232:235], v[26:29]
	v_mfma_f32_16x16x32_bf16 v[14:17], v[150:153], v[240:243], v[14:17]
	v_mfma_f32_16x16x32_bf16 v[10:13], v[158:161], v[240:243], v[10:13]
	v_mfma_f32_16x16x32_bf16 v[62:65], v[154:157], v[220:223], v[62:65]
	v_mfma_f32_16x16x32_bf16 v[58:61], v[186:189], v[220:223], v[58:61]
	v_mfma_f32_16x16x32_bf16 v[46:49], v[154:157], v[228:231], v[46:49]
	v_mfma_f32_16x16x32_bf16 v[42:45], v[186:189], v[228:231], v[42:45]
	v_mfma_f32_16x16x32_bf16 v[30:33], v[154:157], v[236:239], v[30:33]
	v_mfma_f32_16x16x32_bf16 v[26:29], v[186:189], v[236:239], v[26:29]
	v_mfma_f32_16x16x32_bf16 v[14:17], v[154:157], v[244:247], v[14:17]
	v_mfma_f32_16x16x32_bf16 v[10:13], v[186:189], v[244:247], v[10:13]
	v_mfma_f32_16x16x32_bf16 v[54:57], v[190:193], v[216:219], v[54:57]
	v_mfma_f32_16x16x32_bf16 v[50:53], v[198:201], v[216:219], v[50:53]
	v_mfma_f32_16x16x32_bf16 v[38:41], v[190:193], v[224:227], v[38:41]
	v_mfma_f32_16x16x32_bf16 v[34:37], v[198:201], v[224:227], v[34:37]
	v_mfma_f32_16x16x32_bf16 v[22:25], v[190:193], v[232:235], v[22:25]
	v_mfma_f32_16x16x32_bf16 v[18:21], v[198:201], v[232:235], v[18:21]
	v_mfma_f32_16x16x32_bf16 v[6:9], v[190:193], v[240:243], v[6:9]
	v_mfma_f32_16x16x32_bf16 v[2:5], v[198:201], v[240:243], v[2:5]
	v_mfma_f32_16x16x32_bf16 v[54:57], v[194:197], v[220:223], v[54:57]
	v_mfma_f32_16x16x32_bf16 v[50:53], v[212:215], v[220:223], v[50:53]
	v_mfma_f32_16x16x32_bf16 v[38:41], v[194:197], v[228:231], v[38:41]
	v_mfma_f32_16x16x32_bf16 v[34:37], v[212:215], v[228:231], v[34:37]
	v_mfma_f32_16x16x32_bf16 v[22:25], v[194:197], v[236:239], v[22:25]
	v_mfma_f32_16x16x32_bf16 v[18:21], v[212:215], v[236:239], v[18:21]
	v_mfma_f32_16x16x32_bf16 v[6:9], v[194:197], v[244:247], v[6:9]
	v_mfma_f32_16x16x32_bf16 v[2:5], v[212:215], v[244:247], v[2:5]
	s_barrier
	s_add_i32 s44, 0, 0x18000
	v_add_u32_e32 v0, s44, v149
	s_add_i32 s45, 0, 0x1c000
	ds_read_b128 v[150:153], v0
	ds_read_b128 v[154:157], v0 offset:1024
	ds_read_b128 v[158:161], v0 offset:2048
	ds_read_b128 v[186:189], v0 offset:3072
	v_add_u32_e32 v0, s45, v149
	ds_read_b128 v[190:193], v0
	ds_read_b128 v[194:197], v0 offset:1024
	ds_read_b128 v[198:201], v0 offset:2048
	ds_read_b128 v[212:215], v0 offset:3072
	s_add_u32 s34, s34, 0x80000
	s_addc_u32 s35, s35, 0
	s_mov_b32 m0, s59
	v_lshl_add_u64 v[176:177], s[34:35], 0, v[130:131]
	ds_read_b128 v[216:219], v184 offset:32768
	global_load_lds_dwordx4 v[176:177], off
	ds_read_b128 v[220:223], v184 offset:33792
	ds_read_b128 v[224:227], v184 offset:34816
	v_lshl_add_u64 v[176:177], s[34:35], 0, v[134:135]
	s_mov_b32 m0, s60
	s_nop 0
	global_load_lds_dwordx4 v[176:177], off
	ds_read_b128 v[228:231], v184 offset:35840
	ds_read_b128 v[232:235], v184 offset:36864
	ds_read_b128 v[236:239], v184 offset:37888
	ds_read_b128 v[240:243], v184 offset:38912
	ds_read_b128 v[244:247], v184 offset:39936
	s_waitcnt vmcnt(8)
	s_waitcnt lgkmcnt(0)
	s_barrier
	s_waitcnt lgkmcnt(0)
	v_mfma_f32_16x16x32_bf16 v[126:129], v[150:153], v[216:219], v[126:129]
	v_mfma_f32_16x16x32_bf16 v[122:125], v[158:161], v[216:219], v[122:125]
	v_mfma_f32_16x16x32_bf16 v[110:113], v[150:153], v[224:227], v[110:113]
	v_mfma_f32_16x16x32_bf16 v[106:109], v[158:161], v[224:227], v[106:109]
	v_mfma_f32_16x16x32_bf16 v[94:97], v[150:153], v[232:235], v[94:97]
	v_mfma_f32_16x16x32_bf16 v[90:93], v[158:161], v[232:235], v[90:93]
	v_mfma_f32_16x16x32_bf16 v[78:81], v[150:153], v[240:243], v[78:81]
	v_mfma_f32_16x16x32_bf16 v[74:77], v[158:161], v[240:243], v[74:77]
	v_mfma_f32_16x16x32_bf16 v[126:129], v[154:157], v[220:223], v[126:129]
	v_mfma_f32_16x16x32_bf16 v[122:125], v[186:189], v[220:223], v[122:125]
	v_mfma_f32_16x16x32_bf16 v[110:113], v[154:157], v[228:231], v[110:113]
	v_mfma_f32_16x16x32_bf16 v[106:109], v[186:189], v[228:231], v[106:109]
	v_mfma_f32_16x16x32_bf16 v[94:97], v[154:157], v[236:239], v[94:97]
	v_mfma_f32_16x16x32_bf16 v[90:93], v[186:189], v[236:239], v[90:93]
	v_mfma_f32_16x16x32_bf16 v[78:81], v[154:157], v[244:247], v[78:81]
	v_mfma_f32_16x16x32_bf16 v[74:77], v[186:189], v[244:247], v[74:77]
	v_mfma_f32_16x16x32_bf16 v[118:121], v[190:193], v[216:219], v[118:121]
	v_mfma_f32_16x16x32_bf16 v[114:117], v[198:201], v[216:219], v[114:117]
	v_mfma_f32_16x16x32_bf16 v[102:105], v[190:193], v[224:227], v[102:105]
	v_mfma_f32_16x16x32_bf16 v[98:101], v[198:201], v[224:227], v[98:101]
	v_mfma_f32_16x16x32_bf16 v[86:89], v[190:193], v[232:235], v[86:89]
	v_mfma_f32_16x16x32_bf16 v[82:85], v[198:201], v[232:235], v[82:85]
	v_mfma_f32_16x16x32_bf16 v[70:73], v[190:193], v[240:243], v[70:73]
	v_mfma_f32_16x16x32_bf16 v[66:69], v[198:201], v[240:243], v[66:69]
	v_mfma_f32_16x16x32_bf16 v[118:121], v[194:197], v[220:223], v[118:121]
	v_mfma_f32_16x16x32_bf16 v[114:117], v[212:215], v[220:223], v[114:117]
	v_mfma_f32_16x16x32_bf16 v[102:105], v[194:197], v[228:231], v[102:105]
	v_mfma_f32_16x16x32_bf16 v[98:101], v[212:215], v[228:231], v[98:101]
	v_mfma_f32_16x16x32_bf16 v[86:89], v[194:197], v[236:239], v[86:89]
	v_mfma_f32_16x16x32_bf16 v[82:85], v[212:215], v[236:239], v[82:85]
	v_mfma_f32_16x16x32_bf16 v[70:73], v[194:197], v[244:247], v[70:73]
	v_mfma_f32_16x16x32_bf16 v[66:69], v[212:215], v[244:247], v[66:69]
	s_barrier
; #define PG8_STAGE(bufoff, gbase, voff) do { _Pragma("unroll") for (int _i = 0; _i < 2; ++_i) \
;         __builtin_amdgcn_global_load_lds((const unsigned*)((const char*)(gbase) + (voff)[_i]), (LAS unsigned*)(lds + (bufoff) + ldsw + _i * 8192), 16, 0, 0); } while (0)
; #define PG8_LDA(dst, b, h) do { _Pragma("unroll") for (int m = 0; m < 4; ++m) _Pragma("unroll") for (int k = 0; k < 2; ++k) dst[m][k] = *(const LAS bf16x8*)(lds + PG8_SA(b, h) + aoff + m * 2048 + k * 1024); } while (0)
; #define PG8_MMA(ai, bj, At, Bt) do { __builtin_amdgcn_s_setprio(1); _Pragma("unroll") for (int m = 0; m < 4; ++m) _Pragma("unroll") for (int n = 0; n < 2; ++n) _Pragma("unroll") for (int k = 0; k < 2; ++k) \
;         acc[ai][bj][m][n] = __builtin_amdgcn_mfma_f32_16x16x32_bf16(Bt[n][k], At[m][k], acc[ai][bj][m][n], 0, 0, 0); __builtin_amdgcn_s_setprio(0); } while (0)
; #define PG8_WAIT_V(n) asm volatile("s_waitcnt vmcnt(" #n ")" ::: "memory")
; #define PG8_WAIT_L(n) asm volatile("s_waitcnt lgkmcnt(" #n ")" ::: "memory")
; #define PG8_BAR __builtin_amdgcn_s_barrier()
; #define PG8_SCHED __builtin_amdgcn_sched_barrier(0)
; template <class Epi>
; __device__ __forceinline__ void gemm_phase(LAS unsigned char* lds, const Gemm g, const StaticOrder& S, const Epi& E, const int tid) {
;     ...
;             PG8_LDA(At, 1, 1); PG8_STAGE(PG8_SB(1, 0), b3, voffB); PG8_STAGE(PG8_SB(1, 1), b3 + bhs, voffB); PG8_STAGE(PG8_SA(1, 0), a3, voffA);
;             PG8_WAIT_V(8); PG8_WAIT_L(0); PG8_BAR; PG8_MMA(1, 0, At, B0); PG8_MMA(1, 1, At, B1); PG8_BAR; PG8_SCHED;
;     ...
;         if (ALIGN_EPI) { if (wr == 0) PG8_BAR; }
	s_add_i32 s34, s44, s56
	v_lshl_add_u64 v[162:163], v[162:163], 0, s[70:71]
	s_mov_b32 m0, s34
	ds_read_b128 v[216:219], v184 offset:49152
	global_load_lds_dwordx4 v[162:163], off
	ds_read_b128 v[220:223], v184 offset:50176
	ds_read_b128 v[224:227], v184 offset:51200
	s_add_i32 m0, s34, 0x2000
	s_add_u32 s28, s28, 0x8080
	v_lshl_add_u64 v[162:163], v[248:249], 0, s[70:71]
	s_addc_u32 s29, s29, 0
	s_add_i32 s34, s45, s56
	global_load_lds_dwordx4 v[162:163], off
	ds_read_b128 v[228:231], v184 offset:52224
	ds_read_b128 v[232:235], v184 offset:53248
	v_lshl_add_u64 v[162:163], s[28:29], 0, v[132:133]
	s_mov_b32 m0, s34
	s_nop 0
	global_load_lds_dwordx4 v[162:163], off
	ds_read_b128 v[236:239], v184 offset:54272
	ds_read_b128 v[240:243], v184 offset:55296
	v_lshl_add_u64 v[162:163], s[28:29], 0, v[136:137]
	s_add_i32 m0, s34, 0x2000
	s_nop 0
	global_load_lds_dwordx4 v[162:163], off
	ds_read_b128 v[244:247], v184 offset:56320
	v_lshl_add_u64 v[162:163], v[172:173], 0, s[70:71]
	s_mov_b32 m0, s61
	s_nop 0
	global_load_lds_dwordx4 v[162:163], off
	v_lshl_add_u64 v[162:163], v[174:175], 0, s[70:71]
	s_mov_b32 m0, s62
	s_nop 0
	global_load_lds_dwordx4 v[162:163], off
	s_waitcnt vmcnt(8)
	s_waitcnt lgkmcnt(0)
	s_barrier
	s_waitcnt lgkmcnt(0)
	v_mfma_f32_16x16x32_bf16 v[62:65], v[150:153], v[216:219], v[62:65]
	v_mfma_f32_16x16x32_bf16 v[58:61], v[158:161], v[216:219], v[58:61]
	v_mfma_f32_16x16x32_bf16 v[46:49], v[150:153], v[224:227], v[46:49]
	v_mfma_f32_16x16x32_bf16 v[42:45], v[158:161], v[224:227], v[42:45]
	v_mfma_f32_16x16x32_bf16 v[30:33], v[150:153], v[232:235], v[30:33]
	v_mfma_f32_16x16x32_bf16 v[26:29], v[158:161], v[232:235], v[26:29]
	v_mfma_f32_16x16x32_bf16 v[14:17], v[150:153], v[240:243], v[14:17]
	v_mfma_f32_16x16x32_bf16 v[10:13], v[158:161], v[240:243], v[10:13]
	v_mfma_f32_16x16x32_bf16 v[62:65], v[154:157], v[220:223], v[62:65]
	v_mfma_f32_16x16x32_bf16 v[58:61], v[186:189], v[220:223], v[58:61]
	v_mfma_f32_16x16x32_bf16 v[46:49], v[154:157], v[228:231], v[46:49]
	v_mfma_f32_16x16x32_bf16 v[42:45], v[186:189], v[228:231], v[42:45]
	v_mfma_f32_16x16x32_bf16 v[30:33], v[154:157], v[236:239], v[30:33]
	v_mfma_f32_16x16x32_bf16 v[26:29], v[186:189], v[236:239], v[26:29]
	v_mfma_f32_16x16x32_bf16 v[14:17], v[154:157], v[244:247], v[14:17]
	v_mfma_f32_16x16x32_bf16 v[10:13], v[186:189], v[244:247], v[10:13]
	v_mfma_f32_16x16x32_bf16 v[54:57], v[190:193], v[216:219], v[54:57]
	v_mfma_f32_16x16x32_bf16 v[50:53], v[198:201], v[216:219], v[50:53]
	v_mfma_f32_16x16x32_bf16 v[38:41], v[190:193], v[224:227], v[38:41]
	v_mfma_f32_16x16x32_bf16 v[34:37], v[198:201], v[224:227], v[34:37]
	v_mfma_f32_16x16x32_bf16 v[22:25], v[190:193], v[232:235], v[22:25]
	v_mfma_f32_16x16x32_bf16 v[18:21], v[198:201], v[232:235], v[18:21]
	v_mfma_f32_16x16x32_bf16 v[6:9], v[190:193], v[240:243], v[6:9]
	v_mfma_f32_16x16x32_bf16 v[2:5], v[198:201], v[240:243], v[2:5]
	v_mfma_f32_16x16x32_bf16 v[54:57], v[194:197], v[220:223], v[54:57]
	v_mfma_f32_16x16x32_bf16 v[50:53], v[212:215], v[220:223], v[50:53]
	v_mfma_f32_16x16x32_bf16 v[38:41], v[194:197], v[228:231], v[38:41]
	v_mfma_f32_16x16x32_bf16 v[34:37], v[212:215], v[228:231], v[34:37]
	v_mfma_f32_16x16x32_bf16 v[22:25], v[194:197], v[236:239], v[22:25]
	v_mfma_f32_16x16x32_bf16 v[18:21], v[212:215], v[236:239], v[18:21]
	v_mfma_f32_16x16x32_bf16 v[6:9], v[194:197], v[244:247], v[6:9]
	v_mfma_f32_16x16x32_bf16 v[2:5], v[212:215], v[244:247], v[2:5]
	s_barrier
	s_add_i32 s39, s39, 2
	s_add_u32 s37, s37, 0x100
	s_addc_u32 s38, s38, 0
	s_add_u32 s26, s26, 0x100
	s_addc_u32 s27, s27, 0
	s_cmp_gt_u32 s39, 29
	s_cbranch_scc0 .LBB0_546
	s_and_b64 vcc, exec, s[14:15]
	s_cbranch_vccz .LBB0_549
	s_barrier

; #define PG8_STAGE(bufoff, gbase, voff) do { _Pragma("unroll") for (int _i = 0; _i < 2; ++_i) \
;         __builtin_amdgcn_global_load_lds((const unsigned*)((const char*)(gbase) + (voff)[_i]), (LAS unsigned*)(lds + (bufoff) + ldsw + _i * 8192), 16, 0, 0); } while (0)
; #define PG8_LDA(dst, b, h) do { _Pragma("unroll") for (int m = 0; m < 4; ++m) _Pragma("unroll") for (int k = 0; k < 2; ++k) dst[m][k] = *(const LAS bf16x8*)(lds + PG8_SA(b, h) + aoff + m * 2048 + k * 1024); } while (0)
; #define PG8_LDB(dst, b, h) do { _Pragma("unroll") for (int n = 0; n < 2; ++n) _Pragma("unroll") for (int k = 0; k < 2; ++k) dst[n][k] = *(const LAS bf16x8*)(lds + PG8_SB(b, h) + boff + n * 2048 + k * 1024); } while (0)
; #define PG8_MMA(ai, bj, At, Bt) do { __builtin_amdgcn_s_setprio(1); _Pragma("unroll") for (int m = 0; m < 4; ++m) _Pragma("unroll") for (int n = 0; n < 2; ++n) _Pragma("unroll") for (int k = 0; k < 2; ++k) \
;         acc[ai][bj][m][n] = __builtin_amdgcn_mfma_f32_16x16x32_bf16(Bt[n][k], At[m][k], acc[ai][bj][m][n], 0, 0, 0); __builtin_amdgcn_s_setprio(0); } while (0)
; #define PG8_WAIT_V(n) asm volatile("s_waitcnt vmcnt(" #n ")" ::: "memory")
; #define PG8_WAIT_L(n) asm volatile("s_waitcnt lgkmcnt(" #n ")" ::: "memory")
; #define PG8_BAR __builtin_amdgcn_s_barrier()
; #define PG8_SCHED __builtin_amdgcn_sched_barrier(0)
; template <class Epi>
; __device__ __forceinline__ void gemm_phase(LAS unsigned char* lds, const Gemm g, const StaticOrder& S, const Epi& E, const int tid) {
;     ...
;             PG8_LDB(B0, 0, 0); PG8_LDB(B1, 0, 1); PG8_SCHED; PG8_LDA(At, 0, 0); PG8_STAGE(PG8_SA(1, 1), a1 + hstep, voffA);
;             PG8_WAIT_V(8); PG8_WAIT_L(0); PG8_BAR; PG8_MMA(0, 0, At, B0); PG8_MMA(0, 1, At, B1); PG8_BAR; PG8_SCHED;
;             PG8_LDA(At, 0, 1); PG8_STAGE(PG8_SB(0, 0), b2, voffB); PG8_STAGE(PG8_SB(0, 1), b2 + bhs, voffB); PG8_STAGE(PG8_SA(0, 0), a2, voffA);
;             PG8_WAIT_V(8); PG8_WAIT_L(0); PG8_BAR; PG8_MMA(1, 0, At, B0); PG8_MMA(1, 1, At, B1); PG8_BAR; PG8_SCHED;
.LBB0_844:
	s_add_u32 s28, s26, 0xfff80080
	s_addc_u32 s29, s27, -1
	s_add_i32 s48, 0, 0x10000
	s_cmp_eq_u32 s47, 28
	s_cselect_b32 s31, s15, s29
	s_cselect_b32 s30, s43, s28
	v_add_u32_e32 v145, s48, v142
	s_cselect_b32 s29, s13, s46
	s_cselect_b32 s28, s44, s45
	s_add_i32 s50, 0, 0x14000
	ds_read_b128 v[146:149], v145
	ds_read_b128 v[150:153], v145 offset:1024
	ds_read_b128 v[154:157], v145 offset:2048
	ds_read_b128 v[158:161], v145 offset:3072
	v_add_u32_e32 v145, s50, v142
	ds_read_b128 v[162:165], v145
	ds_read_b128 v[166:169], v145 offset:1024
	ds_read_b128 v[178:181], v145 offset:2048
	ds_read_b128 v[182:185], v145 offset:3072
	v_lshl_add_u64 v[172:173], s[26:27], 0, v[138:139]
	s_add_i32 m0, s23, 0xc000
	ds_read_b128 v[186:189], v144
	global_load_lds_dwordx4 v[172:173], off
	ds_read_b128 v[190:193], v144 offset:1024
	ds_read_b128 v[194:197], v144 offset:2048
	v_lshl_add_u64 v[172:173], s[26:27], 0, v[136:137]
	s_add_i32 m0, s23, 0xe000
	s_nop 0
	global_load_lds_dwordx4 v[172:173], off
	ds_read_b128 v[198:201], v144 offset:3072
	ds_read_b128 v[212:215], v144 offset:4096
	ds_read_b128 v[216:219], v144 offset:5120
	ds_read_b128 v[220:223], v144 offset:6144
	ds_read_b128 v[224:227], v144 offset:7168
	s_waitcnt vmcnt(8)
	s_waitcnt lgkmcnt(0)
	s_barrier
	s_waitcnt lgkmcnt(0)
	v_mfma_f32_16x16x32_bf16 v[126:129], v[146:149], v[186:189], v[126:129]
	v_mfma_f32_16x16x32_bf16 v[122:125], v[154:157], v[186:189], v[122:125]
	v_mfma_f32_16x16x32_bf16 v[118:121], v[146:149], v[194:197], v[118:121]
	v_mfma_f32_16x16x32_bf16 v[110:113], v[154:157], v[194:197], v[110:113]
	v_mfma_f32_16x16x32_bf16 v[102:105], v[146:149], v[212:215], v[102:105]
	v_mfma_f32_16x16x32_bf16 v[94:97], v[154:157], v[212:215], v[94:97]
	v_mfma_f32_16x16x32_bf16 v[86:89], v[146:149], v[220:223], v[86:89]
	v_mfma_f32_16x16x32_bf16 v[78:81], v[154:157], v[220:223], v[78:81]
	v_mfma_f32_16x16x32_bf16 v[126:129], v[150:153], v[190:193], v[126:129]
	v_mfma_f32_16x16x32_bf16 v[122:125], v[158:161], v[190:193], v[122:125]
	v_mfma_f32_16x16x32_bf16 v[118:121], v[150:153], v[198:201], v[118:121]
	v_mfma_f32_16x16x32_bf16 v[110:113], v[158:161], v[198:201], v[110:113]
	v_mfma_f32_16x16x32_bf16 v[102:105], v[150:153], v[216:219], v[102:105]
	v_mfma_f32_16x16x32_bf16 v[94:97], v[158:161], v[216:219], v[94:97]
	v_mfma_f32_16x16x32_bf16 v[86:89], v[150:153], v[224:227], v[86:89]
	v_mfma_f32_16x16x32_bf16 v[78:81], v[158:161], v[224:227], v[78:81]
	v_mfma_f32_16x16x32_bf16 v[114:117], v[162:165], v[186:189], v[114:117]
	v_mfma_f32_16x16x32_bf16 v[106:109], v[178:181], v[186:189], v[106:109]
	v_mfma_f32_16x16x32_bf16 v[98:101], v[162:165], v[194:197], v[98:101]
	v_mfma_f32_16x16x32_bf16 v[90:93], v[178:181], v[194:197], v[90:93]
	v_mfma_f32_16x16x32_bf16 v[82:85], v[162:165], v[212:215], v[82:85]
	v_mfma_f32_16x16x32_bf16 v[74:77], v[178:181], v[212:215], v[74:77]
	v_mfma_f32_16x16x32_bf16 v[70:73], v[162:165], v[220:223], v[70:73]
	v_mfma_f32_16x16x32_bf16 v[66:69], v[178:181], v[220:223], v[66:69]
	v_mfma_f32_16x16x32_bf16 v[114:117], v[166:169], v[190:193], v[114:117]
	v_mfma_f32_16x16x32_bf16 v[106:109], v[182:185], v[190:193], v[106:109]
	v_mfma_f32_16x16x32_bf16 v[98:101], v[166:169], v[198:201], v[98:101]
	v_mfma_f32_16x16x32_bf16 v[90:93], v[182:185], v[198:201], v[90:93]
	v_mfma_f32_16x16x32_bf16 v[82:85], v[166:169], v[216:219], v[82:85]
	v_mfma_f32_16x16x32_bf16 v[74:77], v[182:185], v[216:219], v[74:77]
	v_mfma_f32_16x16x32_bf16 v[70:73], v[166:169], v[224:227], v[70:73]
	v_mfma_f32_16x16x32_bf16 v[66:69], v[182:185], v[224:227], v[66:69]
	s_barrier
	s_add_i32 s48, s48, s37
	v_lshl_add_u64 v[172:173], s[28:29], 0, v[0:1]
	s_mov_b32 m0, s48
	ds_read_b128 v[186:189], v144 offset:16384
	global_load_lds_dwordx4 v[172:173], off
	ds_read_b128 v[190:193], v144 offset:17408
	ds_read_b128 v[194:197], v144 offset:18432
	s_add_i32 m0, s48, 0x2000
	s_add_u32 s48, s28, 0x8000
	v_lshl_add_u64 v[174:175], s[28:29], 0, v[134:135]
	s_addc_u32 s49, s29, 0
	s_add_i32 s50, s50, s37
	global_load_lds_dwordx4 v[174:175], off
	ds_read_b128 v[198:201], v144 offset:19456
	ds_read_b128 v[212:215], v144 offset:20480
	v_lshl_add_u64 v[176:177], s[48:49], 0, v[0:1]
	s_mov_b32 m0, s50
	v_lshl_add_u64 v[228:229], s[30:31], 0, v[132:133]
	global_load_lds_dwordx4 v[176:177], off
	ds_read_b128 v[216:219], v144 offset:21504
	ds_read_b128 v[220:223], v144 offset:22528
	v_lshl_add_u64 v[176:177], s[48:49], 0, v[134:135]
	s_add_i32 m0, s50, 0x2000
	s_nop 0
	global_load_lds_dwordx4 v[176:177], off
	ds_read_b128 v[224:227], v144 offset:23552
	v_lshl_add_u64 v[176:177], s[30:31], 0, v[130:131]
	s_mov_b32 m0, s23
	s_nop 0
	global_load_lds_dwordx4 v[176:177], off
	s_mov_b32 m0, s25
	s_nop 0
	global_load_lds_dwordx4 v[228:229], off
	s_waitcnt vmcnt(8)
	s_waitcnt lgkmcnt(0)
	s_barrier
; #define PG8_STAGE(bufoff, gbase, voff) do { _Pragma("unroll") for (int _i = 0; _i < 2; ++_i) \
;         __builtin_amdgcn_global_load_lds((const unsigned*)((const char*)(gbase) + (voff)[_i]), (LAS unsigned*)(lds + (bufoff) + ldsw + _i * 8192), 16, 0, 0); } while (0)
; #define PG8_LDA(dst, b, h) do { _Pragma("unroll") for (int m = 0; m < 4; ++m) _Pragma("unroll") for (int k = 0; k < 2; ++k) dst[m][k] = *(const LAS bf16x8*)(lds + PG8_SA(b, h) + aoff + m * 2048 + k * 1024); } while (0)
; #define PG8_LDB(dst, b, h) do { _Pragma("unroll") for (int n = 0; n < 2; ++n) _Pragma("unroll") for (int k = 0; k < 2; ++k) dst[n][k] = *(const LAS bf16x8*)(lds + PG8_SB(b, h) + boff + n * 2048 + k * 1024); } while (0)
; #define PG8_MMA(ai, bj, At, Bt) do { __builtin_amdgcn_s_setprio(1); _Pragma("unroll") for (int m = 0; m < 4; ++m) _Pragma("unroll") for (int n = 0; n < 2; ++n) _Pragma("unroll") for (int k = 0; k < 2; ++k) \
;         acc[ai][bj][m][n] = __builtin_amdgcn_mfma_f32_16x16x32_bf16(Bt[n][k], At[m][k], acc[ai][bj][m][n], 0, 0, 0); __builtin_amdgcn_s_setprio(0); } while (0)
; #define PG8_WAIT_V(n) asm volatile("s_waitcnt vmcnt(" #n ")" ::: "memory")
; #define PG8_WAIT_L(n) asm volatile("s_waitcnt lgkmcnt(" #n ")" ::: "memory")
; #define PG8_BAR __builtin_amdgcn_s_barrier()
; #define PG8_SCHED __builtin_amdgcn_sched_barrier(0)
; template <class Epi>
; __device__ __forceinline__ void gemm_phase(LAS unsigned char* lds, const Gemm g, const StaticOrder& S, const Epi& E, const int tid) {
;     ...
;             PG8_WAIT_V(8); PG8_WAIT_L(0); PG8_BAR; PG8_MMA(1, 0, At, B0); PG8_MMA(1, 1, At, B1); PG8_BAR; PG8_SCHED;
;             PG8_LDB(B0, 1, 0); PG8_LDB(B1, 1, 1); PG8_SCHED; PG8_LDA(At, 1, 0); PG8_STAGE(PG8_SA(0, 1), a2 + hstep, voffA);
;             PG8_WAIT_V(8); PG8_WAIT_L(0); PG8_BAR; PG8_MMA(0, 0, At, B0); PG8_MMA(0, 1, At, B1); PG8_BAR; PG8_SCHED;
	s_waitcnt lgkmcnt(0)
	v_mfma_f32_16x16x32_bf16 v[62:65], v[146:149], v[186:189], v[62:65]
	v_mfma_f32_16x16x32_bf16 v[58:61], v[154:157], v[186:189], v[58:61]
	v_mfma_f32_16x16x32_bf16 v[54:57], v[146:149], v[194:197], v[54:57]
	v_mfma_f32_16x16x32_bf16 v[46:49], v[154:157], v[194:197], v[46:49]
	v_mfma_f32_16x16x32_bf16 v[38:41], v[146:149], v[212:215], v[38:41]
	v_mfma_f32_16x16x32_bf16 v[30:33], v[154:157], v[212:215], v[30:33]
	v_mfma_f32_16x16x32_bf16 v[22:25], v[146:149], v[220:223], v[22:25]
	v_mfma_f32_16x16x32_bf16 v[14:17], v[154:157], v[220:223], v[14:17]
	v_mfma_f32_16x16x32_bf16 v[62:65], v[150:153], v[190:193], v[62:65]
	v_mfma_f32_16x16x32_bf16 v[58:61], v[158:161], v[190:193], v[58:61]
	v_mfma_f32_16x16x32_bf16 v[54:57], v[150:153], v[198:201], v[54:57]
	v_mfma_f32_16x16x32_bf16 v[46:49], v[158:161], v[198:201], v[46:49]
	v_mfma_f32_16x16x32_bf16 v[38:41], v[150:153], v[216:219], v[38:41]
	v_mfma_f32_16x16x32_bf16 v[30:33], v[158:161], v[216:219], v[30:33]
	v_mfma_f32_16x16x32_bf16 v[22:25], v[150:153], v[224:227], v[22:25]
	v_mfma_f32_16x16x32_bf16 v[14:17], v[158:161], v[224:227], v[14:17]
	v_mfma_f32_16x16x32_bf16 v[50:53], v[162:165], v[186:189], v[50:53]
	v_mfma_f32_16x16x32_bf16 v[42:45], v[178:181], v[186:189], v[42:45]
	v_mfma_f32_16x16x32_bf16 v[34:37], v[162:165], v[194:197], v[34:37]
	v_mfma_f32_16x16x32_bf16 v[26:29], v[178:181], v[194:197], v[26:29]
	v_mfma_f32_16x16x32_bf16 v[18:21], v[162:165], v[212:215], v[18:21]
	v_mfma_f32_16x16x32_bf16 v[10:13], v[178:181], v[212:215], v[10:13]
	v_mfma_f32_16x16x32_bf16 v[6:9], v[162:165], v[220:223], v[6:9]
	v_mfma_f32_16x16x32_bf16 v[2:5], v[178:181], v[220:223], v[2:5]
	v_mfma_f32_16x16x32_bf16 v[50:53], v[166:169], v[190:193], v[50:53]
	v_mfma_f32_16x16x32_bf16 v[42:45], v[182:185], v[190:193], v[42:45]
	v_mfma_f32_16x16x32_bf16 v[34:37], v[166:169], v[198:201], v[34:37]
	v_mfma_f32_16x16x32_bf16 v[26:29], v[182:185], v[198:201], v[26:29]
	v_mfma_f32_16x16x32_bf16 v[18:21], v[166:169], v[216:219], v[18:21]
	v_mfma_f32_16x16x32_bf16 v[10:13], v[182:185], v[216:219], v[10:13]
	v_mfma_f32_16x16x32_bf16 v[6:9], v[166:169], v[224:227], v[6:9]
	v_mfma_f32_16x16x32_bf16 v[2:5], v[182:185], v[224:227], v[2:5]
	s_barrier
	s_add_i32 s48, 0, 0x18000
	v_add_u32_e32 v145, s48, v142
	s_add_i32 s49, 0, 0x1c000
	ds_read_b128 v[146:149], v145
	ds_read_b128 v[150:153], v145 offset:1024
	ds_read_b128 v[154:157], v145 offset:2048
	ds_read_b128 v[158:161], v145 offset:3072
	v_add_u32_e32 v145, s49, v142
	ds_read_b128 v[162:165], v145
	ds_read_b128 v[166:169], v145 offset:1024
	ds_read_b128 v[178:181], v145 offset:2048
	ds_read_b128 v[182:185], v145 offset:3072
	s_add_u32 s30, s30, 0x80000
	s_addc_u32 s31, s31, 0
	s_mov_b32 m0, s38
	v_lshl_add_u64 v[230:231], s[30:31], 0, v[130:131]
	ds_read_b128 v[186:189], v144 offset:32768
	global_load_lds_dwordx4 v[230:231], off
	ds_read_b128 v[190:193], v144 offset:33792
	ds_read_b128 v[194:197], v144 offset:34816
	v_lshl_add_u64 v[230:231], s[30:31], 0, v[132:133]
	s_mov_b32 m0, s39
	s_nop 0
	global_load_lds_dwordx4 v[230:231], off
	ds_read_b128 v[198:201], v144 offset:35840
	ds_read_b128 v[212:215], v144 offset:36864
	ds_read_b128 v[216:219], v144 offset:37888
	ds_read_b128 v[220:223], v144 offset:38912
	ds_read_b128 v[224:227], v144 offset:39936
	s_waitcnt vmcnt(8)
	s_waitcnt lgkmcnt(0)
	s_barrier
	s_waitcnt lgkmcnt(0)
	v_mfma_f32_16x16x32_bf16 v[126:129], v[146:149], v[186:189], v[126:129]
	v_mfma_f32_16x16x32_bf16 v[122:125], v[154:157], v[186:189], v[122:125]
	v_mfma_f32_16x16x32_bf16 v[118:121], v[146:149], v[194:197], v[118:121]
	v_mfma_f32_16x16x32_bf16 v[110:113], v[154:157], v[194:197], v[110:113]
	v_mfma_f32_16x16x32_bf16 v[102:105], v[146:149], v[212:215], v[102:105]
	v_mfma_f32_16x16x32_bf16 v[94:97], v[154:157], v[212:215], v[94:97]
	v_mfma_f32_16x16x32_bf16 v[86:89], v[146:149], v[220:223], v[86:89]
	v_mfma_f32_16x16x32_bf16 v[78:81], v[154:157], v[220:223], v[78:81]
	v_mfma_f32_16x16x32_bf16 v[126:129], v[150:153], v[190:193], v[126:129]
	v_mfma_f32_16x16x32_bf16 v[122:125], v[158:161], v[190:193], v[122:125]
	v_mfma_f32_16x16x32_bf16 v[118:121], v[150:153], v[198:201], v[118:121]
	v_mfma_f32_16x16x32_bf16 v[110:113], v[158:161], v[198:201], v[110:113]
	v_mfma_f32_16x16x32_bf16 v[102:105], v[150:153], v[216:219], v[102:105]
	v_mfma_f32_16x16x32_bf16 v[94:97], v[158:161], v[216:219], v[94:97]
	v_mfma_f32_16x16x32_bf16 v[86:89], v[150:153], v[224:227], v[86:89]
	v_mfma_f32_16x16x32_bf16 v[78:81], v[158:161], v[224:227], v[78:81]
	v_mfma_f32_16x16x32_bf16 v[114:117], v[162:165], v[186:189], v[114:117]
	v_mfma_f32_16x16x32_bf16 v[106:109], v[178:181], v[186:189], v[106:109]
	v_mfma_f32_16x16x32_bf16 v[98:101], v[162:165], v[194:197], v[98:101]
	v_mfma_f32_16x16x32_bf16 v[90:93], v[178:181], v[194:197], v[90:93]
	v_mfma_f32_16x16x32_bf16 v[82:85], v[162:165], v[212:215], v[82:85]
	v_mfma_f32_16x16x32_bf16 v[74:77], v[178:181], v[212:215], v[74:77]
	v_mfma_f32_16x16x32_bf16 v[70:73], v[162:165], v[220:223], v[70:73]
	v_mfma_f32_16x16x32_bf16 v[66:69], v[178:181], v[220:223], v[66:69]
	v_mfma_f32_16x16x32_bf16 v[114:117], v[166:169], v[190:193], v[114:117]
	v_mfma_f32_16x16x32_bf16 v[106:109], v[182:185], v[190:193], v[106:109]
	v_mfma_f32_16x16x32_bf16 v[98:101], v[166:169], v[198:201], v[98:101]
	v_mfma_f32_16x16x32_bf16 v[90:93], v[182:185], v[198:201], v[90:93]
	v_mfma_f32_16x16x32_bf16 v[82:85], v[166:169], v[216:219], v[82:85]
	v_mfma_f32_16x16x32_bf16 v[74:77], v[182:185], v[216:219], v[74:77]
	v_mfma_f32_16x16x32_bf16 v[70:73], v[166:169], v[224:227], v[70:73]
	v_mfma_f32_16x16x32_bf16 v[66:69], v[182:185], v[224:227], v[66:69]
	s_barrier
; #define PG8_STAGE(bufoff, gbase, voff) do { _Pragma("unroll") for (int _i = 0; _i < 2; ++_i) \
;         __builtin_amdgcn_global_load_lds((const unsigned*)((const char*)(gbase) + (voff)[_i]), (LAS unsigned*)(lds + (bufoff) + ldsw + _i * 8192), 16, 0, 0); } while (0)
; #define PG8_LDA(dst, b, h) do { _Pragma("unroll") for (int m = 0; m < 4; ++m) _Pragma("unroll") for (int k = 0; k < 2; ++k) dst[m][k] = *(const LAS bf16x8*)(lds + PG8_SA(b, h) + aoff + m * 2048 + k * 1024); } while (0)
; #define PG8_MMA(ai, bj, At, Bt) do { __builtin_amdgcn_s_setprio(1); _Pragma("unroll") for (int m = 0; m < 4; ++m) _Pragma("unroll") for (int n = 0; n < 2; ++n) _Pragma("unroll") for (int k = 0; k < 2; ++k) \
;         acc[ai][bj][m][n] = __builtin_amdgcn_mfma_f32_16x16x32_bf16(Bt[n][k], At[m][k], acc[ai][bj][m][n], 0, 0, 0); __builtin_amdgcn_s_setprio(0); } while (0)
; #define PG8_WAIT_V(n) asm volatile("s_waitcnt vmcnt(" #n ")" ::: "memory")
; #define PG8_WAIT_L(n) asm volatile("s_waitcnt lgkmcnt(" #n ")" ::: "memory")
; #define PG8_BAR __builtin_amdgcn_s_barrier()
; #define PG8_SCHED __builtin_amdgcn_sched_barrier(0)
; template <class Epi>
; __device__ __forceinline__ void gemm_phase(LAS unsigned char* lds, const Gemm g, const StaticOrder& S, const Epi& E, const int tid) {
;     ...
;             PG8_LDA(At, 1, 1); PG8_STAGE(PG8_SB(1, 0), b3, voffB); PG8_STAGE(PG8_SB(1, 1), b3 + bhs, voffB); PG8_STAGE(PG8_SA(1, 0), a3, voffA);
;             PG8_WAIT_V(8); PG8_WAIT_L(0); PG8_BAR; PG8_MMA(1, 0, At, B0); PG8_MMA(1, 1, At, B1); PG8_BAR; PG8_SCHED;
;     ...
;         if (ALIGN_EPI) { if (wr == 0) PG8_BAR; }
	s_add_i32 s30, s48, s37
	v_lshl_add_u64 v[172:173], v[172:173], 0, s[70:71]
	s_mov_b32 m0, s30
	ds_read_b128 v[186:189], v144 offset:49152
	global_load_lds_dwordx4 v[172:173], off
	ds_read_b128 v[190:193], v144 offset:50176
	ds_read_b128 v[194:197], v144 offset:51200
	s_add_i32 m0, s30, 0x2000
	s_add_u32 s28, s28, 0x8080
	v_lshl_add_u64 v[172:173], v[174:175], 0, s[70:71]
	s_addc_u32 s29, s29, 0
	s_add_i32 s30, s49, s37
	global_load_lds_dwordx4 v[172:173], off
	ds_read_b128 v[198:201], v144 offset:52224
	ds_read_b128 v[212:215], v144 offset:53248
	v_lshl_add_u64 v[172:173], s[28:29], 0, v[0:1]
	s_mov_b32 m0, s30
	s_nop 0
	global_load_lds_dwordx4 v[172:173], off
	ds_read_b128 v[216:219], v144 offset:54272
	ds_read_b128 v[220:223], v144 offset:55296
	v_lshl_add_u64 v[172:173], s[28:29], 0, v[134:135]
	s_add_i32 m0, s30, 0x2000
	s_nop 0
	global_load_lds_dwordx4 v[172:173], off
	ds_read_b128 v[224:227], v144 offset:56320
	v_lshl_add_u64 v[172:173], v[176:177], 0, s[70:71]
	s_mov_b32 m0, s40
	s_nop 0
	global_load_lds_dwordx4 v[172:173], off
	v_lshl_add_u64 v[172:173], v[228:229], 0, s[70:71]
	s_mov_b32 m0, s41
	s_nop 0
	global_load_lds_dwordx4 v[172:173], off
	s_waitcnt vmcnt(8)
	s_waitcnt lgkmcnt(0)
	s_barrier
	s_waitcnt lgkmcnt(0)
	v_mfma_f32_16x16x32_bf16 v[62:65], v[146:149], v[186:189], v[62:65]
	v_mfma_f32_16x16x32_bf16 v[58:61], v[154:157], v[186:189], v[58:61]
	v_mfma_f32_16x16x32_bf16 v[54:57], v[146:149], v[194:197], v[54:57]
	v_mfma_f32_16x16x32_bf16 v[46:49], v[154:157], v[194:197], v[46:49]
	v_mfma_f32_16x16x32_bf16 v[38:41], v[146:149], v[212:215], v[38:41]
	v_mfma_f32_16x16x32_bf16 v[30:33], v[154:157], v[212:215], v[30:33]
	v_mfma_f32_16x16x32_bf16 v[22:25], v[146:149], v[220:223], v[22:25]
	v_mfma_f32_16x16x32_bf16 v[14:17], v[154:157], v[220:223], v[14:17]
	v_mfma_f32_16x16x32_bf16 v[62:65], v[150:153], v[190:193], v[62:65]
	v_mfma_f32_16x16x32_bf16 v[58:61], v[158:161], v[190:193], v[58:61]
	v_mfma_f32_16x16x32_bf16 v[54:57], v[150:153], v[198:201], v[54:57]
	v_mfma_f32_16x16x32_bf16 v[46:49], v[158:161], v[198:201], v[46:49]
	v_mfma_f32_16x16x32_bf16 v[38:41], v[150:153], v[216:219], v[38:41]
	v_mfma_f32_16x16x32_bf16 v[30:33], v[158:161], v[216:219], v[30:33]
	v_mfma_f32_16x16x32_bf16 v[22:25], v[150:153], v[224:227], v[22:25]
	v_mfma_f32_16x16x32_bf16 v[14:17], v[158:161], v[224:227], v[14:17]
	v_mfma_f32_16x16x32_bf16 v[50:53], v[162:165], v[186:189], v[50:53]
	v_mfma_f32_16x16x32_bf16 v[42:45], v[178:181], v[186:189], v[42:45]
	v_mfma_f32_16x16x32_bf16 v[34:37], v[162:165], v[194:197], v[34:37]
	v_mfma_f32_16x16x32_bf16 v[26:29], v[178:181], v[194:197], v[26:29]
	v_mfma_f32_16x16x32_bf16 v[18:21], v[162:165], v[212:215], v[18:21]
	v_mfma_f32_16x16x32_bf16 v[10:13], v[178:181], v[212:215], v[10:13]
	v_mfma_f32_16x16x32_bf16 v[6:9], v[162:165], v[220:223], v[6:9]
	v_mfma_f32_16x16x32_bf16 v[2:5], v[178:181], v[220:223], v[2:5]
	v_mfma_f32_16x16x32_bf16 v[50:53], v[166:169], v[190:193], v[50:53]
	v_mfma_f32_16x16x32_bf16 v[42:45], v[182:185], v[190:193], v[42:45]
	v_mfma_f32_16x16x32_bf16 v[34:37], v[166:169], v[198:201], v[34:37]
	v_mfma_f32_16x16x32_bf16 v[26:29], v[182:185], v[198:201], v[26:29]
	v_mfma_f32_16x16x32_bf16 v[18:21], v[166:169], v[216:219], v[18:21]
	v_mfma_f32_16x16x32_bf16 v[10:13], v[182:185], v[216:219], v[10:13]
	v_mfma_f32_16x16x32_bf16 v[6:9], v[166:169], v[224:227], v[6:9]
	v_mfma_f32_16x16x32_bf16 v[2:5], v[182:185], v[224:227], v[2:5]
	s_barrier
	s_add_i32 s47, s47, 2
	s_add_u32 s45, s45, 0x100
	s_addc_u32 s46, s46, 0
	s_add_u32 s26, s26, 0x100
	s_addc_u32 s27, s27, 0
	s_cmp_gt_u32 s47, 29
	s_cbranch_scc0 .LBB0_844
	s_and_b64 vcc, exec, s[10:11]
	s_cbranch_vccz .LBB0_847
	s_barrier

; #define PG8_STAGE(bufoff, gbase, voff) do { _Pragma("unroll") for (int _i = 0; _i < 2; ++_i) \
;         __builtin_amdgcn_global_load_lds((const unsigned*)((const char*)(gbase) + (voff)[_i]), (LAS unsigned*)(lds + (bufoff) + ldsw + _i * 8192), 16, 0, 0); } while (0)
; #define PG8_LDA(dst, b, h) do { _Pragma("unroll") for (int m = 0; m < 4; ++m) _Pragma("unroll") for (int k = 0; k < 2; ++k) dst[m][k] = *(const LAS bf16x8*)(lds + PG8_SA(b, h) + aoff + m * 2048 + k * 1024); } while (0)
; #define PG8_LDB(dst, b, h) do { _Pragma("unroll") for (int n = 0; n < 2; ++n) _Pragma("unroll") for (int k = 0; k < 2; ++k) dst[n][k] = *(const LAS bf16x8*)(lds + PG8_SB(b, h) + boff + n * 2048 + k * 1024); } while (0)
; #define PG8_MMA(ai, bj, At, Bt) do { __builtin_amdgcn_s_setprio(1); _Pragma("unroll") for (int m = 0; m < 4; ++m) _Pragma("unroll") for (int n = 0; n < 2; ++n) _Pragma("unroll") for (int k = 0; k < 2; ++k) \
;         acc[ai][bj][m][n] = __builtin_amdgcn_mfma_f32_16x16x32_bf16(Bt[n][k], At[m][k], acc[ai][bj][m][n], 0, 0, 0); __builtin_amdgcn_s_setprio(0); } while (0)
; #define PG8_WAIT_V(n) asm volatile("s_waitcnt vmcnt(" #n ")" ::: "memory")
; #define PG8_WAIT_L(n) asm volatile("s_waitcnt lgkmcnt(" #n ")" ::: "memory")
; #define PG8_BAR __builtin_amdgcn_s_barrier()
; #define PG8_SCHED __builtin_amdgcn_sched_barrier(0)
; template <class Epi>
; __device__ __forceinline__ void gemm_phase(LAS unsigned char* lds, const Gemm g, const StaticOrder& S, const Epi& E, const int tid) {
;     ...
;             PG8_LDB(B0, 0, 0); PG8_LDB(B1, 0, 1); PG8_SCHED; PG8_LDA(At, 0, 0); PG8_STAGE(PG8_SA(1, 1), a1 + hstep, voffA);
;             PG8_WAIT_V(8); PG8_WAIT_L(0); PG8_BAR; PG8_MMA(0, 0, At, B0); PG8_MMA(0, 1, At, B1); PG8_BAR; PG8_SCHED;
;             PG8_LDA(At, 0, 1); PG8_STAGE(PG8_SB(0, 0), b2, voffB); PG8_STAGE(PG8_SB(0, 1), b2 + bhs, voffB); PG8_STAGE(PG8_SA(0, 0), a2, voffA);
;             PG8_WAIT_V(8); PG8_WAIT_L(0); PG8_BAR; PG8_MMA(1, 0, At, B0); PG8_MMA(1, 1, At, B1); PG8_BAR; PG8_SCHED;
.LBB0_861:
	s_add_u32 s30, s28, 0xfff80080
	s_addc_u32 s31, s29, -1
	s_add_i32 s51, 0, 0x10000
	s_cmp_eq_u32 s50, 28
	s_cselect_b32 s35, s17, s31
	s_cselect_b32 s34, s46, s30
	v_add_u32_e32 v145, s51, v142
	s_cselect_b32 s31, s15, s49
	s_cselect_b32 s30, s47, s48
	s_add_i32 s54, 0, 0x14000
	ds_read_b128 v[146:149], v145
	ds_read_b128 v[150:153], v145 offset:1024
	ds_read_b128 v[154:157], v145 offset:2048
	ds_read_b128 v[158:161], v145 offset:3072
	v_add_u32_e32 v145, s54, v142
	ds_read_b128 v[162:165], v145
	ds_read_b128 v[166:169], v145 offset:1024
	ds_read_b128 v[178:181], v145 offset:2048
	ds_read_b128 v[182:185], v145 offset:3072
	v_lshl_add_u64 v[172:173], s[28:29], 0, v[138:139]
	s_add_i32 m0, s25, 0xc000
	ds_read_b128 v[186:189], v144
	global_load_lds_dwordx4 v[172:173], off
	ds_read_b128 v[190:193], v144 offset:1024
	ds_read_b128 v[194:197], v144 offset:2048
	v_lshl_add_u64 v[172:173], s[28:29], 0, v[136:137]
	s_add_i32 m0, s25, 0xe000
	s_nop 0
	global_load_lds_dwordx4 v[172:173], off
	ds_read_b128 v[198:201], v144 offset:3072
	ds_read_b128 v[212:215], v144 offset:4096
	ds_read_b128 v[216:219], v144 offset:5120
	ds_read_b128 v[220:223], v144 offset:6144
	ds_read_b128 v[224:227], v144 offset:7168
	s_waitcnt vmcnt(8)
	s_waitcnt lgkmcnt(0)
	s_barrier
	s_waitcnt lgkmcnt(0)
	v_mfma_f32_16x16x32_bf16 v[126:129], v[146:149], v[186:189], v[126:129]
	v_mfma_f32_16x16x32_bf16 v[122:125], v[154:157], v[186:189], v[122:125]
	v_mfma_f32_16x16x32_bf16 v[118:121], v[146:149], v[194:197], v[118:121]
	v_mfma_f32_16x16x32_bf16 v[110:113], v[154:157], v[194:197], v[110:113]
	v_mfma_f32_16x16x32_bf16 v[102:105], v[146:149], v[212:215], v[102:105]
	v_mfma_f32_16x16x32_bf16 v[94:97], v[154:157], v[212:215], v[94:97]
	v_mfma_f32_16x16x32_bf16 v[86:89], v[146:149], v[220:223], v[86:89]
	v_mfma_f32_16x16x32_bf16 v[78:81], v[154:157], v[220:223], v[78:81]
	v_mfma_f32_16x16x32_bf16 v[126:129], v[150:153], v[190:193], v[126:129]
	v_mfma_f32_16x16x32_bf16 v[122:125], v[158:161], v[190:193], v[122:125]
	v_mfma_f32_16x16x32_bf16 v[118:121], v[150:153], v[198:201], v[118:121]
	v_mfma_f32_16x16x32_bf16 v[110:113], v[158:161], v[198:201], v[110:113]
	v_mfma_f32_16x16x32_bf16 v[102:105], v[150:153], v[216:219], v[102:105]
	v_mfma_f32_16x16x32_bf16 v[94:97], v[158:161], v[216:219], v[94:97]
	v_mfma_f32_16x16x32_bf16 v[86:89], v[150:153], v[224:227], v[86:89]
	v_mfma_f32_16x16x32_bf16 v[78:81], v[158:161], v[224:227], v[78:81]
	v_mfma_f32_16x16x32_bf16 v[114:117], v[162:165], v[186:189], v[114:117]
	v_mfma_f32_16x16x32_bf16 v[106:109], v[178:181], v[186:189], v[106:109]
	v_mfma_f32_16x16x32_bf16 v[98:101], v[162:165], v[194:197], v[98:101]
	v_mfma_f32_16x16x32_bf16 v[90:93], v[178:181], v[194:197], v[90:93]
	v_mfma_f32_16x16x32_bf16 v[82:85], v[162:165], v[212:215], v[82:85]
	v_mfma_f32_16x16x32_bf16 v[74:77], v[178:181], v[212:215], v[74:77]
	v_mfma_f32_16x16x32_bf16 v[70:73], v[162:165], v[220:223], v[70:73]
	v_mfma_f32_16x16x32_bf16 v[66:69], v[178:181], v[220:223], v[66:69]
	v_mfma_f32_16x16x32_bf16 v[114:117], v[166:169], v[190:193], v[114:117]
	v_mfma_f32_16x16x32_bf16 v[106:109], v[182:185], v[190:193], v[106:109]
	v_mfma_f32_16x16x32_bf16 v[98:101], v[166:169], v[198:201], v[98:101]
	v_mfma_f32_16x16x32_bf16 v[90:93], v[182:185], v[198:201], v[90:93]
	v_mfma_f32_16x16x32_bf16 v[82:85], v[166:169], v[216:219], v[82:85]
	v_mfma_f32_16x16x32_bf16 v[74:77], v[182:185], v[216:219], v[74:77]
	v_mfma_f32_16x16x32_bf16 v[70:73], v[166:169], v[224:227], v[70:73]
	v_mfma_f32_16x16x32_bf16 v[66:69], v[182:185], v[224:227], v[66:69]
	s_barrier
	s_add_i32 s51, s51, s40
	v_lshl_add_u64 v[172:173], s[30:31], 0, v[0:1]
	s_mov_b32 m0, s51
	ds_read_b128 v[186:189], v144 offset:16384
	global_load_lds_dwordx4 v[172:173], off
	ds_read_b128 v[190:193], v144 offset:17408
	ds_read_b128 v[194:197], v144 offset:18432
	s_add_i32 m0, s51, 0x2000
	s_add_u32 s52, s30, 0x8000
	v_lshl_add_u64 v[174:175], s[30:31], 0, v[134:135]
	s_addc_u32 s53, s31, 0
	s_add_i32 s51, s54, s40
	global_load_lds_dwordx4 v[174:175], off
	ds_read_b128 v[198:201], v144 offset:19456
	ds_read_b128 v[212:215], v144 offset:20480
	v_lshl_add_u64 v[176:177], s[52:53], 0, v[0:1]
	s_mov_b32 m0, s51
	v_lshl_add_u64 v[228:229], s[34:35], 0, v[132:133]
	global_load_lds_dwordx4 v[176:177], off
	ds_read_b128 v[216:219], v144 offset:21504
	ds_read_b128 v[220:223], v144 offset:22528
	v_lshl_add_u64 v[176:177], s[52:53], 0, v[134:135]
	s_add_i32 m0, s51, 0x2000
	s_nop 0
	global_load_lds_dwordx4 v[176:177], off
	ds_read_b128 v[224:227], v144 offset:23552
	v_lshl_add_u64 v[176:177], s[34:35], 0, v[130:131]
	s_mov_b32 m0, s25
	s_nop 0
	global_load_lds_dwordx4 v[176:177], off
	s_mov_b32 m0, s27
	s_nop 0
	global_load_lds_dwordx4 v[228:229], off
	s_waitcnt vmcnt(8)
	s_waitcnt lgkmcnt(0)
	s_barrier
; #define PG8_STAGE(bufoff, gbase, voff) do { _Pragma("unroll") for (int _i = 0; _i < 2; ++_i) \
;         __builtin_amdgcn_global_load_lds((const unsigned*)((const char*)(gbase) + (voff)[_i]), (LAS unsigned*)(lds + (bufoff) + ldsw + _i * 8192), 16, 0, 0); } while (0)
; #define PG8_LDA(dst, b, h) do { _Pragma("unroll") for (int m = 0; m < 4; ++m) _Pragma("unroll") for (int k = 0; k < 2; ++k) dst[m][k] = *(const LAS bf16x8*)(lds + PG8_SA(b, h) + aoff + m * 2048 + k * 1024); } while (0)
; #define PG8_LDB(dst, b, h) do { _Pragma("unroll") for (int n = 0; n < 2; ++n) _Pragma("unroll") for (int k = 0; k < 2; ++k) dst[n][k] = *(const LAS bf16x8*)(lds + PG8_SB(b, h) + boff + n * 2048 + k * 1024); } while (0)
; #define PG8_MMA(ai, bj, At, Bt) do { __builtin_amdgcn_s_setprio(1); _Pragma("unroll") for (int m = 0; m < 4; ++m) _Pragma("unroll") for (int n = 0; n < 2; ++n) _Pragma("unroll") for (int k = 0; k < 2; ++k) \
;         acc[ai][bj][m][n] = __builtin_amdgcn_mfma_f32_16x16x32_bf16(Bt[n][k], At[m][k], acc[ai][bj][m][n], 0, 0, 0); __builtin_amdgcn_s_setprio(0); } while (0)
; #define PG8_WAIT_V(n) asm volatile("s_waitcnt vmcnt(" #n ")" ::: "memory")
; #define PG8_WAIT_L(n) asm volatile("s_waitcnt lgkmcnt(" #n ")" ::: "memory")
; #define PG8_BAR __builtin_amdgcn_s_barrier()
; #define PG8_SCHED __builtin_amdgcn_sched_barrier(0)
; template <class Epi>
; __device__ __forceinline__ void gemm_phase(LAS unsigned char* lds, const Gemm g, const StaticOrder& S, const Epi& E, const int tid) {
;     ...
;             PG8_WAIT_V(8); PG8_WAIT_L(0); PG8_BAR; PG8_MMA(1, 0, At, B0); PG8_MMA(1, 1, At, B1); PG8_BAR; PG8_SCHED;
;             PG8_LDB(B0, 1, 0); PG8_LDB(B1, 1, 1); PG8_SCHED; PG8_LDA(At, 1, 0); PG8_STAGE(PG8_SA(0, 1), a2 + hstep, voffA);
;             PG8_WAIT_V(8); PG8_WAIT_L(0); PG8_BAR; PG8_MMA(0, 0, At, B0); PG8_MMA(0, 1, At, B1); PG8_BAR; PG8_SCHED;
	s_waitcnt lgkmcnt(0)
	v_mfma_f32_16x16x32_bf16 v[62:65], v[146:149], v[186:189], v[62:65]
	v_mfma_f32_16x16x32_bf16 v[58:61], v[154:157], v[186:189], v[58:61]
	v_mfma_f32_16x16x32_bf16 v[54:57], v[146:149], v[194:197], v[54:57]
	v_mfma_f32_16x16x32_bf16 v[46:49], v[154:157], v[194:197], v[46:49]
	v_mfma_f32_16x16x32_bf16 v[38:41], v[146:149], v[212:215], v[38:41]
	v_mfma_f32_16x16x32_bf16 v[30:33], v[154:157], v[212:215], v[30:33]
	v_mfma_f32_16x16x32_bf16 v[22:25], v[146:149], v[220:223], v[22:25]
	v_mfma_f32_16x16x32_bf16 v[14:17], v[154:157], v[220:223], v[14:17]
	v_mfma_f32_16x16x32_bf16 v[62:65], v[150:153], v[190:193], v[62:65]
	v_mfma_f32_16x16x32_bf16 v[58:61], v[158:161], v[190:193], v[58:61]
	v_mfma_f32_16x16x32_bf16 v[54:57], v[150:153], v[198:201], v[54:57]
	v_mfma_f32_16x16x32_bf16 v[46:49], v[158:161], v[198:201], v[46:49]
	v_mfma_f32_16x16x32_bf16 v[38:41], v[150:153], v[216:219], v[38:41]
	v_mfma_f32_16x16x32_bf16 v[30:33], v[158:161], v[216:219], v[30:33]
	v_mfma_f32_16x16x32_bf16 v[22:25], v[150:153], v[224:227], v[22:25]
	v_mfma_f32_16x16x32_bf16 v[14:17], v[158:161], v[224:227], v[14:17]
	v_mfma_f32_16x16x32_bf16 v[50:53], v[162:165], v[186:189], v[50:53]
	v_mfma_f32_16x16x32_bf16 v[42:45], v[178:181], v[186:189], v[42:45]
	v_mfma_f32_16x16x32_bf16 v[34:37], v[162:165], v[194:197], v[34:37]
	v_mfma_f32_16x16x32_bf16 v[26:29], v[178:181], v[194:197], v[26:29]
	v_mfma_f32_16x16x32_bf16 v[18:21], v[162:165], v[212:215], v[18:21]
	v_mfma_f32_16x16x32_bf16 v[10:13], v[178:181], v[212:215], v[10:13]
	v_mfma_f32_16x16x32_bf16 v[6:9], v[162:165], v[220:223], v[6:9]
	v_mfma_f32_16x16x32_bf16 v[2:5], v[178:181], v[220:223], v[2:5]
	v_mfma_f32_16x16x32_bf16 v[50:53], v[166:169], v[190:193], v[50:53]
	v_mfma_f32_16x16x32_bf16 v[42:45], v[182:185], v[190:193], v[42:45]
	v_mfma_f32_16x16x32_bf16 v[34:37], v[166:169], v[198:201], v[34:37]
	v_mfma_f32_16x16x32_bf16 v[26:29], v[182:185], v[198:201], v[26:29]
	v_mfma_f32_16x16x32_bf16 v[18:21], v[166:169], v[216:219], v[18:21]
	v_mfma_f32_16x16x32_bf16 v[10:13], v[182:185], v[216:219], v[10:13]
	v_mfma_f32_16x16x32_bf16 v[6:9], v[166:169], v[224:227], v[6:9]
	v_mfma_f32_16x16x32_bf16 v[2:5], v[182:185], v[224:227], v[2:5]
	s_barrier
	s_add_i32 s51, 0, 0x18000
	v_add_u32_e32 v145, s51, v142
	s_add_i32 s52, 0, 0x1c000
	ds_read_b128 v[146:149], v145
	ds_read_b128 v[150:153], v145 offset:1024
	ds_read_b128 v[154:157], v145 offset:2048
	ds_read_b128 v[158:161], v145 offset:3072
	v_add_u32_e32 v145, s52, v142
	ds_read_b128 v[162:165], v145
	ds_read_b128 v[166:169], v145 offset:1024
	ds_read_b128 v[178:181], v145 offset:2048
	ds_read_b128 v[182:185], v145 offset:3072
	s_add_u32 s34, s34, 0x80000
	s_addc_u32 s35, s35, 0
	s_mov_b32 m0, s41
	v_lshl_add_u64 v[230:231], s[34:35], 0, v[130:131]
	ds_read_b128 v[186:189], v144 offset:32768
	global_load_lds_dwordx4 v[230:231], off
	ds_read_b128 v[190:193], v144 offset:33792
	ds_read_b128 v[194:197], v144 offset:34816
	v_lshl_add_u64 v[230:231], s[34:35], 0, v[132:133]
	s_mov_b32 m0, s42
	s_nop 0
	global_load_lds_dwordx4 v[230:231], off
	ds_read_b128 v[198:201], v144 offset:35840
	ds_read_b128 v[212:215], v144 offset:36864
	ds_read_b128 v[216:219], v144 offset:37888
	ds_read_b128 v[220:223], v144 offset:38912
	ds_read_b128 v[224:227], v144 offset:39936
	s_waitcnt vmcnt(8)
	s_waitcnt lgkmcnt(0)
	s_barrier
	s_waitcnt lgkmcnt(0)
	v_mfma_f32_16x16x32_bf16 v[126:129], v[146:149], v[186:189], v[126:129]
	v_mfma_f32_16x16x32_bf16 v[122:125], v[154:157], v[186:189], v[122:125]
	v_mfma_f32_16x16x32_bf16 v[118:121], v[146:149], v[194:197], v[118:121]
	v_mfma_f32_16x16x32_bf16 v[110:113], v[154:157], v[194:197], v[110:113]
	v_mfma_f32_16x16x32_bf16 v[102:105], v[146:149], v[212:215], v[102:105]
	v_mfma_f32_16x16x32_bf16 v[94:97], v[154:157], v[212:215], v[94:97]
	v_mfma_f32_16x16x32_bf16 v[86:89], v[146:149], v[220:223], v[86:89]
	v_mfma_f32_16x16x32_bf16 v[78:81], v[154:157], v[220:223], v[78:81]
	v_mfma_f32_16x16x32_bf16 v[126:129], v[150:153], v[190:193], v[126:129]
	v_mfma_f32_16x16x32_bf16 v[122:125], v[158:161], v[190:193], v[122:125]
	v_mfma_f32_16x16x32_bf16 v[118:121], v[150:153], v[198:201], v[118:121]
	v_mfma_f32_16x16x32_bf16 v[110:113], v[158:161], v[198:201], v[110:113]
	v_mfma_f32_16x16x32_bf16 v[102:105], v[150:153], v[216:219], v[102:105]
	v_mfma_f32_16x16x32_bf16 v[94:97], v[158:161], v[216:219], v[94:97]
	v_mfma_f32_16x16x32_bf16 v[86:89], v[150:153], v[224:227], v[86:89]
	v_mfma_f32_16x16x32_bf16 v[78:81], v[158:161], v[224:227], v[78:81]
	v_mfma_f32_16x16x32_bf16 v[114:117], v[162:165], v[186:189], v[114:117]
	v_mfma_f32_16x16x32_bf16 v[106:109], v[178:181], v[186:189], v[106:109]
	v_mfma_f32_16x16x32_bf16 v[98:101], v[162:165], v[194:197], v[98:101]
	v_mfma_f32_16x16x32_bf16 v[90:93], v[178:181], v[194:197], v[90:93]
	v_mfma_f32_16x16x32_bf16 v[82:85], v[162:165], v[212:215], v[82:85]
	v_mfma_f32_16x16x32_bf16 v[74:77], v[178:181], v[212:215], v[74:77]
	v_mfma_f32_16x16x32_bf16 v[70:73], v[162:165], v[220:223], v[70:73]
	v_mfma_f32_16x16x32_bf16 v[66:69], v[178:181], v[220:223], v[66:69]
	v_mfma_f32_16x16x32_bf16 v[114:117], v[166:169], v[190:193], v[114:117]
	v_mfma_f32_16x16x32_bf16 v[106:109], v[182:185], v[190:193], v[106:109]
	v_mfma_f32_16x16x32_bf16 v[98:101], v[166:169], v[198:201], v[98:101]
	v_mfma_f32_16x16x32_bf16 v[90:93], v[182:185], v[198:201], v[90:93]
	v_mfma_f32_16x16x32_bf16 v[82:85], v[166:169], v[216:219], v[82:85]
	v_mfma_f32_16x16x32_bf16 v[74:77], v[182:185], v[216:219], v[74:77]
	v_mfma_f32_16x16x32_bf16 v[70:73], v[166:169], v[224:227], v[70:73]
	v_mfma_f32_16x16x32_bf16 v[66:69], v[182:185], v[224:227], v[66:69]
	s_barrier
; #define PG8_STAGE(bufoff, gbase, voff) do { _Pragma("unroll") for (int _i = 0; _i < 2; ++_i) \
;         __builtin_amdgcn_global_load_lds((const unsigned*)((const char*)(gbase) + (voff)[_i]), (LAS unsigned*)(lds + (bufoff) + ldsw + _i * 8192), 16, 0, 0); } while (0)
; #define PG8_LDA(dst, b, h) do { _Pragma("unroll") for (int m = 0; m < 4; ++m) _Pragma("unroll") for (int k = 0; k < 2; ++k) dst[m][k] = *(const LAS bf16x8*)(lds + PG8_SA(b, h) + aoff + m * 2048 + k * 1024); } while (0)
; #define PG8_MMA(ai, bj, At, Bt) do { __builtin_amdgcn_s_setprio(1); _Pragma("unroll") for (int m = 0; m < 4; ++m) _Pragma("unroll") for (int n = 0; n < 2; ++n) _Pragma("unroll") for (int k = 0; k < 2; ++k) \
;         acc[ai][bj][m][n] = __builtin_amdgcn_mfma_f32_16x16x32_bf16(Bt[n][k], At[m][k], acc[ai][bj][m][n], 0, 0, 0); __builtin_amdgcn_s_setprio(0); } while (0)
; #define PG8_WAIT_V(n) asm volatile("s_waitcnt vmcnt(" #n ")" ::: "memory")
; #define PG8_WAIT_L(n) asm volatile("s_waitcnt lgkmcnt(" #n ")" ::: "memory")
; #define PG8_BAR __builtin_amdgcn_s_barrier()
; #define PG8_SCHED __builtin_amdgcn_sched_barrier(0)
; template <class Epi>
; __device__ __forceinline__ void gemm_phase(LAS unsigned char* lds, const Gemm g, const StaticOrder& S, const Epi& E, const int tid) {
;     ...
;             PG8_LDA(At, 1, 1); PG8_STAGE(PG8_SB(1, 0), b3, voffB); PG8_STAGE(PG8_SB(1, 1), b3 + bhs, voffB); PG8_STAGE(PG8_SA(1, 0), a3, voffA);
;             PG8_WAIT_V(8); PG8_WAIT_L(0); PG8_BAR; PG8_MMA(1, 0, At, B0); PG8_MMA(1, 1, At, B1); PG8_BAR; PG8_SCHED;
;     ...
;         if (ALIGN_EPI) { if (wr == 0) PG8_BAR; }
	s_add_i32 s34, s51, s40
	v_lshl_add_u64 v[172:173], v[172:173], 0, s[70:71]
	s_mov_b32 m0, s34
	ds_read_b128 v[186:189], v144 offset:49152
	global_load_lds_dwordx4 v[172:173], off
	ds_read_b128 v[190:193], v144 offset:50176
	ds_read_b128 v[194:197], v144 offset:51200
	s_add_i32 m0, s34, 0x2000
	s_add_u32 s30, s30, 0x8080
	v_lshl_add_u64 v[172:173], v[174:175], 0, s[70:71]
	s_addc_u32 s31, s31, 0
	s_add_i32 s34, s52, s40
	global_load_lds_dwordx4 v[172:173], off
	ds_read_b128 v[198:201], v144 offset:52224
	ds_read_b128 v[212:215], v144 offset:53248
	v_lshl_add_u64 v[172:173], s[30:31], 0, v[0:1]
	s_mov_b32 m0, s34
	s_nop 0
	global_load_lds_dwordx4 v[172:173], off
	ds_read_b128 v[216:219], v144 offset:54272
	ds_read_b128 v[220:223], v144 offset:55296
	v_lshl_add_u64 v[172:173], s[30:31], 0, v[134:135]
	s_add_i32 m0, s34, 0x2000
	s_nop 0
	global_load_lds_dwordx4 v[172:173], off
	ds_read_b128 v[224:227], v144 offset:56320
	v_lshl_add_u64 v[172:173], v[176:177], 0, s[70:71]
	s_mov_b32 m0, s43
	s_nop 0
	global_load_lds_dwordx4 v[172:173], off
	v_lshl_add_u64 v[172:173], v[228:229], 0, s[70:71]
	s_mov_b32 m0, s44
	s_nop 0
	global_load_lds_dwordx4 v[172:173], off
	s_waitcnt vmcnt(8)
	s_waitcnt lgkmcnt(0)
	s_barrier
	s_waitcnt lgkmcnt(0)
	v_mfma_f32_16x16x32_bf16 v[62:65], v[146:149], v[186:189], v[62:65]
	v_mfma_f32_16x16x32_bf16 v[58:61], v[154:157], v[186:189], v[58:61]
	v_mfma_f32_16x16x32_bf16 v[54:57], v[146:149], v[194:197], v[54:57]
	v_mfma_f32_16x16x32_bf16 v[46:49], v[154:157], v[194:197], v[46:49]
	v_mfma_f32_16x16x32_bf16 v[38:41], v[146:149], v[212:215], v[38:41]
	v_mfma_f32_16x16x32_bf16 v[30:33], v[154:157], v[212:215], v[30:33]
	v_mfma_f32_16x16x32_bf16 v[22:25], v[146:149], v[220:223], v[22:25]
	v_mfma_f32_16x16x32_bf16 v[14:17], v[154:157], v[220:223], v[14:17]
	v_mfma_f32_16x16x32_bf16 v[62:65], v[150:153], v[190:193], v[62:65]
	v_mfma_f32_16x16x32_bf16 v[58:61], v[158:161], v[190:193], v[58:61]
	v_mfma_f32_16x16x32_bf16 v[54:57], v[150:153], v[198:201], v[54:57]
	v_mfma_f32_16x16x32_bf16 v[46:49], v[158:161], v[198:201], v[46:49]
	v_mfma_f32_16x16x32_bf16 v[38:41], v[150:153], v[216:219], v[38:41]
	v_mfma_f32_16x16x32_bf16 v[30:33], v[158:161], v[216:219], v[30:33]
	v_mfma_f32_16x16x32_bf16 v[22:25], v[150:153], v[224:227], v[22:25]
	v_mfma_f32_16x16x32_bf16 v[14:17], v[158:161], v[224:227], v[14:17]
	v_mfma_f32_16x16x32_bf16 v[50:53], v[162:165], v[186:189], v[50:53]
	v_mfma_f32_16x16x32_bf16 v[42:45], v[178:181], v[186:189], v[42:45]
	v_mfma_f32_16x16x32_bf16 v[34:37], v[162:165], v[194:197], v[34:37]
	v_mfma_f32_16x16x32_bf16 v[26:29], v[178:181], v[194:197], v[26:29]
	v_mfma_f32_16x16x32_bf16 v[18:21], v[162:165], v[212:215], v[18:21]
	v_mfma_f32_16x16x32_bf16 v[10:13], v[178:181], v[212:215], v[10:13]
	v_mfma_f32_16x16x32_bf16 v[6:9], v[162:165], v[220:223], v[6:9]
	v_mfma_f32_16x16x32_bf16 v[2:5], v[178:181], v[220:223], v[2:5]
	v_mfma_f32_16x16x32_bf16 v[50:53], v[166:169], v[190:193], v[50:53]
	v_mfma_f32_16x16x32_bf16 v[42:45], v[182:185], v[190:193], v[42:45]
	v_mfma_f32_16x16x32_bf16 v[34:37], v[166:169], v[198:201], v[34:37]
	v_mfma_f32_16x16x32_bf16 v[26:29], v[182:185], v[198:201], v[26:29]
	v_mfma_f32_16x16x32_bf16 v[18:21], v[166:169], v[216:219], v[18:21]
	v_mfma_f32_16x16x32_bf16 v[10:13], v[182:185], v[216:219], v[10:13]
	v_mfma_f32_16x16x32_bf16 v[6:9], v[166:169], v[224:227], v[6:9]
	v_mfma_f32_16x16x32_bf16 v[2:5], v[182:185], v[224:227], v[2:5]
	s_barrier
	s_add_i32 s50, s50, 2
	s_add_u32 s48, s48, 0x100
	s_addc_u32 s49, s49, 0
	s_add_u32 s28, s28, 0x100
	s_addc_u32 s29, s29, 0
	s_cmp_gt_u32 s50, 29
	s_cbranch_scc0 .LBB0_861
	s_and_b64 vcc, exec, s[12:13]
	s_cbranch_vccz .LBB0_864
	s_barrier
